# removed m0 save/restore, s_nop3->0 in loop DMA blocks, mid-block setprio toggles and redundant lgkmcnt in GEMM loops
# baseline (speedup 1.0000x reference)
; #define PG8_LDA(dst, b, h) do { _Pragma("unroll") for (int m = 0; m < 4; ++m) _Pragma("unroll") for (int k = 0; k < 2; ++k) dst[m][k] = *(const PG8_LAS bf16x8*)(lds + PG8_SA(b, h) + aoff + m * 2048 + k * 1024); } while (0)
; #define PG8_LDB(dst, b, h) do { _Pragma("unroll") for (int n = 0; n < 2; ++n) _Pragma("unroll") for (int k = 0; k < 2; ++k) dst[n][k] = *(const PG8_LAS bf16x8*)(lds + PG8_SB(b, h) + boff + n * 2048 + k * 1024); } while (0)
; #define PG8_MMA(ai, bj, At, Bt) do { __builtin_amdgcn_s_setprio(1); _Pragma("unroll") for (int m = 0; m < 4; ++m) _Pragma("unroll") for (int n = 0; n < 2; ++n) _Pragma("unroll") for (int k = 0; k < 2; ++k) \
;         acc[ai][bj][m][n] = __builtin_amdgcn_mfma_f32_16x16x32_bf16(Bt[n][k], At[m][k], acc[ai][bj][m][n], 0, 0, 0); __builtin_amdgcn_s_setprio(0); } while (0)
; #define PG8_WAIT_V(n) asm volatile("s_waitcnt vmcnt(" #n ")" ::: "memory")
; #define PG8_WAIT_L(n) asm volatile("s_waitcnt lgkmcnt(" #n ")" ::: "memory")
; #define PG8_BAR __builtin_amdgcn_s_barrier()
; #define PG8_SCHED __builtin_amdgcn_sched_barrier(0)
; template <class Epi, class Sched, bool ALIGN_EPI = false, bool SP2 = false>
; __device__ __forceinline__ void gemm_phase(PG8_LAS unsigned char* lds, const Gemm g, const Sched& S, const Epi& E, const int tid) {
;     ...
;             const char* a1 = cA + (size_t)(t + 1) * kstepA;
;             const char* a2 = last ? nA : cA + (size_t)(t + 2) * kstepA; const char* b2 = last ? nB : cB + (size_t)(t + 2) * kstepB;
;             const char* a3 = a2 + kstepA; const char* b3 = b2 + kstepB;
;             if (last && has_next) S.a_ready(nxt);
;             if constexpr (SP2) {
;             PG8_LDB(B0, 0, 0); PG8_LDB(B1, 0, 1); PG8_SCHED; PG8_LDA(At, 0, 0); PG8_STAGE(PG8_SA(1, 1), a1 + hstepA, voffA);
;             PG8_WAIT_V(8); PG8_WAIT_L(0); PG8_BAR; PG8_MMA(0, 0, At, B0); PG8_MMA(0, 1, At, B1); PG8_BAR; PG8_SCHED;
;             PG8_LDA(At, 0, 1); PG8_STAGE(PG8_SB(0, 0), b2, voffB); PG8_STAGE(PG8_SB(0, 1), b2 + hstepB, voffB); PG8_STAGE(PG8_SA(0, 0), a2, voffA);
;             PG8_WAIT_V(8); PG8_WAIT_L(0); PG8_BAR; PG8_MMA(1, 0, At, B0); PG8_MMA(1, 1, At, B1); PG8_BAR; PG8_SCHED;
.LBB0_380:
	s_or_b64 exec, exec, s[34:35]
	v_add_u32_e32 v145, 0x10000, v154
	ds_read_b128 v[156:159], v145
	ds_read_b128 v[160:163], v145 offset:1024
	ds_read_b128 v[164:167], v145 offset:2048
	ds_read_b128 v[168:171], v145 offset:3072
	v_add_u32_e32 v145, 0x14000, v154
	s_add_u32 s34, s28, 0x100
	ds_read_b128 v[172:175], v145
	ds_read_b128 v[176:179], v145 offset:1024
	ds_read_b128 v[180:183], v145 offset:2048
	ds_read_b128 v[184:187], v145 offset:3072
	s_addc_u32 s35, s29, 0
	s_and_b64 s[30:31], s[30:31], exec
	s_cselect_b32 s42, s91, s34
	s_cselect_b32 s43, s17, s35
	s_cselect_b32 s31, s15, s97
	s_cselect_b32 s30, s95, s96
	s_add_u32 s38, s42, 0x80
	s_addc_u32 s39, s43, 0
	s_add_u32 s40, s30, 0x80
	s_addc_u32 s41, s31, 0
	ds_read_b128 v[188:191], v155
	ds_read_b128 v[192:195], v155 offset:1024
	ds_read_b128 v[196:199], v155 offset:2048
	ds_read_b128 v[200:203], v155 offset:3072
	ds_read_b128 v[204:207], v155 offset:4096
	ds_read_b128 v[208:211], v155 offset:5120
	ds_read_b128 v[212:215], v155 offset:6144
	ds_read_b128 v[216:219], v155 offset:7168
	s_add_u32 s28, s28, 0x80080
	s_addc_u32 s29, s29, 0
	s_mov_b32 m0, s69
	s_nop 0
	global_load_lds_dwordx4 v149, s[28:29]
	s_nop 0
	s_mov_b32 m0, s58
	s_nop 0
	global_load_lds_dwordx4 v151, s[28:29]
	s_waitcnt vmcnt(8)
	s_waitcnt lgkmcnt(0)
	s_barrier
	s_setprio 1
	v_mfma_f32_16x16x32_bf16 v[126:129], v[156:159], v[188:191], v[126:129]
	v_mfma_f32_16x16x32_bf16 v[122:125], v[164:167], v[188:191], v[122:125]
	v_mfma_f32_16x16x32_bf16 v[110:113], v[156:159], v[196:199], v[110:113]
	v_mfma_f32_16x16x32_bf16 v[106:109], v[164:167], v[196:199], v[106:109]
	v_mfma_f32_16x16x32_bf16 v[94:97], v[156:159], v[204:207], v[94:97]
	v_mfma_f32_16x16x32_bf16 v[90:93], v[164:167], v[204:207], v[90:93]
	v_mfma_f32_16x16x32_bf16 v[78:81], v[156:159], v[212:215], v[78:81]
	v_mfma_f32_16x16x32_bf16 v[74:77], v[164:167], v[212:215], v[74:77]
	v_mfma_f32_16x16x32_bf16 v[126:129], v[160:163], v[192:195], v[126:129]
	v_mfma_f32_16x16x32_bf16 v[122:125], v[168:171], v[192:195], v[122:125]
	v_mfma_f32_16x16x32_bf16 v[110:113], v[160:163], v[200:203], v[110:113]
	v_mfma_f32_16x16x32_bf16 v[106:109], v[168:171], v[200:203], v[106:109]
	v_mfma_f32_16x16x32_bf16 v[94:97], v[160:163], v[208:211], v[94:97]
	v_mfma_f32_16x16x32_bf16 v[90:93], v[168:171], v[208:211], v[90:93]
	v_mfma_f32_16x16x32_bf16 v[78:81], v[160:163], v[216:219], v[78:81]
	v_mfma_f32_16x16x32_bf16 v[74:77], v[168:171], v[216:219], v[74:77]
	v_mfma_f32_16x16x32_bf16 v[118:121], v[172:175], v[188:191], v[118:121]
	v_mfma_f32_16x16x32_bf16 v[114:117], v[180:183], v[188:191], v[114:117]
	v_mfma_f32_16x16x32_bf16 v[102:105], v[172:175], v[196:199], v[102:105]
	v_mfma_f32_16x16x32_bf16 v[98:101], v[180:183], v[196:199], v[98:101]
	v_mfma_f32_16x16x32_bf16 v[86:89], v[172:175], v[204:207], v[86:89]
	v_mfma_f32_16x16x32_bf16 v[82:85], v[180:183], v[204:207], v[82:85]
	v_mfma_f32_16x16x32_bf16 v[70:73], v[172:175], v[212:215], v[70:73]
	v_mfma_f32_16x16x32_bf16 v[66:69], v[180:183], v[212:215], v[66:69]
	v_mfma_f32_16x16x32_bf16 v[118:121], v[176:179], v[192:195], v[118:121]
	v_mfma_f32_16x16x32_bf16 v[114:117], v[184:187], v[192:195], v[114:117]
	v_mfma_f32_16x16x32_bf16 v[102:105], v[176:179], v[200:203], v[102:105]
	v_mfma_f32_16x16x32_bf16 v[98:101], v[184:187], v[200:203], v[98:101]
	v_mfma_f32_16x16x32_bf16 v[86:89], v[176:179], v[208:211], v[86:89]
	v_mfma_f32_16x16x32_bf16 v[82:85], v[184:187], v[208:211], v[82:85]
	v_mfma_f32_16x16x32_bf16 v[70:73], v[176:179], v[216:219], v[70:73]
	v_mfma_f32_16x16x32_bf16 v[66:69], v[184:187], v[216:219], v[66:69]
	s_setprio 0
	s_barrier
	ds_read_b128 v[188:191], v155 offset:16384
	ds_read_b128 v[192:195], v155 offset:17408
	ds_read_b128 v[196:199], v155 offset:18432
	ds_read_b128 v[200:203], v155 offset:19456
	ds_read_b128 v[204:207], v155 offset:20480
	ds_read_b128 v[208:211], v155 offset:21504
	ds_read_b128 v[212:215], v155 offset:22528
	ds_read_b128 v[216:219], v155 offset:23552
	s_mov_b32 m0, s23
	s_nop 0
	global_load_lds_dwordx4 v150, s[30:31]
	s_add_u32 s28, s30, 0x80000
	s_mov_b32 m0, s25
	s_nop 0
	global_load_lds_dwordx4 v152, s[30:31]
	s_addc_u32 s29, s31, 0
	s_mov_b32 m0, s48
	s_nop 0
	global_load_lds_dwordx4 v150, s[28:29]
	s_nop 0
	s_mov_b32 m0, s49
	s_nop 0
	global_load_lds_dwordx4 v152, s[28:29]
	s_nop 0
	s_mov_b32 m0, s10
	s_nop 0
	global_load_lds_dwordx4 v149, s[42:43]
	s_nop 0
	s_mov_b32 m0, s50
	s_nop 0
	global_load_lds_dwordx4 v151, s[42:43]
	s_waitcnt vmcnt(8)
	s_waitcnt lgkmcnt(0)
	s_barrier
	s_setprio 1
	v_mfma_f32_16x16x32_bf16 v[62:65], v[156:159], v[188:191], v[62:65]
	v_mfma_f32_16x16x32_bf16 v[58:61], v[164:167], v[188:191], v[58:61]
	v_mfma_f32_16x16x32_bf16 v[46:49], v[156:159], v[196:199], v[46:49]
	v_mfma_f32_16x16x32_bf16 v[42:45], v[164:167], v[196:199], v[42:45]
	v_mfma_f32_16x16x32_bf16 v[30:33], v[156:159], v[204:207], v[30:33]
	v_mfma_f32_16x16x32_bf16 v[26:29], v[164:167], v[204:207], v[26:29]
	v_mfma_f32_16x16x32_bf16 v[14:17], v[156:159], v[212:215], v[14:17]
	v_mfma_f32_16x16x32_bf16 v[10:13], v[164:167], v[212:215], v[10:13]
	v_mfma_f32_16x16x32_bf16 v[62:65], v[160:163], v[192:195], v[62:65]
	v_mfma_f32_16x16x32_bf16 v[58:61], v[168:171], v[192:195], v[58:61]
	v_mfma_f32_16x16x32_bf16 v[46:49], v[160:163], v[200:203], v[46:49]
	v_mfma_f32_16x16x32_bf16 v[42:45], v[168:171], v[200:203], v[42:45]
	v_mfma_f32_16x16x32_bf16 v[30:33], v[160:163], v[208:211], v[30:33]
	v_mfma_f32_16x16x32_bf16 v[26:29], v[168:171], v[208:211], v[26:29]
	v_mfma_f32_16x16x32_bf16 v[14:17], v[160:163], v[216:219], v[14:17]
	v_mfma_f32_16x16x32_bf16 v[10:13], v[168:171], v[216:219], v[10:13]
	v_mfma_f32_16x16x32_bf16 v[54:57], v[172:175], v[188:191], v[54:57]
	v_mfma_f32_16x16x32_bf16 v[50:53], v[180:183], v[188:191], v[50:53]
	v_mfma_f32_16x16x32_bf16 v[38:41], v[172:175], v[196:199], v[38:41]
	v_mfma_f32_16x16x32_bf16 v[34:37], v[180:183], v[196:199], v[34:37]
	v_mfma_f32_16x16x32_bf16 v[22:25], v[172:175], v[204:207], v[22:25]
	v_mfma_f32_16x16x32_bf16 v[18:21], v[180:183], v[204:207], v[18:21]
	v_mfma_f32_16x16x32_bf16 v[6:9], v[172:175], v[212:215], v[6:9]
	v_mfma_f32_16x16x32_bf16 v[2:5], v[180:183], v[212:215], v[2:5]
	v_mfma_f32_16x16x32_bf16 v[54:57], v[176:179], v[192:195], v[54:57]
	v_mfma_f32_16x16x32_bf16 v[50:53], v[184:187], v[192:195], v[50:53]
	v_mfma_f32_16x16x32_bf16 v[38:41], v[176:179], v[200:203], v[38:41]
	v_mfma_f32_16x16x32_bf16 v[34:37], v[184:187], v[200:203], v[34:37]
	v_mfma_f32_16x16x32_bf16 v[22:25], v[176:179], v[208:211], v[22:25]
	v_mfma_f32_16x16x32_bf16 v[18:21], v[184:187], v[208:211], v[18:21]
	v_mfma_f32_16x16x32_bf16 v[6:9], v[176:179], v[216:219], v[6:9]
	v_mfma_f32_16x16x32_bf16 v[2:5], v[184:187], v[216:219], v[2:5]
	s_setprio 0
	s_barrier
; #define PG8_LDA(dst, b, h) do { _Pragma("unroll") for (int m = 0; m < 4; ++m) _Pragma("unroll") for (int k = 0; k < 2; ++k) dst[m][k] = *(const PG8_LAS bf16x8*)(lds + PG8_SA(b, h) + aoff + m * 2048 + k * 1024); } while (0)
; #define PG8_LDB(dst, b, h) do { _Pragma("unroll") for (int n = 0; n < 2; ++n) _Pragma("unroll") for (int k = 0; k < 2; ++k) dst[n][k] = *(const PG8_LAS bf16x8*)(lds + PG8_SB(b, h) + boff + n * 2048 + k * 1024); } while (0)
; #define PG8_MMA(ai, bj, At, Bt) do { __builtin_amdgcn_s_setprio(1); _Pragma("unroll") for (int m = 0; m < 4; ++m) _Pragma("unroll") for (int n = 0; n < 2; ++n) _Pragma("unroll") for (int k = 0; k < 2; ++k) \
;         acc[ai][bj][m][n] = __builtin_amdgcn_mfma_f32_16x16x32_bf16(Bt[n][k], At[m][k], acc[ai][bj][m][n], 0, 0, 0); __builtin_amdgcn_s_setprio(0); } while (0)
; #define PG8_WAIT_V(n) asm volatile("s_waitcnt vmcnt(" #n ")" ::: "memory")
; #define PG8_WAIT_L(n) asm volatile("s_waitcnt lgkmcnt(" #n ")" ::: "memory")
; #define PG8_BAR __builtin_amdgcn_s_barrier()
; #define PG8_SCHED __builtin_amdgcn_sched_barrier(0)
; template <class Epi, class Sched, bool ALIGN_EPI = false, bool SP2 = false>
; __device__ __forceinline__ void gemm_phase(PG8_LAS unsigned char* lds, const Gemm g, const Sched& S, const Epi& E, const int tid) {
;     ...
;             PG8_LDB(B0, 1, 0); PG8_LDB(B1, 1, 1); PG8_SCHED; PG8_LDA(At, 1, 0); PG8_STAGE(PG8_SA(0, 1), a2 + hstepA, voffA);
;             PG8_WAIT_V(8); PG8_WAIT_L(0); PG8_BAR; PG8_MMA(0, 0, At, B0); PG8_MMA(0, 1, At, B1); PG8_BAR; PG8_SCHED;
;             PG8_LDA(At, 1, 1); PG8_STAGE(PG8_SB(1, 0), b3, voffB); PG8_STAGE(PG8_SB(1, 1), b3 + hstepB, voffB); PG8_STAGE(PG8_SA(1, 0), a3, voffA);
;             PG8_WAIT_V(8); PG8_WAIT_L(0); PG8_BAR; PG8_MMA(1, 0, At, B0); PG8_MMA(1, 1, At, B1); PG8_BAR; PG8_SCHED;
	v_add_u32_e32 v145, 0x18000, v154
	ds_read_b128 v[156:159], v145
	ds_read_b128 v[160:163], v145 offset:1024
	ds_read_b128 v[164:167], v145 offset:2048
	ds_read_b128 v[168:171], v145 offset:3072
	v_add_u32_e32 v145, 0x1c000, v154
	ds_read_b128 v[172:175], v145
	ds_read_b128 v[176:179], v145 offset:1024
	ds_read_b128 v[180:183], v145 offset:2048
	ds_read_b128 v[184:187], v145 offset:3072
	ds_read_b128 v[188:191], v155 offset:32768
	ds_read_b128 v[192:195], v155 offset:33792
	ds_read_b128 v[196:199], v155 offset:34816
	ds_read_b128 v[200:203], v155 offset:35840
	ds_read_b128 v[204:207], v155 offset:36864
	ds_read_b128 v[208:211], v155 offset:37888
	ds_read_b128 v[212:215], v155 offset:38912
	ds_read_b128 v[216:219], v155 offset:39936
	s_add_u32 s28, s42, 0x80000
	s_addc_u32 s29, s43, 0
	s_mov_b32 m0, s51
	s_nop 0
	global_load_lds_dwordx4 v149, s[28:29]
	s_nop 0
	s_mov_b32 m0, s54
	s_nop 0
	global_load_lds_dwordx4 v151, s[28:29]
	s_waitcnt vmcnt(8)
	s_waitcnt lgkmcnt(0)
	s_barrier
	s_setprio 1
	v_mfma_f32_16x16x32_bf16 v[126:129], v[156:159], v[188:191], v[126:129]
	v_mfma_f32_16x16x32_bf16 v[122:125], v[164:167], v[188:191], v[122:125]
	v_mfma_f32_16x16x32_bf16 v[110:113], v[156:159], v[196:199], v[110:113]
	v_mfma_f32_16x16x32_bf16 v[106:109], v[164:167], v[196:199], v[106:109]
	v_mfma_f32_16x16x32_bf16 v[94:97], v[156:159], v[204:207], v[94:97]
	v_mfma_f32_16x16x32_bf16 v[90:93], v[164:167], v[204:207], v[90:93]
	v_mfma_f32_16x16x32_bf16 v[78:81], v[156:159], v[212:215], v[78:81]
	v_mfma_f32_16x16x32_bf16 v[74:77], v[164:167], v[212:215], v[74:77]
	v_mfma_f32_16x16x32_bf16 v[126:129], v[160:163], v[192:195], v[126:129]
	v_mfma_f32_16x16x32_bf16 v[122:125], v[168:171], v[192:195], v[122:125]
	v_mfma_f32_16x16x32_bf16 v[110:113], v[160:163], v[200:203], v[110:113]
	v_mfma_f32_16x16x32_bf16 v[106:109], v[168:171], v[200:203], v[106:109]
	v_mfma_f32_16x16x32_bf16 v[94:97], v[160:163], v[208:211], v[94:97]
	v_mfma_f32_16x16x32_bf16 v[90:93], v[168:171], v[208:211], v[90:93]
	v_mfma_f32_16x16x32_bf16 v[78:81], v[160:163], v[216:219], v[78:81]
	v_mfma_f32_16x16x32_bf16 v[74:77], v[168:171], v[216:219], v[74:77]
	v_mfma_f32_16x16x32_bf16 v[118:121], v[172:175], v[188:191], v[118:121]
	v_mfma_f32_16x16x32_bf16 v[114:117], v[180:183], v[188:191], v[114:117]
	v_mfma_f32_16x16x32_bf16 v[102:105], v[172:175], v[196:199], v[102:105]
	v_mfma_f32_16x16x32_bf16 v[98:101], v[180:183], v[196:199], v[98:101]
	v_mfma_f32_16x16x32_bf16 v[86:89], v[172:175], v[204:207], v[86:89]
	v_mfma_f32_16x16x32_bf16 v[82:85], v[180:183], v[204:207], v[82:85]
	v_mfma_f32_16x16x32_bf16 v[70:73], v[172:175], v[212:215], v[70:73]
	v_mfma_f32_16x16x32_bf16 v[66:69], v[180:183], v[212:215], v[66:69]
	v_mfma_f32_16x16x32_bf16 v[118:121], v[176:179], v[192:195], v[118:121]
	v_mfma_f32_16x16x32_bf16 v[114:117], v[184:187], v[192:195], v[114:117]
	v_mfma_f32_16x16x32_bf16 v[102:105], v[176:179], v[200:203], v[102:105]
	v_mfma_f32_16x16x32_bf16 v[98:101], v[184:187], v[200:203], v[98:101]
	v_mfma_f32_16x16x32_bf16 v[86:89], v[176:179], v[208:211], v[86:89]
	v_mfma_f32_16x16x32_bf16 v[82:85], v[184:187], v[208:211], v[82:85]
	v_mfma_f32_16x16x32_bf16 v[70:73], v[176:179], v[216:219], v[70:73]
	v_mfma_f32_16x16x32_bf16 v[66:69], v[184:187], v[216:219], v[66:69]
	s_setprio 0
	s_barrier
	ds_read_b128 v[188:191], v155 offset:49152
	ds_read_b128 v[192:195], v155 offset:50176
	ds_read_b128 v[196:199], v155 offset:51200
	ds_read_b128 v[200:203], v155 offset:52224
	ds_read_b128 v[204:207], v155 offset:53248
	ds_read_b128 v[208:211], v155 offset:54272
	ds_read_b128 v[212:215], v155 offset:55296
	ds_read_b128 v[216:219], v155 offset:56320
	s_mov_b32 m0, s55
	s_nop 0
	global_load_lds_dwordx4 v150, s[40:41]
	s_add_u32 s28, s30, 0x80080
	s_mov_b32 m0, s56
	s_nop 0
	global_load_lds_dwordx4 v152, s[40:41]
	s_addc_u32 s29, s31, 0
	s_mov_b32 m0, s64
	s_nop 0
	global_load_lds_dwordx4 v150, s[28:29]
	s_nop 0
	s_mov_b32 m0, s65
	s_nop 0
	global_load_lds_dwordx4 v152, s[28:29]
	s_nop 0
	s_mov_b32 m0, s57
	s_nop 0
	global_load_lds_dwordx4 v149, s[38:39]
	s_nop 0
	s_mov_b32 m0, s61
	s_nop 0
	global_load_lds_dwordx4 v151, s[38:39]
	s_waitcnt vmcnt(8)
	s_waitcnt lgkmcnt(0)
	s_barrier
	s_setprio 1
	v_mfma_f32_16x16x32_bf16 v[62:65], v[156:159], v[188:191], v[62:65]
	v_mfma_f32_16x16x32_bf16 v[58:61], v[164:167], v[188:191], v[58:61]
	v_mfma_f32_16x16x32_bf16 v[46:49], v[156:159], v[196:199], v[46:49]
	v_mfma_f32_16x16x32_bf16 v[42:45], v[164:167], v[196:199], v[42:45]
	v_mfma_f32_16x16x32_bf16 v[30:33], v[156:159], v[204:207], v[30:33]
	v_mfma_f32_16x16x32_bf16 v[26:29], v[164:167], v[204:207], v[26:29]
	v_mfma_f32_16x16x32_bf16 v[14:17], v[156:159], v[212:215], v[14:17]
	v_mfma_f32_16x16x32_bf16 v[10:13], v[164:167], v[212:215], v[10:13]
	v_mfma_f32_16x16x32_bf16 v[62:65], v[160:163], v[192:195], v[62:65]
	v_mfma_f32_16x16x32_bf16 v[58:61], v[168:171], v[192:195], v[58:61]
	v_mfma_f32_16x16x32_bf16 v[46:49], v[160:163], v[200:203], v[46:49]
	v_mfma_f32_16x16x32_bf16 v[42:45], v[168:171], v[200:203], v[42:45]
	v_mfma_f32_16x16x32_bf16 v[30:33], v[160:163], v[208:211], v[30:33]
	v_mfma_f32_16x16x32_bf16 v[26:29], v[168:171], v[208:211], v[26:29]
	v_mfma_f32_16x16x32_bf16 v[14:17], v[160:163], v[216:219], v[14:17]
	v_mfma_f32_16x16x32_bf16 v[10:13], v[168:171], v[216:219], v[10:13]
	v_mfma_f32_16x16x32_bf16 v[54:57], v[172:175], v[188:191], v[54:57]
	v_mfma_f32_16x16x32_bf16 v[50:53], v[180:183], v[188:191], v[50:53]
	v_mfma_f32_16x16x32_bf16 v[38:41], v[172:175], v[196:199], v[38:41]
	v_mfma_f32_16x16x32_bf16 v[34:37], v[180:183], v[196:199], v[34:37]
	v_mfma_f32_16x16x32_bf16 v[22:25], v[172:175], v[204:207], v[22:25]
	v_mfma_f32_16x16x32_bf16 v[18:21], v[180:183], v[204:207], v[18:21]
	v_mfma_f32_16x16x32_bf16 v[6:9], v[172:175], v[212:215], v[6:9]
	v_mfma_f32_16x16x32_bf16 v[2:5], v[180:183], v[212:215], v[2:5]
	v_mfma_f32_16x16x32_bf16 v[54:57], v[176:179], v[192:195], v[54:57]
	v_mfma_f32_16x16x32_bf16 v[50:53], v[184:187], v[192:195], v[50:53]
	v_mfma_f32_16x16x32_bf16 v[38:41], v[176:179], v[200:203], v[38:41]
	v_mfma_f32_16x16x32_bf16 v[34:37], v[184:187], v[200:203], v[34:37]
	v_mfma_f32_16x16x32_bf16 v[22:25], v[176:179], v[208:211], v[22:25]
	v_mfma_f32_16x16x32_bf16 v[18:21], v[184:187], v[208:211], v[18:21]
	v_mfma_f32_16x16x32_bf16 v[6:9], v[176:179], v[216:219], v[6:9]
	v_mfma_f32_16x16x32_bf16 v[2:5], v[184:187], v[216:219], v[2:5]
	s_setprio 0
	s_barrier
	s_add_i32 s59, s59, 2
	s_add_u32 s96, s96, 0x100
	s_addc_u32 s97, s97, 0
	s_cmp_gt_u32 s59, 29
	s_mov_b64 s[28:29], s[34:35]
	s_cbranch_scc1 .LBB0_383

; #define PG8_LDA(dst, b, h) do { _Pragma("unroll") for (int m = 0; m < 4; ++m) _Pragma("unroll") for (int k = 0; k < 2; ++k) dst[m][k] = *(const PG8_LAS bf16x8*)(lds + PG8_SA(b, h) + aoff + m * 2048 + k * 1024); } while (0)
; #define PG8_LDB(dst, b, h) do { _Pragma("unroll") for (int n = 0; n < 2; ++n) _Pragma("unroll") for (int k = 0; k < 2; ++k) dst[n][k] = *(const PG8_LAS bf16x8*)(lds + PG8_SB(b, h) + boff + n * 2048 + k * 1024); } while (0)
; #define PG8_MMA(ai, bj, At, Bt) do { __builtin_amdgcn_s_setprio(1); _Pragma("unroll") for (int m = 0; m < 4; ++m) _Pragma("unroll") for (int n = 0; n < 2; ++n) _Pragma("unroll") for (int k = 0; k < 2; ++k) \
;         acc[ai][bj][m][n] = __builtin_amdgcn_mfma_f32_16x16x32_bf16(Bt[n][k], At[m][k], acc[ai][bj][m][n], 0, 0, 0); __builtin_amdgcn_s_setprio(0); } while (0)
; #define PG8_WAIT_V(n) asm volatile("s_waitcnt vmcnt(" #n ")" ::: "memory")
; #define PG8_WAIT_L(n) asm volatile("s_waitcnt lgkmcnt(" #n ")" ::: "memory")
; #define PG8_BAR __builtin_amdgcn_s_barrier()
; #define PG8_SCHED __builtin_amdgcn_sched_barrier(0)
; template <class Epi, class Sched, bool ALIGN_EPI = false, bool SP2 = false>
; __device__ __forceinline__ void gemm_phase(PG8_LAS unsigned char* lds, const Gemm g, const Sched& S, const Epi& E, const int tid) {
;     ...
;             const char* a1 = cA + (size_t)(t + 1) * kstepA;
;             const char* a2 = last ? nA : cA + (size_t)(t + 2) * kstepA; const char* b2 = last ? nB : cB + (size_t)(t + 2) * kstepB;
;             const char* a3 = a2 + kstepA; const char* b3 = b2 + kstepB;
;             if (last && has_next) S.a_ready(nxt);
;             if constexpr (SP2) {
;             PG8_LDB(B0, 0, 0); PG8_LDB(B1, 0, 1); PG8_SCHED; PG8_LDA(At, 0, 0); PG8_STAGE(PG8_SA(1, 1), a1 + hstepA, voffA);
;             PG8_WAIT_V(8); PG8_WAIT_L(0); PG8_BAR; PG8_MMA(0, 0, At, B0); PG8_MMA(0, 1, At, B1); PG8_BAR; PG8_SCHED;
;             PG8_LDA(At, 0, 1); PG8_STAGE(PG8_SB(0, 0), b2, voffB); PG8_STAGE(PG8_SB(0, 1), b2 + hstepB, voffB); PG8_STAGE(PG8_SA(0, 0), a2, voffA);
;             PG8_WAIT_V(8); PG8_WAIT_L(0); PG8_BAR; PG8_MMA(1, 0, At, B0); PG8_MMA(1, 1, At, B1); PG8_BAR; PG8_SCHED;
.LBB0_462:
	v_add_u32_e32 v142, 0x10000, v181
	v_add_u32_e32 v158, 0x14000, v181
	ds_read_b128 v[130:133], v142
	ds_read_b128 v[134:137], v142 offset:1024
	ds_read_b128 v[138:141], v142 offset:2048
	ds_read_b128 v[142:145], v142 offset:3072
	ds_read_b128 v[146:149], v158
	ds_read_b128 v[150:153], v158 offset:1024
	ds_read_b128 v[154:157], v158 offset:2048
	ds_read_b128 v[158:161], v158 offset:3072
	s_cmpk_eq_i32 s67, 0x54
	s_cselect_b32 s26, s6, s64
	s_cselect_b32 s27, s7, s65
	s_cselect_b32 s24, s18, s11
	s_cselect_b32 s25, s19, s59
	s_add_u32 s22, s26, 0x8000
	s_addc_u32 s23, s27, 0
	ds_read_b128 v[162:165], v182
	ds_read_b128 v[166:169], v182 offset:1024
	ds_read_b128 v[170:173], v182 offset:2048
	ds_read_b128 v[184:187], v182 offset:3072
	ds_read_b128 v[188:191], v182 offset:4096
	ds_read_b128 v[192:195], v182 offset:5120
	ds_read_b128 v[196:199], v182 offset:6144
	ds_read_b128 v[200:203], v182 offset:7168
	s_mov_b32 m0, s50
	s_nop 0
	global_load_lds_dwordx4 v0, s[20:21]
	s_nop 0
	s_mov_b32 m0, s54
	s_nop 0
	global_load_lds_dwordx4 v177, s[20:21]
	s_waitcnt vmcnt(8)
	s_waitcnt lgkmcnt(0)
	s_barrier
	s_setprio 1
	v_mfma_f32_16x16x32_bf16 v[126:129], v[130:133], v[162:165], v[126:129]
	v_mfma_f32_16x16x32_bf16 v[122:125], v[138:141], v[162:165], v[122:125]
	v_mfma_f32_16x16x32_bf16 v[110:113], v[130:133], v[170:173], v[110:113]
	v_mfma_f32_16x16x32_bf16 v[106:109], v[138:141], v[170:173], v[106:109]
	v_mfma_f32_16x16x32_bf16 v[94:97], v[130:133], v[188:191], v[94:97]
	v_mfma_f32_16x16x32_bf16 v[90:93], v[138:141], v[188:191], v[90:93]
	v_mfma_f32_16x16x32_bf16 v[78:81], v[130:133], v[196:199], v[78:81]
	v_mfma_f32_16x16x32_bf16 v[74:77], v[138:141], v[196:199], v[74:77]
	v_mfma_f32_16x16x32_bf16 v[126:129], v[134:137], v[166:169], v[126:129]
	v_mfma_f32_16x16x32_bf16 v[122:125], v[142:145], v[166:169], v[122:125]
	v_mfma_f32_16x16x32_bf16 v[110:113], v[134:137], v[184:187], v[110:113]
	v_mfma_f32_16x16x32_bf16 v[106:109], v[142:145], v[184:187], v[106:109]
	v_mfma_f32_16x16x32_bf16 v[94:97], v[134:137], v[192:195], v[94:97]
	v_mfma_f32_16x16x32_bf16 v[90:93], v[142:145], v[192:195], v[90:93]
	v_mfma_f32_16x16x32_bf16 v[78:81], v[134:137], v[200:203], v[78:81]
	v_mfma_f32_16x16x32_bf16 v[74:77], v[142:145], v[200:203], v[74:77]
	v_mfma_f32_16x16x32_bf16 v[118:121], v[146:149], v[162:165], v[118:121]
	v_mfma_f32_16x16x32_bf16 v[114:117], v[154:157], v[162:165], v[114:117]
	v_mfma_f32_16x16x32_bf16 v[102:105], v[146:149], v[170:173], v[102:105]
	v_mfma_f32_16x16x32_bf16 v[98:101], v[154:157], v[170:173], v[98:101]
	v_mfma_f32_16x16x32_bf16 v[86:89], v[146:149], v[188:191], v[86:89]
	v_mfma_f32_16x16x32_bf16 v[82:85], v[154:157], v[188:191], v[82:85]
	v_mfma_f32_16x16x32_bf16 v[70:73], v[146:149], v[196:199], v[70:73]
	v_mfma_f32_16x16x32_bf16 v[66:69], v[154:157], v[196:199], v[66:69]
	v_mfma_f32_16x16x32_bf16 v[118:121], v[150:153], v[166:169], v[118:121]
	v_mfma_f32_16x16x32_bf16 v[114:117], v[158:161], v[166:169], v[114:117]
	v_mfma_f32_16x16x32_bf16 v[102:105], v[150:153], v[184:187], v[102:105]
	v_mfma_f32_16x16x32_bf16 v[98:101], v[158:161], v[184:187], v[98:101]
	v_mfma_f32_16x16x32_bf16 v[86:89], v[150:153], v[192:195], v[86:89]
	v_mfma_f32_16x16x32_bf16 v[82:85], v[158:161], v[192:195], v[82:85]
	v_mfma_f32_16x16x32_bf16 v[70:73], v[150:153], v[200:203], v[70:73]
	v_mfma_f32_16x16x32_bf16 v[66:69], v[158:161], v[200:203], v[66:69]
	s_setprio 0
	s_barrier
	ds_read_b128 v[162:165], v182 offset:16384
	ds_read_b128 v[166:169], v182 offset:17408
	ds_read_b128 v[170:173], v182 offset:18432
	ds_read_b128 v[184:187], v182 offset:19456
	ds_read_b128 v[188:191], v182 offset:20480
	ds_read_b128 v[192:195], v182 offset:21504
	ds_read_b128 v[196:199], v182 offset:22528
	ds_read_b128 v[200:203], v182 offset:23552
	s_mov_b32 m0, s35
	s_nop 0
	global_load_lds_dwordx4 v176, s[24:25]
	s_add_u32 s90, s24, 0x4000
	s_mov_b32 m0, s37
	s_nop 0
	global_load_lds_dwordx4 v178, s[24:25]
	s_addc_u32 s91, s25, 0
	s_mov_b32 m0, s38
	s_nop 0
	global_load_lds_dwordx4 v176, s[90:91]
	s_nop 0
	s_mov_b32 m0, s39
	s_nop 0
	global_load_lds_dwordx4 v178, s[90:91]
	s_nop 0
	s_mov_b32 m0, s10
	s_nop 0
	global_load_lds_dwordx4 v0, s[26:27]
	s_nop 0
	s_mov_b32 m0, s40
	s_nop 0
	global_load_lds_dwordx4 v177, s[26:27]
	s_waitcnt vmcnt(8)
	s_waitcnt lgkmcnt(0)
	s_barrier
	s_setprio 1
	v_mfma_f32_16x16x32_bf16 v[62:65], v[130:133], v[162:165], v[62:65]
	v_mfma_f32_16x16x32_bf16 v[58:61], v[138:141], v[162:165], v[58:61]
	v_mfma_f32_16x16x32_bf16 v[46:49], v[130:133], v[170:173], v[46:49]
	v_mfma_f32_16x16x32_bf16 v[42:45], v[138:141], v[170:173], v[42:45]
	v_mfma_f32_16x16x32_bf16 v[30:33], v[130:133], v[188:191], v[30:33]
	v_mfma_f32_16x16x32_bf16 v[26:29], v[138:141], v[188:191], v[26:29]
	v_mfma_f32_16x16x32_bf16 v[14:17], v[130:133], v[196:199], v[14:17]
	v_mfma_f32_16x16x32_bf16 v[10:13], v[138:141], v[196:199], v[10:13]
	v_mfma_f32_16x16x32_bf16 v[62:65], v[134:137], v[166:169], v[62:65]
	v_mfma_f32_16x16x32_bf16 v[58:61], v[142:145], v[166:169], v[58:61]
	v_mfma_f32_16x16x32_bf16 v[46:49], v[134:137], v[184:187], v[46:49]
	v_mfma_f32_16x16x32_bf16 v[42:45], v[142:145], v[184:187], v[42:45]
	v_mfma_f32_16x16x32_bf16 v[30:33], v[134:137], v[192:195], v[30:33]
	v_mfma_f32_16x16x32_bf16 v[26:29], v[142:145], v[192:195], v[26:29]
	v_mfma_f32_16x16x32_bf16 v[14:17], v[134:137], v[200:203], v[14:17]
	v_mfma_f32_16x16x32_bf16 v[10:13], v[142:145], v[200:203], v[10:13]
	v_mfma_f32_16x16x32_bf16 v[54:57], v[146:149], v[162:165], v[54:57]
	v_mfma_f32_16x16x32_bf16 v[50:53], v[154:157], v[162:165], v[50:53]
	v_mfma_f32_16x16x32_bf16 v[38:41], v[146:149], v[170:173], v[38:41]
	v_mfma_f32_16x16x32_bf16 v[34:37], v[154:157], v[170:173], v[34:37]
	v_mfma_f32_16x16x32_bf16 v[22:25], v[146:149], v[188:191], v[22:25]
	v_mfma_f32_16x16x32_bf16 v[18:21], v[154:157], v[188:191], v[18:21]
	v_mfma_f32_16x16x32_bf16 v[6:9], v[146:149], v[196:199], v[6:9]
	v_mfma_f32_16x16x32_bf16 v[2:5], v[154:157], v[196:199], v[2:5]
	v_mfma_f32_16x16x32_bf16 v[54:57], v[150:153], v[166:169], v[54:57]
	v_mfma_f32_16x16x32_bf16 v[50:53], v[158:161], v[166:169], v[50:53]
	v_mfma_f32_16x16x32_bf16 v[38:41], v[150:153], v[184:187], v[38:41]
	v_mfma_f32_16x16x32_bf16 v[34:37], v[158:161], v[184:187], v[34:37]
	v_mfma_f32_16x16x32_bf16 v[22:25], v[150:153], v[192:195], v[22:25]
	v_mfma_f32_16x16x32_bf16 v[18:21], v[158:161], v[192:195], v[18:21]
	v_mfma_f32_16x16x32_bf16 v[6:9], v[150:153], v[200:203], v[6:9]
	v_mfma_f32_16x16x32_bf16 v[2:5], v[158:161], v[200:203], v[2:5]
	s_setprio 0
	s_barrier
; #define PG8_LDA(dst, b, h) do { _Pragma("unroll") for (int m = 0; m < 4; ++m) _Pragma("unroll") for (int k = 0; k < 2; ++k) dst[m][k] = *(const PG8_LAS bf16x8*)(lds + PG8_SA(b, h) + aoff + m * 2048 + k * 1024); } while (0)
; #define PG8_LDB(dst, b, h) do { _Pragma("unroll") for (int n = 0; n < 2; ++n) _Pragma("unroll") for (int k = 0; k < 2; ++k) dst[n][k] = *(const PG8_LAS bf16x8*)(lds + PG8_SB(b, h) + boff + n * 2048 + k * 1024); } while (0)
; #define PG8_MMA(ai, bj, At, Bt) do { __builtin_amdgcn_s_setprio(1); _Pragma("unroll") for (int m = 0; m < 4; ++m) _Pragma("unroll") for (int n = 0; n < 2; ++n) _Pragma("unroll") for (int k = 0; k < 2; ++k) \
;         acc[ai][bj][m][n] = __builtin_amdgcn_mfma_f32_16x16x32_bf16(Bt[n][k], At[m][k], acc[ai][bj][m][n], 0, 0, 0); __builtin_amdgcn_s_setprio(0); } while (0)
; #define PG8_WAIT_V(n) asm volatile("s_waitcnt vmcnt(" #n ")" ::: "memory")
; #define PG8_WAIT_L(n) asm volatile("s_waitcnt lgkmcnt(" #n ")" ::: "memory")
; #define PG8_BAR __builtin_amdgcn_s_barrier()
; #define PG8_SCHED __builtin_amdgcn_sched_barrier(0)
; template <class Epi, class Sched, bool ALIGN_EPI = false, bool SP2 = false>
; __device__ __forceinline__ void gemm_phase(PG8_LAS unsigned char* lds, const Gemm g, const Sched& S, const Epi& E, const int tid) {
;     ...
;             PG8_LDB(B0, 1, 0); PG8_LDB(B1, 1, 1); PG8_SCHED; PG8_LDA(At, 1, 0); PG8_STAGE(PG8_SA(0, 1), a2 + hstepA, voffA);
;             PG8_WAIT_V(8); PG8_WAIT_L(0); PG8_BAR; PG8_MMA(0, 0, At, B0); PG8_MMA(0, 1, At, B1); PG8_BAR; PG8_SCHED;
;             PG8_LDA(At, 1, 1); PG8_STAGE(PG8_SB(1, 0), b3, voffB); PG8_STAGE(PG8_SB(1, 1), b3 + hstepB, voffB); PG8_STAGE(PG8_SA(1, 0), a3, voffA);
;             PG8_WAIT_V(8); PG8_WAIT_L(0); PG8_BAR; PG8_MMA(1, 0, At, B0); PG8_MMA(1, 1, At, B1); PG8_BAR; PG8_SCHED;
	v_add_u32_e32 v142, 0x18000, v181
	v_add_u32_e32 v158, 0x1c000, v181
	ds_read_b128 v[130:133], v142
	ds_read_b128 v[134:137], v142 offset:1024
	ds_read_b128 v[138:141], v142 offset:2048
	ds_read_b128 v[142:145], v142 offset:3072
	ds_read_b128 v[146:149], v158
	ds_read_b128 v[150:153], v158 offset:1024
	ds_read_b128 v[154:157], v158 offset:2048
	ds_read_b128 v[158:161], v158 offset:3072
	ds_read_b128 v[162:165], v182 offset:32768
	ds_read_b128 v[166:169], v182 offset:33792
	ds_read_b128 v[170:173], v182 offset:34816
	ds_read_b128 v[184:187], v182 offset:35840
	ds_read_b128 v[188:191], v182 offset:36864
	ds_read_b128 v[192:195], v182 offset:37888
	ds_read_b128 v[196:199], v182 offset:38912
	ds_read_b128 v[200:203], v182 offset:39936
	s_add_u32 s26, s26, 0x4000
	s_addc_u32 s27, s27, 0
	s_mov_b32 m0, s41
	s_nop 0
	global_load_lds_dwordx4 v0, s[26:27]
	s_nop 0
	s_mov_b32 m0, s42
	s_nop 0
	global_load_lds_dwordx4 v177, s[26:27]
	s_waitcnt vmcnt(8)
	s_waitcnt lgkmcnt(0)
	s_barrier
	s_setprio 1
	v_mfma_f32_16x16x32_bf16 v[126:129], v[130:133], v[162:165], v[126:129]
	v_mfma_f32_16x16x32_bf16 v[122:125], v[138:141], v[162:165], v[122:125]
	v_mfma_f32_16x16x32_bf16 v[110:113], v[130:133], v[170:173], v[110:113]
	v_mfma_f32_16x16x32_bf16 v[106:109], v[138:141], v[170:173], v[106:109]
	v_mfma_f32_16x16x32_bf16 v[94:97], v[130:133], v[188:191], v[94:97]
	v_mfma_f32_16x16x32_bf16 v[90:93], v[138:141], v[188:191], v[90:93]
	v_mfma_f32_16x16x32_bf16 v[78:81], v[130:133], v[196:199], v[78:81]
	v_mfma_f32_16x16x32_bf16 v[74:77], v[138:141], v[196:199], v[74:77]
	v_mfma_f32_16x16x32_bf16 v[126:129], v[134:137], v[166:169], v[126:129]
	v_mfma_f32_16x16x32_bf16 v[122:125], v[142:145], v[166:169], v[122:125]
	v_mfma_f32_16x16x32_bf16 v[110:113], v[134:137], v[184:187], v[110:113]
	v_mfma_f32_16x16x32_bf16 v[106:109], v[142:145], v[184:187], v[106:109]
	v_mfma_f32_16x16x32_bf16 v[94:97], v[134:137], v[192:195], v[94:97]
	v_mfma_f32_16x16x32_bf16 v[90:93], v[142:145], v[192:195], v[90:93]
	v_mfma_f32_16x16x32_bf16 v[78:81], v[134:137], v[200:203], v[78:81]
	v_mfma_f32_16x16x32_bf16 v[74:77], v[142:145], v[200:203], v[74:77]
	v_mfma_f32_16x16x32_bf16 v[118:121], v[146:149], v[162:165], v[118:121]
	v_mfma_f32_16x16x32_bf16 v[114:117], v[154:157], v[162:165], v[114:117]
	v_mfma_f32_16x16x32_bf16 v[102:105], v[146:149], v[170:173], v[102:105]
	v_mfma_f32_16x16x32_bf16 v[98:101], v[154:157], v[170:173], v[98:101]
	v_mfma_f32_16x16x32_bf16 v[86:89], v[146:149], v[188:191], v[86:89]
	v_mfma_f32_16x16x32_bf16 v[82:85], v[154:157], v[188:191], v[82:85]
	v_mfma_f32_16x16x32_bf16 v[70:73], v[146:149], v[196:199], v[70:73]
	v_mfma_f32_16x16x32_bf16 v[66:69], v[154:157], v[196:199], v[66:69]
	v_mfma_f32_16x16x32_bf16 v[118:121], v[150:153], v[166:169], v[118:121]
	v_mfma_f32_16x16x32_bf16 v[114:117], v[158:161], v[166:169], v[114:117]
	v_mfma_f32_16x16x32_bf16 v[102:105], v[150:153], v[184:187], v[102:105]
	v_mfma_f32_16x16x32_bf16 v[98:101], v[158:161], v[184:187], v[98:101]
	v_mfma_f32_16x16x32_bf16 v[86:89], v[150:153], v[192:195], v[86:89]
	v_mfma_f32_16x16x32_bf16 v[82:85], v[158:161], v[192:195], v[82:85]
	v_mfma_f32_16x16x32_bf16 v[70:73], v[150:153], v[200:203], v[70:73]
	v_mfma_f32_16x16x32_bf16 v[66:69], v[158:161], v[200:203], v[66:69]
	s_setprio 0
	s_barrier
	ds_read_b128 v[162:165], v182 offset:49152
	ds_read_b128 v[166:169], v182 offset:50176
	ds_read_b128 v[170:173], v182 offset:51200
	ds_read_b128 v[184:187], v182 offset:52224
	ds_read_b128 v[188:191], v182 offset:53248
	ds_read_b128 v[192:195], v182 offset:54272
	ds_read_b128 v[196:199], v182 offset:55296
	ds_read_b128 v[200:203], v182 offset:56320
	s_add_u32 s26, s24, 0x8000
	s_addc_u32 s27, s25, 0
	s_mov_b32 m0, s44
	s_nop 0
	global_load_lds_dwordx4 v176, s[26:27]
	s_add_u32 s24, s24, 0xc000
	s_mov_b32 m0, s45
	s_nop 0
	global_load_lds_dwordx4 v178, s[26:27]
	s_addc_u32 s25, s25, 0
	s_mov_b32 m0, s48
	s_nop 0
	global_load_lds_dwordx4 v176, s[24:25]
	s_nop 0
	s_mov_b32 m0, s49
	s_nop 0
	global_load_lds_dwordx4 v178, s[24:25]
	s_mov_b32 m0, s46
	s_nop 0
	global_load_lds_dwordx4 v0, s[22:23]
	s_nop 0
	s_mov_b32 m0, s47
	s_nop 0
	global_load_lds_dwordx4 v177, s[22:23]
	s_waitcnt vmcnt(8)
	s_waitcnt lgkmcnt(0)
	s_barrier
	s_setprio 1
	v_mfma_f32_16x16x32_bf16 v[62:65], v[130:133], v[162:165], v[62:65]
	v_mfma_f32_16x16x32_bf16 v[58:61], v[138:141], v[162:165], v[58:61]
	v_mfma_f32_16x16x32_bf16 v[46:49], v[130:133], v[170:173], v[46:49]
	v_mfma_f32_16x16x32_bf16 v[42:45], v[138:141], v[170:173], v[42:45]
	v_mfma_f32_16x16x32_bf16 v[30:33], v[130:133], v[188:191], v[30:33]
	v_mfma_f32_16x16x32_bf16 v[26:29], v[138:141], v[188:191], v[26:29]
	v_mfma_f32_16x16x32_bf16 v[14:17], v[130:133], v[196:199], v[14:17]
	v_mfma_f32_16x16x32_bf16 v[10:13], v[138:141], v[196:199], v[10:13]
	v_mfma_f32_16x16x32_bf16 v[62:65], v[134:137], v[166:169], v[62:65]
	v_mfma_f32_16x16x32_bf16 v[58:61], v[142:145], v[166:169], v[58:61]
	v_mfma_f32_16x16x32_bf16 v[46:49], v[134:137], v[184:187], v[46:49]
	v_mfma_f32_16x16x32_bf16 v[42:45], v[142:145], v[184:187], v[42:45]
	v_mfma_f32_16x16x32_bf16 v[30:33], v[134:137], v[192:195], v[30:33]
	v_mfma_f32_16x16x32_bf16 v[26:29], v[142:145], v[192:195], v[26:29]
	v_mfma_f32_16x16x32_bf16 v[14:17], v[134:137], v[200:203], v[14:17]
	v_mfma_f32_16x16x32_bf16 v[10:13], v[142:145], v[200:203], v[10:13]
	v_mfma_f32_16x16x32_bf16 v[54:57], v[146:149], v[162:165], v[54:57]
	v_mfma_f32_16x16x32_bf16 v[50:53], v[154:157], v[162:165], v[50:53]
	v_mfma_f32_16x16x32_bf16 v[38:41], v[146:149], v[170:173], v[38:41]
	v_mfma_f32_16x16x32_bf16 v[34:37], v[154:157], v[170:173], v[34:37]
	v_mfma_f32_16x16x32_bf16 v[22:25], v[146:149], v[188:191], v[22:25]
	v_mfma_f32_16x16x32_bf16 v[18:21], v[154:157], v[188:191], v[18:21]
	v_mfma_f32_16x16x32_bf16 v[6:9], v[146:149], v[196:199], v[6:9]
	v_mfma_f32_16x16x32_bf16 v[2:5], v[154:157], v[196:199], v[2:5]
	v_mfma_f32_16x16x32_bf16 v[54:57], v[150:153], v[166:169], v[54:57]
	v_mfma_f32_16x16x32_bf16 v[50:53], v[158:161], v[166:169], v[50:53]
	v_mfma_f32_16x16x32_bf16 v[38:41], v[150:153], v[184:187], v[38:41]
	v_mfma_f32_16x16x32_bf16 v[34:37], v[158:161], v[184:187], v[34:37]
	v_mfma_f32_16x16x32_bf16 v[22:25], v[150:153], v[192:195], v[22:25]
	v_mfma_f32_16x16x32_bf16 v[18:21], v[158:161], v[192:195], v[18:21]
	v_mfma_f32_16x16x32_bf16 v[6:9], v[150:153], v[200:203], v[6:9]
	v_mfma_f32_16x16x32_bf16 v[2:5], v[158:161], v[200:203], v[2:5]
	s_setprio 0
	s_barrier
	s_add_i32 s67, s67, 2
	s_add_u32 s11, s11, 0x10000
	s_addc_u32 s59, s59, 0
	s_add_u32 s64, s64, 0x10000
	s_addc_u32 s65, s65, 0
	s_add_u32 s20, s20, 0x10000
	s_addc_u32 s21, s21, 0
	s_cmpk_gt_u32 s67, 0x55
	s_cbranch_scc0 .LBB0_462
	s_and_b64 vcc, exec, s[16:17]
	s_cbranch_vccz .LBB0_465
	s_barrier

; #define PG8_LDA(dst, b, h) do { _Pragma("unroll") for (int m = 0; m < 4; ++m) _Pragma("unroll") for (int k = 0; k < 2; ++k) dst[m][k] = *(const PG8_LAS bf16x8*)(lds + PG8_SA(b, h) + aoff + m * 2048 + k * 1024); } while (0)
; #define PG8_LDB(dst, b, h) do { _Pragma("unroll") for (int n = 0; n < 2; ++n) _Pragma("unroll") for (int k = 0; k < 2; ++k) dst[n][k] = *(const PG8_LAS bf16x8*)(lds + PG8_SB(b, h) + boff + n * 2048 + k * 1024); } while (0)
; #define PG8_MMA(ai, bj, At, Bt) do { __builtin_amdgcn_s_setprio(1); _Pragma("unroll") for (int m = 0; m < 4; ++m) _Pragma("unroll") for (int n = 0; n < 2; ++n) _Pragma("unroll") for (int k = 0; k < 2; ++k) \
;         acc[ai][bj][m][n] = __builtin_amdgcn_mfma_f32_16x16x32_bf16(Bt[n][k], At[m][k], acc[ai][bj][m][n], 0, 0, 0); __builtin_amdgcn_s_setprio(0); } while (0)
; #define PG8_WAIT_V(n) asm volatile("s_waitcnt vmcnt(" #n ")" ::: "memory")
; #define PG8_WAIT_L(n) asm volatile("s_waitcnt lgkmcnt(" #n ")" ::: "memory")
; #define PG8_BAR __builtin_amdgcn_s_barrier()
; #define PG8_SCHED __builtin_amdgcn_sched_barrier(0)
; template <class Epi, class Sched, bool ALIGN_EPI = false, bool SP2 = false>
; __device__ __forceinline__ void gemm_phase(PG8_LAS unsigned char* lds, const Gemm g, const Sched& S, const Epi& E, const int tid) {
;     ...
;             const char* a1 = cA + (size_t)(t + 1) * kstepA;
;             const char* a2 = last ? nA : cA + (size_t)(t + 2) * kstepA; const char* b2 = last ? nB : cB + (size_t)(t + 2) * kstepB;
;             const char* a3 = a2 + kstepA; const char* b3 = b2 + kstepB;
;             if (last && has_next) S.a_ready(nxt);
;             if constexpr (SP2) {
;             PG8_LDB(B0, 0, 0); PG8_LDB(B1, 0, 1); PG8_SCHED; PG8_LDA(At, 0, 0); PG8_STAGE(PG8_SA(1, 1), a1 + hstepA, voffA);
;             PG8_WAIT_V(8); PG8_WAIT_L(0); PG8_BAR; PG8_MMA(0, 0, At, B0); PG8_MMA(0, 1, At, B1); PG8_BAR; PG8_SCHED;
;             PG8_LDA(At, 0, 1); PG8_STAGE(PG8_SB(0, 0), b2, voffB); PG8_STAGE(PG8_SB(0, 1), b2 + hstepB, voffB); PG8_STAGE(PG8_SA(0, 0), a2, voffA);
;             PG8_WAIT_V(8); PG8_WAIT_L(0); PG8_BAR; PG8_MMA(1, 0, At, B0); PG8_MMA(1, 1, At, B1); PG8_BAR; PG8_SCHED;
.LBB0_546:
	s_or_b64 exec, exec, s[34:35]
	v_add_u32_e32 v133, 0x10000, v144
	ds_read_b128 v[146:149], v133
	ds_read_b128 v[150:153], v133 offset:1024
	ds_read_b128 v[154:157], v133 offset:2048
	ds_read_b128 v[158:161], v133 offset:3072
	v_add_u32_e32 v133, 0x14000, v144
	s_add_u32 s34, s28, 0x100
	ds_read_b128 v[162:165], v133
	ds_read_b128 v[166:169], v133 offset:1024
	ds_read_b128 v[170:173], v133 offset:2048
	ds_read_b128 v[174:177], v133 offset:3072
	s_addc_u32 s35, s29, 0
	s_and_b64 s[30:31], s[30:31], exec
	s_cselect_b32 s42, s95, s34
	s_cselect_b32 s43, s21, s35
	s_cselect_b32 s31, s19, s59
	s_cselect_b32 s30, s96, s97
	s_add_u32 s38, s42, 0x80
	s_addc_u32 s39, s43, 0
	s_add_u32 s40, s30, 0x80
	s_addc_u32 s41, s31, 0
	ds_read_b128 v[178:181], v145
	ds_read_b128 v[182:185], v145 offset:1024
	ds_read_b128 v[186:189], v145 offset:2048
	ds_read_b128 v[190:193], v145 offset:3072
	ds_read_b128 v[194:197], v145 offset:4096
	ds_read_b128 v[198:201], v145 offset:5120
	ds_read_b128 v[202:205], v145 offset:6144
	ds_read_b128 v[206:209], v145 offset:7168
	s_add_u32 s28, s28, 0x80080
	s_addc_u32 s29, s29, 0
	s_mov_b32 m0, s70
	s_nop 0
	global_load_lds_dwordx4 v136, s[28:29]
	s_nop 0
	s_mov_b32 m0, s78
	s_nop 0
	global_load_lds_dwordx4 v138, s[28:29]
	s_waitcnt vmcnt(8)
	s_waitcnt lgkmcnt(0)
	s_barrier
	s_setprio 1
	v_mfma_f32_16x16x32_bf16 v[126:129], v[146:149], v[178:181], v[126:129]
	v_mfma_f32_16x16x32_bf16 v[122:125], v[154:157], v[178:181], v[122:125]
	v_mfma_f32_16x16x32_bf16 v[118:121], v[146:149], v[186:189], v[118:121]
	v_mfma_f32_16x16x32_bf16 v[110:113], v[154:157], v[186:189], v[110:113]
	v_mfma_f32_16x16x32_bf16 v[102:105], v[146:149], v[194:197], v[102:105]
	v_mfma_f32_16x16x32_bf16 v[94:97], v[154:157], v[194:197], v[94:97]
	v_mfma_f32_16x16x32_bf16 v[86:89], v[146:149], v[202:205], v[86:89]
	v_mfma_f32_16x16x32_bf16 v[78:81], v[154:157], v[202:205], v[78:81]
	v_mfma_f32_16x16x32_bf16 v[126:129], v[150:153], v[182:185], v[126:129]
	v_mfma_f32_16x16x32_bf16 v[122:125], v[158:161], v[182:185], v[122:125]
	v_mfma_f32_16x16x32_bf16 v[118:121], v[150:153], v[190:193], v[118:121]
	v_mfma_f32_16x16x32_bf16 v[110:113], v[158:161], v[190:193], v[110:113]
	v_mfma_f32_16x16x32_bf16 v[102:105], v[150:153], v[198:201], v[102:105]
	v_mfma_f32_16x16x32_bf16 v[94:97], v[158:161], v[198:201], v[94:97]
	v_mfma_f32_16x16x32_bf16 v[86:89], v[150:153], v[206:209], v[86:89]
	v_mfma_f32_16x16x32_bf16 v[78:81], v[158:161], v[206:209], v[78:81]
	v_mfma_f32_16x16x32_bf16 v[114:117], v[162:165], v[178:181], v[114:117]
	v_mfma_f32_16x16x32_bf16 v[106:109], v[170:173], v[178:181], v[106:109]
	v_mfma_f32_16x16x32_bf16 v[98:101], v[162:165], v[186:189], v[98:101]
	v_mfma_f32_16x16x32_bf16 v[90:93], v[170:173], v[186:189], v[90:93]
	v_mfma_f32_16x16x32_bf16 v[82:85], v[162:165], v[194:197], v[82:85]
	v_mfma_f32_16x16x32_bf16 v[74:77], v[170:173], v[194:197], v[74:77]
	v_mfma_f32_16x16x32_bf16 v[70:73], v[162:165], v[202:205], v[70:73]
	v_mfma_f32_16x16x32_bf16 v[66:69], v[170:173], v[202:205], v[66:69]
	v_mfma_f32_16x16x32_bf16 v[114:117], v[166:169], v[182:185], v[114:117]
	v_mfma_f32_16x16x32_bf16 v[106:109], v[174:177], v[182:185], v[106:109]
	v_mfma_f32_16x16x32_bf16 v[98:101], v[166:169], v[190:193], v[98:101]
	v_mfma_f32_16x16x32_bf16 v[90:93], v[174:177], v[190:193], v[90:93]
	v_mfma_f32_16x16x32_bf16 v[82:85], v[166:169], v[198:201], v[82:85]
	v_mfma_f32_16x16x32_bf16 v[74:77], v[174:177], v[198:201], v[74:77]
	v_mfma_f32_16x16x32_bf16 v[70:73], v[166:169], v[206:209], v[70:73]
	v_mfma_f32_16x16x32_bf16 v[66:69], v[174:177], v[206:209], v[66:69]
	s_setprio 0
	s_barrier
	ds_read_b128 v[178:181], v145 offset:16384
	ds_read_b128 v[182:185], v145 offset:17408
	ds_read_b128 v[186:189], v145 offset:18432
	ds_read_b128 v[190:193], v145 offset:19456
	ds_read_b128 v[194:197], v145 offset:20480
	ds_read_b128 v[198:201], v145 offset:21504
	ds_read_b128 v[202:205], v145 offset:22528
	ds_read_b128 v[206:209], v145 offset:23552
	s_mov_b32 m0, s9
	s_nop 0
	global_load_lds_dwordx4 v137, s[30:31]
	s_add_u32 s28, s30, 0x80000
	s_mov_b32 m0, s49
	s_nop 0
	global_load_lds_dwordx4 v139, s[30:31]
	s_addc_u32 s29, s31, 0
	s_mov_b32 m0, s50
	s_nop 0
	global_load_lds_dwordx4 v137, s[28:29]
	s_nop 0
	s_mov_b32 m0, s51
	s_nop 0
	global_load_lds_dwordx4 v139, s[28:29]
	s_nop 0
	s_mov_b32 m0, s10
	s_nop 0
	global_load_lds_dwordx4 v136, s[42:43]
	s_nop 0
	s_mov_b32 m0, s54
	s_nop 0
	global_load_lds_dwordx4 v138, s[42:43]
	s_waitcnt vmcnt(8)
	s_waitcnt lgkmcnt(0)
	s_barrier
	s_setprio 1
	v_mfma_f32_16x16x32_bf16 v[62:65], v[146:149], v[178:181], v[62:65]
	v_mfma_f32_16x16x32_bf16 v[58:61], v[154:157], v[178:181], v[58:61]
	v_mfma_f32_16x16x32_bf16 v[54:57], v[146:149], v[186:189], v[54:57]
	v_mfma_f32_16x16x32_bf16 v[46:49], v[154:157], v[186:189], v[46:49]
	v_mfma_f32_16x16x32_bf16 v[38:41], v[146:149], v[194:197], v[38:41]
	v_mfma_f32_16x16x32_bf16 v[30:33], v[154:157], v[194:197], v[30:33]
	v_mfma_f32_16x16x32_bf16 v[22:25], v[146:149], v[202:205], v[22:25]
	v_mfma_f32_16x16x32_bf16 v[14:17], v[154:157], v[202:205], v[14:17]
	v_mfma_f32_16x16x32_bf16 v[62:65], v[150:153], v[182:185], v[62:65]
	v_mfma_f32_16x16x32_bf16 v[58:61], v[158:161], v[182:185], v[58:61]
	v_mfma_f32_16x16x32_bf16 v[54:57], v[150:153], v[190:193], v[54:57]
	v_mfma_f32_16x16x32_bf16 v[46:49], v[158:161], v[190:193], v[46:49]
	v_mfma_f32_16x16x32_bf16 v[38:41], v[150:153], v[198:201], v[38:41]
	v_mfma_f32_16x16x32_bf16 v[30:33], v[158:161], v[198:201], v[30:33]
	v_mfma_f32_16x16x32_bf16 v[22:25], v[150:153], v[206:209], v[22:25]
	v_mfma_f32_16x16x32_bf16 v[14:17], v[158:161], v[206:209], v[14:17]
	v_mfma_f32_16x16x32_bf16 v[50:53], v[162:165], v[178:181], v[50:53]
	v_mfma_f32_16x16x32_bf16 v[42:45], v[170:173], v[178:181], v[42:45]
	v_mfma_f32_16x16x32_bf16 v[34:37], v[162:165], v[186:189], v[34:37]
	v_mfma_f32_16x16x32_bf16 v[26:29], v[170:173], v[186:189], v[26:29]
	v_mfma_f32_16x16x32_bf16 v[18:21], v[162:165], v[194:197], v[18:21]
	v_mfma_f32_16x16x32_bf16 v[10:13], v[170:173], v[194:197], v[10:13]
	v_mfma_f32_16x16x32_bf16 v[6:9], v[162:165], v[202:205], v[6:9]
	v_mfma_f32_16x16x32_bf16 v[2:5], v[170:173], v[202:205], v[2:5]
	v_mfma_f32_16x16x32_bf16 v[50:53], v[166:169], v[182:185], v[50:53]
	v_mfma_f32_16x16x32_bf16 v[42:45], v[174:177], v[182:185], v[42:45]
	v_mfma_f32_16x16x32_bf16 v[34:37], v[166:169], v[190:193], v[34:37]
	v_mfma_f32_16x16x32_bf16 v[26:29], v[174:177], v[190:193], v[26:29]
	v_mfma_f32_16x16x32_bf16 v[18:21], v[166:169], v[198:201], v[18:21]
	v_mfma_f32_16x16x32_bf16 v[10:13], v[174:177], v[198:201], v[10:13]
	v_mfma_f32_16x16x32_bf16 v[6:9], v[166:169], v[206:209], v[6:9]
	v_mfma_f32_16x16x32_bf16 v[2:5], v[174:177], v[206:209], v[2:5]
	s_setprio 0
	s_barrier
; #define PG8_LDA(dst, b, h) do { _Pragma("unroll") for (int m = 0; m < 4; ++m) _Pragma("unroll") for (int k = 0; k < 2; ++k) dst[m][k] = *(const PG8_LAS bf16x8*)(lds + PG8_SA(b, h) + aoff + m * 2048 + k * 1024); } while (0)
; #define PG8_LDB(dst, b, h) do { _Pragma("unroll") for (int n = 0; n < 2; ++n) _Pragma("unroll") for (int k = 0; k < 2; ++k) dst[n][k] = *(const PG8_LAS bf16x8*)(lds + PG8_SB(b, h) + boff + n * 2048 + k * 1024); } while (0)
; #define PG8_MMA(ai, bj, At, Bt) do { __builtin_amdgcn_s_setprio(1); _Pragma("unroll") for (int m = 0; m < 4; ++m) _Pragma("unroll") for (int n = 0; n < 2; ++n) _Pragma("unroll") for (int k = 0; k < 2; ++k) \
;         acc[ai][bj][m][n] = __builtin_amdgcn_mfma_f32_16x16x32_bf16(Bt[n][k], At[m][k], acc[ai][bj][m][n], 0, 0, 0); __builtin_amdgcn_s_setprio(0); } while (0)
; #define PG8_WAIT_V(n) asm volatile("s_waitcnt vmcnt(" #n ")" ::: "memory")
; #define PG8_WAIT_L(n) asm volatile("s_waitcnt lgkmcnt(" #n ")" ::: "memory")
; #define PG8_BAR __builtin_amdgcn_s_barrier()
; #define PG8_SCHED __builtin_amdgcn_sched_barrier(0)
; template <class Epi, class Sched, bool ALIGN_EPI = false, bool SP2 = false>
; __device__ __forceinline__ void gemm_phase(PG8_LAS unsigned char* lds, const Gemm g, const Sched& S, const Epi& E, const int tid) {
;     ...
;             PG8_LDB(B0, 1, 0); PG8_LDB(B1, 1, 1); PG8_SCHED; PG8_LDA(At, 1, 0); PG8_STAGE(PG8_SA(0, 1), a2 + hstepA, voffA);
;             PG8_WAIT_V(8); PG8_WAIT_L(0); PG8_BAR; PG8_MMA(0, 0, At, B0); PG8_MMA(0, 1, At, B1); PG8_BAR; PG8_SCHED;
;             PG8_LDA(At, 1, 1); PG8_STAGE(PG8_SB(1, 0), b3, voffB); PG8_STAGE(PG8_SB(1, 1), b3 + hstepB, voffB); PG8_STAGE(PG8_SA(1, 0), a3, voffA);
;             PG8_WAIT_V(8); PG8_WAIT_L(0); PG8_BAR; PG8_MMA(1, 0, At, B0); PG8_MMA(1, 1, At, B1); PG8_BAR; PG8_SCHED;
	v_add_u32_e32 v133, 0x18000, v144
	ds_read_b128 v[146:149], v133
	ds_read_b128 v[150:153], v133 offset:1024
	ds_read_b128 v[154:157], v133 offset:2048
	ds_read_b128 v[158:161], v133 offset:3072
	v_add_u32_e32 v133, 0x1c000, v144
	ds_read_b128 v[162:165], v133
	ds_read_b128 v[166:169], v133 offset:1024
	ds_read_b128 v[170:173], v133 offset:2048
	ds_read_b128 v[174:177], v133 offset:3072
	ds_read_b128 v[178:181], v145 offset:32768
	ds_read_b128 v[182:185], v145 offset:33792
	ds_read_b128 v[186:189], v145 offset:34816
	ds_read_b128 v[190:193], v145 offset:35840
	ds_read_b128 v[194:197], v145 offset:36864
	ds_read_b128 v[198:201], v145 offset:37888
	ds_read_b128 v[202:205], v145 offset:38912
	ds_read_b128 v[206:209], v145 offset:39936
	s_add_u32 s28, s42, 0x80000
	s_addc_u32 s29, s43, 0
	s_mov_b32 m0, s55
	s_nop 0
	global_load_lds_dwordx4 v136, s[28:29]
	s_nop 0
	s_mov_b32 m0, s56
	s_nop 0
	global_load_lds_dwordx4 v138, s[28:29]
	s_waitcnt vmcnt(8)
	s_waitcnt lgkmcnt(0)
	s_barrier
	s_setprio 1
	v_mfma_f32_16x16x32_bf16 v[126:129], v[146:149], v[178:181], v[126:129]
	v_mfma_f32_16x16x32_bf16 v[122:125], v[154:157], v[178:181], v[122:125]
	v_mfma_f32_16x16x32_bf16 v[118:121], v[146:149], v[186:189], v[118:121]
	v_mfma_f32_16x16x32_bf16 v[110:113], v[154:157], v[186:189], v[110:113]
	v_mfma_f32_16x16x32_bf16 v[102:105], v[146:149], v[194:197], v[102:105]
	v_mfma_f32_16x16x32_bf16 v[94:97], v[154:157], v[194:197], v[94:97]
	v_mfma_f32_16x16x32_bf16 v[86:89], v[146:149], v[202:205], v[86:89]
	v_mfma_f32_16x16x32_bf16 v[78:81], v[154:157], v[202:205], v[78:81]
	v_mfma_f32_16x16x32_bf16 v[126:129], v[150:153], v[182:185], v[126:129]
	v_mfma_f32_16x16x32_bf16 v[122:125], v[158:161], v[182:185], v[122:125]
	v_mfma_f32_16x16x32_bf16 v[118:121], v[150:153], v[190:193], v[118:121]
	v_mfma_f32_16x16x32_bf16 v[110:113], v[158:161], v[190:193], v[110:113]
	v_mfma_f32_16x16x32_bf16 v[102:105], v[150:153], v[198:201], v[102:105]
	v_mfma_f32_16x16x32_bf16 v[94:97], v[158:161], v[198:201], v[94:97]
	v_mfma_f32_16x16x32_bf16 v[86:89], v[150:153], v[206:209], v[86:89]
	v_mfma_f32_16x16x32_bf16 v[78:81], v[158:161], v[206:209], v[78:81]
	v_mfma_f32_16x16x32_bf16 v[114:117], v[162:165], v[178:181], v[114:117]
	v_mfma_f32_16x16x32_bf16 v[106:109], v[170:173], v[178:181], v[106:109]
	v_mfma_f32_16x16x32_bf16 v[98:101], v[162:165], v[186:189], v[98:101]
	v_mfma_f32_16x16x32_bf16 v[90:93], v[170:173], v[186:189], v[90:93]
	v_mfma_f32_16x16x32_bf16 v[82:85], v[162:165], v[194:197], v[82:85]
	v_mfma_f32_16x16x32_bf16 v[74:77], v[170:173], v[194:197], v[74:77]
	v_mfma_f32_16x16x32_bf16 v[70:73], v[162:165], v[202:205], v[70:73]
	v_mfma_f32_16x16x32_bf16 v[66:69], v[170:173], v[202:205], v[66:69]
	v_mfma_f32_16x16x32_bf16 v[114:117], v[166:169], v[182:185], v[114:117]
	v_mfma_f32_16x16x32_bf16 v[106:109], v[174:177], v[182:185], v[106:109]
	v_mfma_f32_16x16x32_bf16 v[98:101], v[166:169], v[190:193], v[98:101]
	v_mfma_f32_16x16x32_bf16 v[90:93], v[174:177], v[190:193], v[90:93]
	v_mfma_f32_16x16x32_bf16 v[82:85], v[166:169], v[198:201], v[82:85]
	v_mfma_f32_16x16x32_bf16 v[74:77], v[174:177], v[198:201], v[74:77]
	v_mfma_f32_16x16x32_bf16 v[70:73], v[166:169], v[206:209], v[70:73]
	v_mfma_f32_16x16x32_bf16 v[66:69], v[174:177], v[206:209], v[66:69]
	s_setprio 0
	s_barrier
	ds_read_b128 v[178:181], v145 offset:49152
	ds_read_b128 v[182:185], v145 offset:50176
	ds_read_b128 v[186:189], v145 offset:51200
	ds_read_b128 v[190:193], v145 offset:52224
	ds_read_b128 v[194:197], v145 offset:53248
	ds_read_b128 v[198:201], v145 offset:54272
	ds_read_b128 v[202:205], v145 offset:55296
	ds_read_b128 v[206:209], v145 offset:56320
	s_mov_b32 m0, s57
	s_nop 0
	global_load_lds_dwordx4 v137, s[40:41]
	s_add_u32 s28, s30, 0x80080
	s_mov_b32 m0, s58
	s_nop 0
	global_load_lds_dwordx4 v139, s[40:41]
	s_addc_u32 s29, s31, 0
	s_mov_b32 m0, s65
	s_nop 0
	global_load_lds_dwordx4 v137, s[28:29]
	s_nop 0
	s_mov_b32 m0, s69
	s_nop 0
	global_load_lds_dwordx4 v139, s[28:29]
	s_nop 0
	s_mov_b32 m0, s61
	s_nop 0
	global_load_lds_dwordx4 v136, s[38:39]
	s_nop 0
	s_mov_b32 m0, s64
	s_nop 0
	global_load_lds_dwordx4 v138, s[38:39]
	s_waitcnt vmcnt(8)
	s_waitcnt lgkmcnt(0)
	s_barrier
	s_setprio 1
	v_mfma_f32_16x16x32_bf16 v[62:65], v[146:149], v[178:181], v[62:65]
	v_mfma_f32_16x16x32_bf16 v[58:61], v[154:157], v[178:181], v[58:61]
	v_mfma_f32_16x16x32_bf16 v[54:57], v[146:149], v[186:189], v[54:57]
	v_mfma_f32_16x16x32_bf16 v[46:49], v[154:157], v[186:189], v[46:49]
	v_mfma_f32_16x16x32_bf16 v[38:41], v[146:149], v[194:197], v[38:41]
	v_mfma_f32_16x16x32_bf16 v[30:33], v[154:157], v[194:197], v[30:33]
	v_mfma_f32_16x16x32_bf16 v[22:25], v[146:149], v[202:205], v[22:25]
	v_mfma_f32_16x16x32_bf16 v[14:17], v[154:157], v[202:205], v[14:17]
	v_mfma_f32_16x16x32_bf16 v[62:65], v[150:153], v[182:185], v[62:65]
	v_mfma_f32_16x16x32_bf16 v[58:61], v[158:161], v[182:185], v[58:61]
	v_mfma_f32_16x16x32_bf16 v[54:57], v[150:153], v[190:193], v[54:57]
	v_mfma_f32_16x16x32_bf16 v[46:49], v[158:161], v[190:193], v[46:49]
	v_mfma_f32_16x16x32_bf16 v[38:41], v[150:153], v[198:201], v[38:41]
	v_mfma_f32_16x16x32_bf16 v[30:33], v[158:161], v[198:201], v[30:33]
	v_mfma_f32_16x16x32_bf16 v[22:25], v[150:153], v[206:209], v[22:25]
	v_mfma_f32_16x16x32_bf16 v[14:17], v[158:161], v[206:209], v[14:17]
	v_mfma_f32_16x16x32_bf16 v[50:53], v[162:165], v[178:181], v[50:53]
	v_mfma_f32_16x16x32_bf16 v[42:45], v[170:173], v[178:181], v[42:45]
	v_mfma_f32_16x16x32_bf16 v[34:37], v[162:165], v[186:189], v[34:37]
	v_mfma_f32_16x16x32_bf16 v[26:29], v[170:173], v[186:189], v[26:29]
	v_mfma_f32_16x16x32_bf16 v[18:21], v[162:165], v[194:197], v[18:21]
	v_mfma_f32_16x16x32_bf16 v[10:13], v[170:173], v[194:197], v[10:13]
	v_mfma_f32_16x16x32_bf16 v[6:9], v[162:165], v[202:205], v[6:9]
	v_mfma_f32_16x16x32_bf16 v[2:5], v[170:173], v[202:205], v[2:5]
	v_mfma_f32_16x16x32_bf16 v[50:53], v[166:169], v[182:185], v[50:53]
	v_mfma_f32_16x16x32_bf16 v[42:45], v[174:177], v[182:185], v[42:45]
	v_mfma_f32_16x16x32_bf16 v[34:37], v[166:169], v[190:193], v[34:37]
	v_mfma_f32_16x16x32_bf16 v[26:29], v[174:177], v[190:193], v[26:29]
	v_mfma_f32_16x16x32_bf16 v[18:21], v[166:169], v[198:201], v[18:21]
	v_mfma_f32_16x16x32_bf16 v[10:13], v[174:177], v[198:201], v[10:13]
	v_mfma_f32_16x16x32_bf16 v[6:9], v[166:169], v[206:209], v[6:9]
	v_mfma_f32_16x16x32_bf16 v[2:5], v[174:177], v[206:209], v[2:5]
	s_setprio 0
	s_barrier
	s_add_i32 s67, s67, 2
	s_add_u32 s97, s97, 0x100
	s_addc_u32 s59, s59, 0
	s_cmp_gt_u32 s67, 29
	s_mov_b64 s[28:29], s[34:35]
	s_cbranch_scc1 .LBB0_549

; #define PG8_LDA(dst, b, h) do { _Pragma("unroll") for (int m = 0; m < 4; ++m) _Pragma("unroll") for (int k = 0; k < 2; ++k) dst[m][k] = *(const PG8_LAS bf16x8*)(lds + PG8_SA(b, h) + aoff + m * 2048 + k * 1024); } while (0)
; #define PG8_LDB(dst, b, h) do { _Pragma("unroll") for (int n = 0; n < 2; ++n) _Pragma("unroll") for (int k = 0; k < 2; ++k) dst[n][k] = *(const PG8_LAS bf16x8*)(lds + PG8_SB(b, h) + boff + n * 2048 + k * 1024); } while (0)
; #define PG8_MMA(ai, bj, At, Bt) do { __builtin_amdgcn_s_setprio(1); _Pragma("unroll") for (int m = 0; m < 4; ++m) _Pragma("unroll") for (int n = 0; n < 2; ++n) _Pragma("unroll") for (int k = 0; k < 2; ++k) \
;         acc[ai][bj][m][n] = __builtin_amdgcn_mfma_f32_16x16x32_bf16(Bt[n][k], At[m][k], acc[ai][bj][m][n], 0, 0, 0); __builtin_amdgcn_s_setprio(0); } while (0)
; #define PG8_WAIT_V(n) asm volatile("s_waitcnt vmcnt(" #n ")" ::: "memory")
; #define PG8_WAIT_L(n) asm volatile("s_waitcnt lgkmcnt(" #n ")" ::: "memory")
; #define PG8_BAR __builtin_amdgcn_s_barrier()
; #define PG8_SCHED __builtin_amdgcn_sched_barrier(0)
; template <class Epi, class Sched, bool ALIGN_EPI = false, bool SP2 = false>
; __device__ __forceinline__ void gemm_phase(PG8_LAS unsigned char* lds, const Gemm g, const Sched& S, const Epi& E, const int tid) {
;     ...
;             const char* a1 = cA + (size_t)(t + 1) * kstepA;
;             const char* a2 = last ? nA : cA + (size_t)(t + 2) * kstepA; const char* b2 = last ? nB : cB + (size_t)(t + 2) * kstepB;
;             const char* a3 = a2 + kstepA; const char* b3 = b2 + kstepB;
;             if (last && has_next) S.a_ready(nxt);
;             if constexpr (SP2) {
;             PG8_LDB(B0, 0, 0); PG8_LDB(B1, 0, 1); PG8_SCHED; PG8_LDA(At, 0, 0); PG8_STAGE(PG8_SA(1, 1), a1 + hstepA, voffA);
;             PG8_WAIT_V(8); PG8_WAIT_L(0); PG8_BAR; PG8_MMA(0, 0, At, B0); PG8_MMA(0, 1, At, B1); PG8_BAR; PG8_SCHED;
;             PG8_LDA(At, 0, 1); PG8_STAGE(PG8_SB(0, 0), b2, voffB); PG8_STAGE(PG8_SB(0, 1), b2 + hstepB, voffB); PG8_STAGE(PG8_SA(0, 0), a2, voffA);
;             PG8_WAIT_V(8); PG8_WAIT_L(0); PG8_BAR; PG8_MMA(1, 0, At, B0); PG8_MMA(1, 1, At, B1); PG8_BAR; PG8_SCHED;
.LBB0_813:
	v_add_u32_e32 v0, 0x10000, v135
	ds_read_b128 v[138:141], v0
	ds_read_b128 v[142:145], v0 offset:1024
	ds_read_b128 v[146:149], v0 offset:2048
	ds_read_b128 v[150:153], v0 offset:3072
	v_add_u32_e32 v0, 0x14000, v135
	ds_read_b128 v[154:157], v0
	ds_read_b128 v[158:161], v0 offset:1024
	ds_read_b128 v[162:165], v0 offset:2048
	ds_read_b128 v[166:169], v0 offset:3072
	s_add_u32 s4, s18, 0x100
	s_addc_u32 s5, s19, 0
	s_cmp_eq_u32 s61, 12
	s_cselect_b32 s24, s14, s4
	s_cselect_b32 s25, s15, s5
	s_cselect_b32 s22, s57, s58
	s_cselect_b32 s23, s13, s59
	s_add_u32 s20, s24, 0x80
	s_addc_u32 s21, s25, 0
	ds_read_b128 v[170:173], v136
	ds_read_b128 v[174:177], v136 offset:1024
	ds_read_b128 v[178:181], v136 offset:2048
	ds_read_b128 v[182:185], v136 offset:3072
	ds_read_b128 v[186:189], v136 offset:4096
	ds_read_b128 v[190:193], v136 offset:5120
	ds_read_b128 v[194:197], v136 offset:6144
	ds_read_b128 v[198:201], v136 offset:7168
	s_add_u32 s18, s18, 0xc0080
	s_addc_u32 s19, s19, 0
	s_mov_b32 m0, s49
	s_nop 0
	global_load_lds_dwordx4 v131, s[18:19]
	s_nop 0
	s_mov_b32 m0, s50
	s_nop 0
	global_load_lds_dwordx4 v133, s[18:19]
	s_waitcnt vmcnt(8)
	s_waitcnt lgkmcnt(0)
	s_barrier
	s_setprio 1
	v_mfma_f32_16x16x32_bf16 v[126:129], v[138:141], v[170:173], v[126:129]
	v_mfma_f32_16x16x32_bf16 v[122:125], v[146:149], v[170:173], v[122:125]
	v_mfma_f32_16x16x32_bf16 v[118:121], v[138:141], v[178:181], v[118:121]
	v_mfma_f32_16x16x32_bf16 v[114:117], v[146:149], v[178:181], v[114:117]
	v_mfma_f32_16x16x32_bf16 v[102:105], v[138:141], v[186:189], v[102:105]
	v_mfma_f32_16x16x32_bf16 v[98:101], v[146:149], v[186:189], v[98:101]
	v_mfma_f32_16x16x32_bf16 v[86:89], v[138:141], v[194:197], v[86:89]
	v_mfma_f32_16x16x32_bf16 v[82:85], v[146:149], v[194:197], v[82:85]
	v_mfma_f32_16x16x32_bf16 v[126:129], v[142:145], v[174:177], v[126:129]
	v_mfma_f32_16x16x32_bf16 v[122:125], v[150:153], v[174:177], v[122:125]
	v_mfma_f32_16x16x32_bf16 v[118:121], v[142:145], v[182:185], v[118:121]
	v_mfma_f32_16x16x32_bf16 v[114:117], v[150:153], v[182:185], v[114:117]
	v_mfma_f32_16x16x32_bf16 v[102:105], v[142:145], v[190:193], v[102:105]
	v_mfma_f32_16x16x32_bf16 v[98:101], v[150:153], v[190:193], v[98:101]
	v_mfma_f32_16x16x32_bf16 v[86:89], v[142:145], v[198:201], v[86:89]
	v_mfma_f32_16x16x32_bf16 v[82:85], v[150:153], v[198:201], v[82:85]
	v_mfma_f32_16x16x32_bf16 v[110:113], v[154:157], v[170:173], v[110:113]
	v_mfma_f32_16x16x32_bf16 v[106:109], v[162:165], v[170:173], v[106:109]
	v_mfma_f32_16x16x32_bf16 v[94:97], v[154:157], v[178:181], v[94:97]
	v_mfma_f32_16x16x32_bf16 v[90:93], v[162:165], v[178:181], v[90:93]
	v_mfma_f32_16x16x32_bf16 v[78:81], v[154:157], v[186:189], v[78:81]
	v_mfma_f32_16x16x32_bf16 v[74:77], v[162:165], v[186:189], v[74:77]
	v_mfma_f32_16x16x32_bf16 v[70:73], v[154:157], v[194:197], v[70:73]
	v_mfma_f32_16x16x32_bf16 v[66:69], v[162:165], v[194:197], v[66:69]
	v_mfma_f32_16x16x32_bf16 v[110:113], v[158:161], v[174:177], v[110:113]
	v_mfma_f32_16x16x32_bf16 v[106:109], v[166:169], v[174:177], v[106:109]
	v_mfma_f32_16x16x32_bf16 v[94:97], v[158:161], v[182:185], v[94:97]
	v_mfma_f32_16x16x32_bf16 v[90:93], v[166:169], v[182:185], v[90:93]
	v_mfma_f32_16x16x32_bf16 v[78:81], v[158:161], v[190:193], v[78:81]
	v_mfma_f32_16x16x32_bf16 v[74:77], v[166:169], v[190:193], v[74:77]
	v_mfma_f32_16x16x32_bf16 v[70:73], v[158:161], v[198:201], v[70:73]
	v_mfma_f32_16x16x32_bf16 v[66:69], v[166:169], v[198:201], v[66:69]
	s_setprio 0
	s_barrier
	ds_read_b128 v[170:173], v136 offset:16384
	ds_read_b128 v[174:177], v136 offset:17408
	ds_read_b128 v[178:181], v136 offset:18432
	ds_read_b128 v[182:185], v136 offset:19456
	ds_read_b128 v[186:189], v136 offset:20480
	ds_read_b128 v[190:193], v136 offset:21504
	ds_read_b128 v[194:197], v136 offset:22528
	ds_read_b128 v[198:201], v136 offset:23552
	s_mov_b32 m0, s31
	s_nop 0
	global_load_lds_dwordx4 v132, s[22:23]
	s_nop 0
	s_mov_b32 m0, s34
	s_nop 0
	global_load_lds_dwordx4 v134, s[22:23]
	s_add_u32 s18, s22, 0x40000
	s_addc_u32 s19, s23, 0
	s_mov_b32 m0, s35
	s_nop 0
	global_load_lds_dwordx4 v132, s[18:19]
	s_nop 0
	s_mov_b32 m0, s37
	s_nop 0
	global_load_lds_dwordx4 v134, s[18:19]
	s_mov_b32 m0, s10
	s_nop 0
	global_load_lds_dwordx4 v131, s[24:25]
	s_nop 0
	s_mov_b32 m0, s38
	s_nop 0
	global_load_lds_dwordx4 v133, s[24:25]
	s_waitcnt vmcnt(8)
	s_waitcnt lgkmcnt(0)
	s_barrier
	s_setprio 1
	v_mfma_f32_16x16x32_bf16 v[62:65], v[138:141], v[170:173], v[62:65]
	v_mfma_f32_16x16x32_bf16 v[58:61], v[146:149], v[170:173], v[58:61]
	v_mfma_f32_16x16x32_bf16 v[54:57], v[138:141], v[178:181], v[54:57]
	v_mfma_f32_16x16x32_bf16 v[50:53], v[146:149], v[178:181], v[50:53]
	v_mfma_f32_16x16x32_bf16 v[38:41], v[138:141], v[186:189], v[38:41]
	v_mfma_f32_16x16x32_bf16 v[34:37], v[146:149], v[186:189], v[34:37]
	v_mfma_f32_16x16x32_bf16 v[22:25], v[138:141], v[194:197], v[22:25]
	v_mfma_f32_16x16x32_bf16 v[18:21], v[146:149], v[194:197], v[18:21]
	v_mfma_f32_16x16x32_bf16 v[62:65], v[142:145], v[174:177], v[62:65]
	v_mfma_f32_16x16x32_bf16 v[58:61], v[150:153], v[174:177], v[58:61]
	v_mfma_f32_16x16x32_bf16 v[54:57], v[142:145], v[182:185], v[54:57]
	v_mfma_f32_16x16x32_bf16 v[50:53], v[150:153], v[182:185], v[50:53]
	v_mfma_f32_16x16x32_bf16 v[38:41], v[142:145], v[190:193], v[38:41]
	v_mfma_f32_16x16x32_bf16 v[34:37], v[150:153], v[190:193], v[34:37]
	v_mfma_f32_16x16x32_bf16 v[22:25], v[142:145], v[198:201], v[22:25]
	v_mfma_f32_16x16x32_bf16 v[18:21], v[150:153], v[198:201], v[18:21]
	v_mfma_f32_16x16x32_bf16 v[46:49], v[154:157], v[170:173], v[46:49]
	v_mfma_f32_16x16x32_bf16 v[42:45], v[162:165], v[170:173], v[42:45]
	v_mfma_f32_16x16x32_bf16 v[30:33], v[154:157], v[178:181], v[30:33]
	v_mfma_f32_16x16x32_bf16 v[26:29], v[162:165], v[178:181], v[26:29]
	v_mfma_f32_16x16x32_bf16 v[14:17], v[154:157], v[186:189], v[14:17]
	v_mfma_f32_16x16x32_bf16 v[10:13], v[162:165], v[186:189], v[10:13]
	v_mfma_f32_16x16x32_bf16 v[6:9], v[154:157], v[194:197], v[6:9]
	v_mfma_f32_16x16x32_bf16 v[2:5], v[162:165], v[194:197], v[2:5]
	v_mfma_f32_16x16x32_bf16 v[46:49], v[158:161], v[174:177], v[46:49]
	v_mfma_f32_16x16x32_bf16 v[42:45], v[166:169], v[174:177], v[42:45]
	v_mfma_f32_16x16x32_bf16 v[30:33], v[158:161], v[182:185], v[30:33]
	v_mfma_f32_16x16x32_bf16 v[26:29], v[166:169], v[182:185], v[26:29]
	v_mfma_f32_16x16x32_bf16 v[14:17], v[158:161], v[190:193], v[14:17]
	v_mfma_f32_16x16x32_bf16 v[10:13], v[166:169], v[190:193], v[10:13]
	v_mfma_f32_16x16x32_bf16 v[6:9], v[158:161], v[198:201], v[6:9]
	v_mfma_f32_16x16x32_bf16 v[2:5], v[166:169], v[198:201], v[2:5]
	s_setprio 0
	s_barrier
; #define PG8_LDA(dst, b, h) do { _Pragma("unroll") for (int m = 0; m < 4; ++m) _Pragma("unroll") for (int k = 0; k < 2; ++k) dst[m][k] = *(const PG8_LAS bf16x8*)(lds + PG8_SA(b, h) + aoff + m * 2048 + k * 1024); } while (0)
; #define PG8_LDB(dst, b, h) do { _Pragma("unroll") for (int n = 0; n < 2; ++n) _Pragma("unroll") for (int k = 0; k < 2; ++k) dst[n][k] = *(const PG8_LAS bf16x8*)(lds + PG8_SB(b, h) + boff + n * 2048 + k * 1024); } while (0)
; #define PG8_MMA(ai, bj, At, Bt) do { __builtin_amdgcn_s_setprio(1); _Pragma("unroll") for (int m = 0; m < 4; ++m) _Pragma("unroll") for (int n = 0; n < 2; ++n) _Pragma("unroll") for (int k = 0; k < 2; ++k) \
;         acc[ai][bj][m][n] = __builtin_amdgcn_mfma_f32_16x16x32_bf16(Bt[n][k], At[m][k], acc[ai][bj][m][n], 0, 0, 0); __builtin_amdgcn_s_setprio(0); } while (0)
; #define PG8_WAIT_V(n) asm volatile("s_waitcnt vmcnt(" #n ")" ::: "memory")
; #define PG8_WAIT_L(n) asm volatile("s_waitcnt lgkmcnt(" #n ")" ::: "memory")
; #define PG8_BAR __builtin_amdgcn_s_barrier()
; #define PG8_SCHED __builtin_amdgcn_sched_barrier(0)
; template <class Epi, class Sched, bool ALIGN_EPI = false, bool SP2 = false>
; __device__ __forceinline__ void gemm_phase(PG8_LAS unsigned char* lds, const Gemm g, const Sched& S, const Epi& E, const int tid) {
;     ...
;             PG8_LDB(B0, 1, 0); PG8_LDB(B1, 1, 1); PG8_SCHED; PG8_LDA(At, 1, 0); PG8_STAGE(PG8_SA(0, 1), a2 + hstepA, voffA);
;             PG8_WAIT_V(8); PG8_WAIT_L(0); PG8_BAR; PG8_MMA(0, 0, At, B0); PG8_MMA(0, 1, At, B1); PG8_BAR; PG8_SCHED;
;             PG8_LDA(At, 1, 1); PG8_STAGE(PG8_SB(1, 0), b3, voffB); PG8_STAGE(PG8_SB(1, 1), b3 + hstepB, voffB); PG8_STAGE(PG8_SA(1, 0), a3, voffA);
;             PG8_WAIT_V(8); PG8_WAIT_L(0); PG8_BAR; PG8_MMA(1, 0, At, B0); PG8_MMA(1, 1, At, B1); PG8_BAR; PG8_SCHED;
	v_add_u32_e32 v0, 0x18000, v135
	ds_read_b128 v[138:141], v0
	ds_read_b128 v[142:145], v0 offset:1024
	ds_read_b128 v[146:149], v0 offset:2048
	ds_read_b128 v[150:153], v0 offset:3072
	v_add_u32_e32 v0, 0x1c000, v135
	ds_read_b128 v[154:157], v0
	ds_read_b128 v[158:161], v0 offset:1024
	ds_read_b128 v[162:165], v0 offset:2048
	ds_read_b128 v[166:169], v0 offset:3072
	ds_read_b128 v[170:173], v136 offset:32768
	ds_read_b128 v[174:177], v136 offset:33792
	ds_read_b128 v[178:181], v136 offset:34816
	ds_read_b128 v[182:185], v136 offset:35840
	ds_read_b128 v[186:189], v136 offset:36864
	ds_read_b128 v[190:193], v136 offset:37888
	ds_read_b128 v[194:197], v136 offset:38912
	ds_read_b128 v[198:201], v136 offset:39936
	s_add_u32 s18, s24, 0xc0000
	s_addc_u32 s19, s25, 0
	s_mov_b32 m0, s39
	s_nop 0
	global_load_lds_dwordx4 v131, s[18:19]
	s_nop 0
	s_mov_b32 m0, s40
	s_nop 0
	global_load_lds_dwordx4 v133, s[18:19]
	s_waitcnt vmcnt(8)
	s_waitcnt lgkmcnt(0)
	s_barrier
	s_setprio 1
	v_mfma_f32_16x16x32_bf16 v[126:129], v[138:141], v[170:173], v[126:129]
	v_mfma_f32_16x16x32_bf16 v[122:125], v[146:149], v[170:173], v[122:125]
	v_mfma_f32_16x16x32_bf16 v[118:121], v[138:141], v[178:181], v[118:121]
	v_mfma_f32_16x16x32_bf16 v[114:117], v[146:149], v[178:181], v[114:117]
	v_mfma_f32_16x16x32_bf16 v[102:105], v[138:141], v[186:189], v[102:105]
	v_mfma_f32_16x16x32_bf16 v[98:101], v[146:149], v[186:189], v[98:101]
	v_mfma_f32_16x16x32_bf16 v[86:89], v[138:141], v[194:197], v[86:89]
	v_mfma_f32_16x16x32_bf16 v[82:85], v[146:149], v[194:197], v[82:85]
	v_mfma_f32_16x16x32_bf16 v[126:129], v[142:145], v[174:177], v[126:129]
	v_mfma_f32_16x16x32_bf16 v[122:125], v[150:153], v[174:177], v[122:125]
	v_mfma_f32_16x16x32_bf16 v[118:121], v[142:145], v[182:185], v[118:121]
	v_mfma_f32_16x16x32_bf16 v[114:117], v[150:153], v[182:185], v[114:117]
	v_mfma_f32_16x16x32_bf16 v[102:105], v[142:145], v[190:193], v[102:105]
	v_mfma_f32_16x16x32_bf16 v[98:101], v[150:153], v[190:193], v[98:101]
	v_mfma_f32_16x16x32_bf16 v[86:89], v[142:145], v[198:201], v[86:89]
	v_mfma_f32_16x16x32_bf16 v[82:85], v[150:153], v[198:201], v[82:85]
	v_mfma_f32_16x16x32_bf16 v[110:113], v[154:157], v[170:173], v[110:113]
	v_mfma_f32_16x16x32_bf16 v[106:109], v[162:165], v[170:173], v[106:109]
	v_mfma_f32_16x16x32_bf16 v[94:97], v[154:157], v[178:181], v[94:97]
	v_mfma_f32_16x16x32_bf16 v[90:93], v[162:165], v[178:181], v[90:93]
	v_mfma_f32_16x16x32_bf16 v[78:81], v[154:157], v[186:189], v[78:81]
	v_mfma_f32_16x16x32_bf16 v[74:77], v[162:165], v[186:189], v[74:77]
	v_mfma_f32_16x16x32_bf16 v[70:73], v[154:157], v[194:197], v[70:73]
	v_mfma_f32_16x16x32_bf16 v[66:69], v[162:165], v[194:197], v[66:69]
	v_mfma_f32_16x16x32_bf16 v[110:113], v[158:161], v[174:177], v[110:113]
	v_mfma_f32_16x16x32_bf16 v[106:109], v[166:169], v[174:177], v[106:109]
	v_mfma_f32_16x16x32_bf16 v[94:97], v[158:161], v[182:185], v[94:97]
	v_mfma_f32_16x16x32_bf16 v[90:93], v[166:169], v[182:185], v[90:93]
	v_mfma_f32_16x16x32_bf16 v[78:81], v[158:161], v[190:193], v[78:81]
	v_mfma_f32_16x16x32_bf16 v[74:77], v[166:169], v[190:193], v[74:77]
	v_mfma_f32_16x16x32_bf16 v[70:73], v[158:161], v[198:201], v[70:73]
	v_mfma_f32_16x16x32_bf16 v[66:69], v[166:169], v[198:201], v[66:69]
	s_setprio 0
	s_barrier
	ds_read_b128 v[170:173], v136 offset:49152
	ds_read_b128 v[174:177], v136 offset:50176
	ds_read_b128 v[178:181], v136 offset:51200
	ds_read_b128 v[182:185], v136 offset:52224
	ds_read_b128 v[186:189], v136 offset:53248
	ds_read_b128 v[190:193], v136 offset:54272
	ds_read_b128 v[194:197], v136 offset:55296
	ds_read_b128 v[198:201], v136 offset:56320
	s_add_u32 s18, s22, 0x80
	s_addc_u32 s19, s23, 0
	s_mov_b32 m0, s43
	s_nop 0
	global_load_lds_dwordx4 v132, s[18:19]
	s_nop 0
	s_mov_b32 m0, s44
	s_nop 0
	global_load_lds_dwordx4 v134, s[18:19]
	s_add_u32 s18, s22, 0x40080
	s_addc_u32 s19, s23, 0
	s_mov_b32 m0, s47
	s_nop 0
	global_load_lds_dwordx4 v132, s[18:19]
	s_nop 0
	s_mov_b32 m0, s48
	s_nop 0
	global_load_lds_dwordx4 v134, s[18:19]
	s_mov_b32 m0, s45
	s_nop 0
	global_load_lds_dwordx4 v131, s[20:21]
	s_nop 0
	s_mov_b32 m0, s46
	s_nop 0
	global_load_lds_dwordx4 v133, s[20:21]
	s_waitcnt vmcnt(8)
	s_waitcnt lgkmcnt(0)
	s_barrier
	s_setprio 1
	v_mfma_f32_16x16x32_bf16 v[62:65], v[138:141], v[170:173], v[62:65]
	v_mfma_f32_16x16x32_bf16 v[58:61], v[146:149], v[170:173], v[58:61]
	v_mfma_f32_16x16x32_bf16 v[54:57], v[138:141], v[178:181], v[54:57]
	v_mfma_f32_16x16x32_bf16 v[50:53], v[146:149], v[178:181], v[50:53]
	v_mfma_f32_16x16x32_bf16 v[38:41], v[138:141], v[186:189], v[38:41]
	v_mfma_f32_16x16x32_bf16 v[34:37], v[146:149], v[186:189], v[34:37]
	v_mfma_f32_16x16x32_bf16 v[22:25], v[138:141], v[194:197], v[22:25]
	v_mfma_f32_16x16x32_bf16 v[18:21], v[146:149], v[194:197], v[18:21]
	v_mfma_f32_16x16x32_bf16 v[62:65], v[142:145], v[174:177], v[62:65]
	v_mfma_f32_16x16x32_bf16 v[58:61], v[150:153], v[174:177], v[58:61]
	v_mfma_f32_16x16x32_bf16 v[54:57], v[142:145], v[182:185], v[54:57]
	v_mfma_f32_16x16x32_bf16 v[50:53], v[150:153], v[182:185], v[50:53]
	v_mfma_f32_16x16x32_bf16 v[38:41], v[142:145], v[190:193], v[38:41]
	v_mfma_f32_16x16x32_bf16 v[34:37], v[150:153], v[190:193], v[34:37]
	v_mfma_f32_16x16x32_bf16 v[22:25], v[142:145], v[198:201], v[22:25]
	v_mfma_f32_16x16x32_bf16 v[18:21], v[150:153], v[198:201], v[18:21]
	v_mfma_f32_16x16x32_bf16 v[46:49], v[154:157], v[170:173], v[46:49]
	v_mfma_f32_16x16x32_bf16 v[42:45], v[162:165], v[170:173], v[42:45]
	v_mfma_f32_16x16x32_bf16 v[30:33], v[154:157], v[178:181], v[30:33]
	v_mfma_f32_16x16x32_bf16 v[26:29], v[162:165], v[178:181], v[26:29]
	v_mfma_f32_16x16x32_bf16 v[14:17], v[154:157], v[186:189], v[14:17]
	v_mfma_f32_16x16x32_bf16 v[10:13], v[162:165], v[186:189], v[10:13]
	v_mfma_f32_16x16x32_bf16 v[6:9], v[154:157], v[194:197], v[6:9]
	v_mfma_f32_16x16x32_bf16 v[2:5], v[162:165], v[194:197], v[2:5]
	v_mfma_f32_16x16x32_bf16 v[46:49], v[158:161], v[174:177], v[46:49]
	v_mfma_f32_16x16x32_bf16 v[42:45], v[166:169], v[174:177], v[42:45]
	v_mfma_f32_16x16x32_bf16 v[30:33], v[158:161], v[182:185], v[30:33]
	v_mfma_f32_16x16x32_bf16 v[26:29], v[166:169], v[182:185], v[26:29]
	v_mfma_f32_16x16x32_bf16 v[14:17], v[158:161], v[190:193], v[14:17]
	v_mfma_f32_16x16x32_bf16 v[10:13], v[166:169], v[190:193], v[10:13]
	v_mfma_f32_16x16x32_bf16 v[6:9], v[158:161], v[198:201], v[6:9]
	v_mfma_f32_16x16x32_bf16 v[2:5], v[166:169], v[198:201], v[2:5]
	s_setprio 0
	s_barrier
	s_add_i32 s61, s61, 2
	s_add_u32 s58, s58, 0x100
	s_addc_u32 s59, s59, 0
	s_cmp_gt_u32 s61, 13
	s_mov_b64 s[18:19], s[4:5]
	s_cbranch_scc0 .LBB0_813
	s_and_b64 vcc, exec, s[8:9]
	s_cbranch_vccz .LBB0_816
	s_barrier

; #define PG8_LDA(dst, b, h) do { _Pragma("unroll") for (int m = 0; m < 4; ++m) _Pragma("unroll") for (int k = 0; k < 2; ++k) dst[m][k] = *(const PG8_LAS bf16x8*)(lds + PG8_SA(b, h) + aoff + m * 2048 + k * 1024); } while (0)
; #define PG8_LDB(dst, b, h) do { _Pragma("unroll") for (int n = 0; n < 2; ++n) _Pragma("unroll") for (int k = 0; k < 2; ++k) dst[n][k] = *(const PG8_LAS bf16x8*)(lds + PG8_SB(b, h) + boff + n * 2048 + k * 1024); } while (0)
; #define PG8_MMA(ai, bj, At, Bt) do { __builtin_amdgcn_s_setprio(1); _Pragma("unroll") for (int m = 0; m < 4; ++m) _Pragma("unroll") for (int n = 0; n < 2; ++n) _Pragma("unroll") for (int k = 0; k < 2; ++k) \
;         acc[ai][bj][m][n] = __builtin_amdgcn_mfma_f32_16x16x32_bf16(Bt[n][k], At[m][k], acc[ai][bj][m][n], 0, 0, 0); __builtin_amdgcn_s_setprio(0); } while (0)
; #define PG8_WAIT_V(n) asm volatile("s_waitcnt vmcnt(" #n ")" ::: "memory")
; #define PG8_WAIT_L(n) asm volatile("s_waitcnt lgkmcnt(" #n ")" ::: "memory")
; #define PG8_BAR __builtin_amdgcn_s_barrier()
; #define PG8_SCHED __builtin_amdgcn_sched_barrier(0)
; template <class Epi, class Sched, bool ALIGN_EPI = false, bool SP2 = false>
; __device__ __forceinline__ void gemm_phase(PG8_LAS unsigned char* lds, const Gemm g, const Sched& S, const Epi& E, const int tid) {
;     ...
;             const char* a1 = cA + (size_t)(t + 1) * kstepA;
;             const char* a2 = last ? nA : cA + (size_t)(t + 2) * kstepA; const char* b2 = last ? nB : cB + (size_t)(t + 2) * kstepB;
;             const char* a3 = a2 + kstepA; const char* b3 = b2 + kstepB;
;             if (last && has_next) S.a_ready(nxt);
;             if constexpr (SP2) {
;             PG8_LDB(B0, 0, 0); PG8_LDB(B1, 0, 1); PG8_SCHED; PG8_LDA(At, 0, 0); PG8_STAGE(PG8_SA(1, 1), a1 + hstepA, voffA);
;             PG8_WAIT_V(8); PG8_WAIT_L(0); PG8_BAR; PG8_MMA(0, 0, At, B0); PG8_MMA(0, 1, At, B1); PG8_BAR; PG8_SCHED;
;             PG8_LDA(At, 0, 1); PG8_STAGE(PG8_SB(0, 0), b2, voffB); PG8_STAGE(PG8_SB(0, 1), b2 + hstepB, voffB); PG8_STAGE(PG8_SA(0, 0), a2, voffA);
;             PG8_WAIT_V(8); PG8_WAIT_L(0); PG8_BAR; PG8_MMA(1, 0, At, B0); PG8_MMA(1, 1, At, B1); PG8_BAR; PG8_SCHED;
.LBB0_899:
	s_or_b64 exec, exec, s[42:43]
	v_add_u32_e32 v144, 0x10000, v200
	v_add_u32_e32 v160, 0x14000, v200
	s_add_u32 s42, s34, 0x100
	ds_read_b128 v[132:135], v144
	ds_read_b128 v[136:139], v144 offset:1024
	ds_read_b128 v[140:143], v144 offset:2048
	ds_read_b128 v[144:147], v144 offset:3072
	ds_read_b128 v[148:151], v160
	ds_read_b128 v[152:155], v160 offset:1024
	ds_read_b128 v[156:159], v160 offset:2048
	ds_read_b128 v[160:163], v160 offset:3072
	s_addc_u32 s43, s35, 0
	s_and_b64 s[40:41], s[40:41], exec
	s_cselect_b32 s48, vcc_lo, s42
	s_cselect_b32 s49, s21, s43
	s_cselect_b32 s41, s23, s67
	s_cselect_b32 s40, vcc_hi, s59
	s_add_u32 s44, s48, 0x80
	s_addc_u32 s45, s49, 0
	s_add_u32 s46, s40, 0x80
	s_addc_u32 s47, s41, 0
	ds_read_b128 v[164:167], v201
	ds_read_b128 v[168:171], v201 offset:1024
	ds_read_b128 v[172:175], v201 offset:2048
	ds_read_b128 v[176:179], v201 offset:3072
	ds_read_b128 v[180:183], v201 offset:4096
	ds_read_b128 v[184:187], v201 offset:5120
	ds_read_b128 v[202:205], v201 offset:6144
	ds_read_b128 v[206:209], v201 offset:7168
	s_add_u32 s34, s34, 0x80080
	s_addc_u32 s35, s35, 0
	s_mov_b32 m0, s96
	s_nop 0
	global_load_lds_dwordx4 v192, s[34:35]
	s_nop 0
	s_mov_b32 m0, s97
	s_nop 0
	global_load_lds_dwordx4 v194, s[34:35]
	s_waitcnt vmcnt(8)
	s_waitcnt lgkmcnt(0)
	s_barrier
	s_setprio 1
	v_mfma_f32_16x16x32_bf16 v[126:129], v[132:135], v[164:167], v[126:129]
	v_mfma_f32_16x16x32_bf16 v[122:125], v[140:143], v[164:167], v[122:125]
	v_mfma_f32_16x16x32_bf16 v[118:121], v[132:135], v[172:175], v[118:121]
	v_mfma_f32_16x16x32_bf16 v[114:117], v[140:143], v[172:175], v[114:117]
	v_mfma_f32_16x16x32_bf16 v[94:97], v[132:135], v[180:183], v[94:97]
	v_mfma_f32_16x16x32_bf16 v[90:93], v[140:143], v[180:183], v[90:93]
	v_mfma_f32_16x16x32_bf16 v[78:81], v[132:135], v[202:205], v[78:81]
	v_mfma_f32_16x16x32_bf16 v[74:77], v[140:143], v[202:205], v[74:77]
	v_mfma_f32_16x16x32_bf16 v[126:129], v[136:139], v[168:171], v[126:129]
	v_mfma_f32_16x16x32_bf16 v[122:125], v[144:147], v[168:171], v[122:125]
	v_mfma_f32_16x16x32_bf16 v[118:121], v[136:139], v[176:179], v[118:121]
	v_mfma_f32_16x16x32_bf16 v[114:117], v[144:147], v[176:179], v[114:117]
	v_mfma_f32_16x16x32_bf16 v[94:97], v[136:139], v[184:187], v[94:97]
	v_mfma_f32_16x16x32_bf16 v[90:93], v[144:147], v[184:187], v[90:93]
	v_mfma_f32_16x16x32_bf16 v[78:81], v[136:139], v[206:209], v[78:81]
	v_mfma_f32_16x16x32_bf16 v[74:77], v[144:147], v[206:209], v[74:77]
	v_mfma_f32_16x16x32_bf16 v[110:113], v[148:151], v[164:167], v[110:113]
	v_mfma_f32_16x16x32_bf16 v[106:109], v[156:159], v[164:167], v[106:109]
	v_mfma_f32_16x16x32_bf16 v[102:105], v[148:151], v[172:175], v[102:105]
	v_mfma_f32_16x16x32_bf16 v[98:101], v[156:159], v[172:175], v[98:101]
	v_mfma_f32_16x16x32_bf16 v[86:89], v[148:151], v[180:183], v[86:89]
	v_mfma_f32_16x16x32_bf16 v[82:85], v[156:159], v[180:183], v[82:85]
	v_mfma_f32_16x16x32_bf16 v[70:73], v[148:151], v[202:205], v[70:73]
	v_mfma_f32_16x16x32_bf16 v[66:69], v[156:159], v[202:205], v[66:69]
	v_mfma_f32_16x16x32_bf16 v[110:113], v[152:155], v[168:171], v[110:113]
	v_mfma_f32_16x16x32_bf16 v[106:109], v[160:163], v[168:171], v[106:109]
	v_mfma_f32_16x16x32_bf16 v[102:105], v[152:155], v[176:179], v[102:105]
	v_mfma_f32_16x16x32_bf16 v[98:101], v[160:163], v[176:179], v[98:101]
	v_mfma_f32_16x16x32_bf16 v[86:89], v[152:155], v[184:187], v[86:89]
	v_mfma_f32_16x16x32_bf16 v[82:85], v[160:163], v[184:187], v[82:85]
	v_mfma_f32_16x16x32_bf16 v[70:73], v[152:155], v[206:209], v[70:73]
	v_mfma_f32_16x16x32_bf16 v[66:69], v[160:163], v[206:209], v[66:69]
	s_setprio 0
	s_barrier
	ds_read_b128 v[164:167], v201 offset:16384
	ds_read_b128 v[168:171], v201 offset:17408
	ds_read_b128 v[172:175], v201 offset:18432
	ds_read_b128 v[176:179], v201 offset:19456
	ds_read_b128 v[180:183], v201 offset:20480
	ds_read_b128 v[184:187], v201 offset:21504
	ds_read_b128 v[202:205], v201 offset:22528
	ds_read_b128 v[206:209], v201 offset:23552
	s_mov_b32 m0, s29
	s_nop 0
	global_load_lds_dwordx4 v193, s[40:41]
	s_nop 0
	s_mov_b32 m0, s31
	s_nop 0
	global_load_lds_dwordx4 v195, s[40:41]
	s_add_u32 s34, s40, 0x80000
	s_addc_u32 s35, s41, 0
	s_mov_b32 m0, s54
	s_nop 0
	global_load_lds_dwordx4 v193, s[34:35]
	s_nop 0
	s_mov_b32 m0, s55
	s_nop 0
	global_load_lds_dwordx4 v195, s[34:35]
	s_mov_b32 m0, s10
	s_nop 0
	global_load_lds_dwordx4 v192, s[48:49]
	s_nop 0
	s_mov_b32 m0, s56
	s_nop 0
	global_load_lds_dwordx4 v194, s[48:49]
	s_waitcnt vmcnt(8)
	s_waitcnt lgkmcnt(0)
	s_barrier
	s_setprio 1
	v_mfma_f32_16x16x32_bf16 v[62:65], v[132:135], v[164:167], v[62:65]
	v_mfma_f32_16x16x32_bf16 v[58:61], v[140:143], v[164:167], v[58:61]
	v_mfma_f32_16x16x32_bf16 v[46:49], v[132:135], v[172:175], v[46:49]
	v_mfma_f32_16x16x32_bf16 v[42:45], v[140:143], v[172:175], v[42:45]
	v_mfma_f32_16x16x32_bf16 v[30:33], v[132:135], v[180:183], v[30:33]
	v_mfma_f32_16x16x32_bf16 v[26:29], v[140:143], v[180:183], v[26:29]
	v_mfma_f32_16x16x32_bf16 v[14:17], v[132:135], v[202:205], v[14:17]
	v_mfma_f32_16x16x32_bf16 v[10:13], v[140:143], v[202:205], v[10:13]
	v_mfma_f32_16x16x32_bf16 v[62:65], v[136:139], v[168:171], v[62:65]
	v_mfma_f32_16x16x32_bf16 v[58:61], v[144:147], v[168:171], v[58:61]
	v_mfma_f32_16x16x32_bf16 v[46:49], v[136:139], v[176:179], v[46:49]
	v_mfma_f32_16x16x32_bf16 v[42:45], v[144:147], v[176:179], v[42:45]
	v_mfma_f32_16x16x32_bf16 v[30:33], v[136:139], v[184:187], v[30:33]
	v_mfma_f32_16x16x32_bf16 v[26:29], v[144:147], v[184:187], v[26:29]
	v_mfma_f32_16x16x32_bf16 v[14:17], v[136:139], v[206:209], v[14:17]
	v_mfma_f32_16x16x32_bf16 v[10:13], v[144:147], v[206:209], v[10:13]
	v_mfma_f32_16x16x32_bf16 v[54:57], v[148:151], v[164:167], v[54:57]
	v_mfma_f32_16x16x32_bf16 v[50:53], v[156:159], v[164:167], v[50:53]
	v_mfma_f32_16x16x32_bf16 v[38:41], v[148:151], v[172:175], v[38:41]
	v_mfma_f32_16x16x32_bf16 v[34:37], v[156:159], v[172:175], v[34:37]
	v_mfma_f32_16x16x32_bf16 v[22:25], v[148:151], v[180:183], v[22:25]
	v_mfma_f32_16x16x32_bf16 v[18:21], v[156:159], v[180:183], v[18:21]
	v_mfma_f32_16x16x32_bf16 v[6:9], v[148:151], v[202:205], v[6:9]
	v_mfma_f32_16x16x32_bf16 v[2:5], v[156:159], v[202:205], v[2:5]
	v_mfma_f32_16x16x32_bf16 v[54:57], v[152:155], v[168:171], v[54:57]
	v_mfma_f32_16x16x32_bf16 v[50:53], v[160:163], v[168:171], v[50:53]
	v_mfma_f32_16x16x32_bf16 v[38:41], v[152:155], v[176:179], v[38:41]
	v_mfma_f32_16x16x32_bf16 v[34:37], v[160:163], v[176:179], v[34:37]
	v_mfma_f32_16x16x32_bf16 v[22:25], v[152:155], v[184:187], v[22:25]
	v_mfma_f32_16x16x32_bf16 v[18:21], v[160:163], v[184:187], v[18:21]
	v_mfma_f32_16x16x32_bf16 v[6:9], v[152:155], v[206:209], v[6:9]
	v_mfma_f32_16x16x32_bf16 v[2:5], v[160:163], v[206:209], v[2:5]
	s_setprio 0
	s_barrier
; #define PG8_LDA(dst, b, h) do { _Pragma("unroll") for (int m = 0; m < 4; ++m) _Pragma("unroll") for (int k = 0; k < 2; ++k) dst[m][k] = *(const PG8_LAS bf16x8*)(lds + PG8_SA(b, h) + aoff + m * 2048 + k * 1024); } while (0)
; #define PG8_LDB(dst, b, h) do { _Pragma("unroll") for (int n = 0; n < 2; ++n) _Pragma("unroll") for (int k = 0; k < 2; ++k) dst[n][k] = *(const PG8_LAS bf16x8*)(lds + PG8_SB(b, h) + boff + n * 2048 + k * 1024); } while (0)
; #define PG8_MMA(ai, bj, At, Bt) do { __builtin_amdgcn_s_setprio(1); _Pragma("unroll") for (int m = 0; m < 4; ++m) _Pragma("unroll") for (int n = 0; n < 2; ++n) _Pragma("unroll") for (int k = 0; k < 2; ++k) \
;         acc[ai][bj][m][n] = __builtin_amdgcn_mfma_f32_16x16x32_bf16(Bt[n][k], At[m][k], acc[ai][bj][m][n], 0, 0, 0); __builtin_amdgcn_s_setprio(0); } while (0)
; #define PG8_WAIT_V(n) asm volatile("s_waitcnt vmcnt(" #n ")" ::: "memory")
; #define PG8_WAIT_L(n) asm volatile("s_waitcnt lgkmcnt(" #n ")" ::: "memory")
; #define PG8_BAR __builtin_amdgcn_s_barrier()
; #define PG8_SCHED __builtin_amdgcn_sched_barrier(0)
; template <class Epi, class Sched, bool ALIGN_EPI = false, bool SP2 = false>
; __device__ __forceinline__ void gemm_phase(PG8_LAS unsigned char* lds, const Gemm g, const Sched& S, const Epi& E, const int tid) {
;     ...
;             PG8_LDB(B0, 1, 0); PG8_LDB(B1, 1, 1); PG8_SCHED; PG8_LDA(At, 1, 0); PG8_STAGE(PG8_SA(0, 1), a2 + hstepA, voffA);
;             PG8_WAIT_V(8); PG8_WAIT_L(0); PG8_BAR; PG8_MMA(0, 0, At, B0); PG8_MMA(0, 1, At, B1); PG8_BAR; PG8_SCHED;
;             PG8_LDA(At, 1, 1); PG8_STAGE(PG8_SB(1, 0), b3, voffB); PG8_STAGE(PG8_SB(1, 1), b3 + hstepB, voffB); PG8_STAGE(PG8_SA(1, 0), a3, voffA);
;             PG8_WAIT_V(8); PG8_WAIT_L(0); PG8_BAR; PG8_MMA(1, 0, At, B0); PG8_MMA(1, 1, At, B1); PG8_BAR; PG8_SCHED;
	v_add_u32_e32 v144, 0x18000, v200
	v_add_u32_e32 v160, 0x1c000, v200
	ds_read_b128 v[132:135], v144
	ds_read_b128 v[136:139], v144 offset:1024
	ds_read_b128 v[140:143], v144 offset:2048
	ds_read_b128 v[144:147], v144 offset:3072
	ds_read_b128 v[148:151], v160
	ds_read_b128 v[152:155], v160 offset:1024
	ds_read_b128 v[156:159], v160 offset:2048
	ds_read_b128 v[160:163], v160 offset:3072
	ds_read_b128 v[164:167], v201 offset:32768
	ds_read_b128 v[168:171], v201 offset:33792
	ds_read_b128 v[172:175], v201 offset:34816
	ds_read_b128 v[176:179], v201 offset:35840
	ds_read_b128 v[180:183], v201 offset:36864
	ds_read_b128 v[184:187], v201 offset:37888
	ds_read_b128 v[202:205], v201 offset:38912
	ds_read_b128 v[206:209], v201 offset:39936
	s_add_u32 s34, s48, 0x80000
	s_addc_u32 s35, s49, 0
	s_mov_b32 m0, s57
	s_nop 0
	global_load_lds_dwordx4 v192, s[34:35]
	s_nop 0
	s_mov_b32 m0, s64
	s_nop 0
	global_load_lds_dwordx4 v194, s[34:35]
	s_waitcnt vmcnt(8)
	s_waitcnt lgkmcnt(0)
	s_barrier
	s_setprio 1
	v_mfma_f32_16x16x32_bf16 v[126:129], v[132:135], v[164:167], v[126:129]
	v_mfma_f32_16x16x32_bf16 v[122:125], v[140:143], v[164:167], v[122:125]
	v_mfma_f32_16x16x32_bf16 v[118:121], v[132:135], v[172:175], v[118:121]
	v_mfma_f32_16x16x32_bf16 v[114:117], v[140:143], v[172:175], v[114:117]
	v_mfma_f32_16x16x32_bf16 v[94:97], v[132:135], v[180:183], v[94:97]
	v_mfma_f32_16x16x32_bf16 v[90:93], v[140:143], v[180:183], v[90:93]
	v_mfma_f32_16x16x32_bf16 v[78:81], v[132:135], v[202:205], v[78:81]
	v_mfma_f32_16x16x32_bf16 v[74:77], v[140:143], v[202:205], v[74:77]
	v_mfma_f32_16x16x32_bf16 v[126:129], v[136:139], v[168:171], v[126:129]
	v_mfma_f32_16x16x32_bf16 v[122:125], v[144:147], v[168:171], v[122:125]
	v_mfma_f32_16x16x32_bf16 v[118:121], v[136:139], v[176:179], v[118:121]
	v_mfma_f32_16x16x32_bf16 v[114:117], v[144:147], v[176:179], v[114:117]
	v_mfma_f32_16x16x32_bf16 v[94:97], v[136:139], v[184:187], v[94:97]
	v_mfma_f32_16x16x32_bf16 v[90:93], v[144:147], v[184:187], v[90:93]
	v_mfma_f32_16x16x32_bf16 v[78:81], v[136:139], v[206:209], v[78:81]
	v_mfma_f32_16x16x32_bf16 v[74:77], v[144:147], v[206:209], v[74:77]
	v_mfma_f32_16x16x32_bf16 v[110:113], v[148:151], v[164:167], v[110:113]
	v_mfma_f32_16x16x32_bf16 v[106:109], v[156:159], v[164:167], v[106:109]
	v_mfma_f32_16x16x32_bf16 v[102:105], v[148:151], v[172:175], v[102:105]
	v_mfma_f32_16x16x32_bf16 v[98:101], v[156:159], v[172:175], v[98:101]
	v_mfma_f32_16x16x32_bf16 v[86:89], v[148:151], v[180:183], v[86:89]
	v_mfma_f32_16x16x32_bf16 v[82:85], v[156:159], v[180:183], v[82:85]
	v_mfma_f32_16x16x32_bf16 v[70:73], v[148:151], v[202:205], v[70:73]
	v_mfma_f32_16x16x32_bf16 v[66:69], v[156:159], v[202:205], v[66:69]
	v_mfma_f32_16x16x32_bf16 v[110:113], v[152:155], v[168:171], v[110:113]
	v_mfma_f32_16x16x32_bf16 v[106:109], v[160:163], v[168:171], v[106:109]
	v_mfma_f32_16x16x32_bf16 v[102:105], v[152:155], v[176:179], v[102:105]
	v_mfma_f32_16x16x32_bf16 v[98:101], v[160:163], v[176:179], v[98:101]
	v_mfma_f32_16x16x32_bf16 v[86:89], v[152:155], v[184:187], v[86:89]
	v_mfma_f32_16x16x32_bf16 v[82:85], v[160:163], v[184:187], v[82:85]
	v_mfma_f32_16x16x32_bf16 v[70:73], v[152:155], v[206:209], v[70:73]
	v_mfma_f32_16x16x32_bf16 v[66:69], v[160:163], v[206:209], v[66:69]
	s_setprio 0
	s_barrier
	ds_read_b128 v[164:167], v201 offset:49152
	ds_read_b128 v[168:171], v201 offset:50176
	ds_read_b128 v[172:175], v201 offset:51200
	ds_read_b128 v[176:179], v201 offset:52224
	ds_read_b128 v[180:183], v201 offset:53248
	ds_read_b128 v[184:187], v201 offset:54272
	ds_read_b128 v[202:205], v201 offset:55296
	ds_read_b128 v[206:209], v201 offset:56320
	s_mov_b32 m0, s87
	s_nop 0
	global_load_lds_dwordx4 v193, s[46:47]
	s_nop 0
	s_mov_b32 m0, s89
	s_nop 0
	global_load_lds_dwordx4 v195, s[46:47]
	s_add_u32 s34, s40, 0x80080
	s_addc_u32 s35, s41, 0
	s_mov_b32 m0, s83
	s_nop 0
	global_load_lds_dwordx4 v193, s[34:35]
	s_nop 0
	s_mov_b32 m0, s95
	s_nop 0
	global_load_lds_dwordx4 v195, s[34:35]
	s_mov_b32 m0, s90
	s_nop 0
	global_load_lds_dwordx4 v192, s[44:45]
	s_nop 0
	s_mov_b32 m0, s91
	s_nop 0
	global_load_lds_dwordx4 v194, s[44:45]
	s_waitcnt vmcnt(8)
	s_waitcnt lgkmcnt(0)
	s_barrier
	s_setprio 1
	v_mfma_f32_16x16x32_bf16 v[62:65], v[132:135], v[164:167], v[62:65]
	v_mfma_f32_16x16x32_bf16 v[58:61], v[140:143], v[164:167], v[58:61]
	v_mfma_f32_16x16x32_bf16 v[46:49], v[132:135], v[172:175], v[46:49]
	v_mfma_f32_16x16x32_bf16 v[42:45], v[140:143], v[172:175], v[42:45]
	v_mfma_f32_16x16x32_bf16 v[30:33], v[132:135], v[180:183], v[30:33]
	v_mfma_f32_16x16x32_bf16 v[26:29], v[140:143], v[180:183], v[26:29]
	v_mfma_f32_16x16x32_bf16 v[14:17], v[132:135], v[202:205], v[14:17]
	v_mfma_f32_16x16x32_bf16 v[10:13], v[140:143], v[202:205], v[10:13]
	v_mfma_f32_16x16x32_bf16 v[62:65], v[136:139], v[168:171], v[62:65]
	v_mfma_f32_16x16x32_bf16 v[58:61], v[144:147], v[168:171], v[58:61]
	v_mfma_f32_16x16x32_bf16 v[46:49], v[136:139], v[176:179], v[46:49]
	v_mfma_f32_16x16x32_bf16 v[42:45], v[144:147], v[176:179], v[42:45]
	v_mfma_f32_16x16x32_bf16 v[30:33], v[136:139], v[184:187], v[30:33]
	v_mfma_f32_16x16x32_bf16 v[26:29], v[144:147], v[184:187], v[26:29]
	v_mfma_f32_16x16x32_bf16 v[14:17], v[136:139], v[206:209], v[14:17]
	v_mfma_f32_16x16x32_bf16 v[10:13], v[144:147], v[206:209], v[10:13]
	v_mfma_f32_16x16x32_bf16 v[54:57], v[148:151], v[164:167], v[54:57]
	v_mfma_f32_16x16x32_bf16 v[50:53], v[156:159], v[164:167], v[50:53]
	v_mfma_f32_16x16x32_bf16 v[38:41], v[148:151], v[172:175], v[38:41]
	v_mfma_f32_16x16x32_bf16 v[34:37], v[156:159], v[172:175], v[34:37]
	v_mfma_f32_16x16x32_bf16 v[22:25], v[148:151], v[180:183], v[22:25]
	v_mfma_f32_16x16x32_bf16 v[18:21], v[156:159], v[180:183], v[18:21]
	v_mfma_f32_16x16x32_bf16 v[6:9], v[148:151], v[202:205], v[6:9]
	v_mfma_f32_16x16x32_bf16 v[2:5], v[156:159], v[202:205], v[2:5]
	v_mfma_f32_16x16x32_bf16 v[54:57], v[152:155], v[168:171], v[54:57]
	v_mfma_f32_16x16x32_bf16 v[50:53], v[160:163], v[168:171], v[50:53]
	v_mfma_f32_16x16x32_bf16 v[38:41], v[152:155], v[176:179], v[38:41]
	v_mfma_f32_16x16x32_bf16 v[34:37], v[160:163], v[176:179], v[34:37]
	v_mfma_f32_16x16x32_bf16 v[22:25], v[152:155], v[184:187], v[22:25]
	v_mfma_f32_16x16x32_bf16 v[18:21], v[160:163], v[184:187], v[18:21]
	v_mfma_f32_16x16x32_bf16 v[6:9], v[152:155], v[206:209], v[6:9]
	v_mfma_f32_16x16x32_bf16 v[2:5], v[160:163], v[206:209], v[2:5]
	s_setprio 0
	s_barrier
	s_add_i32 s11, s11, 2
	s_add_u32 s59, s59, 0x100
	s_addc_u32 s67, s67, 0
	s_cmp_gt_u32 s11, 29
	s_mov_b64 s[34:35], s[42:43]
	s_cbranch_scc1 .LBB0_902

; #define PG8_LDA(dst, b, h) do { _Pragma("unroll") for (int m = 0; m < 4; ++m) _Pragma("unroll") for (int k = 0; k < 2; ++k) dst[m][k] = *(const PG8_LAS bf16x8*)(lds + PG8_SA(b, h) + aoff + m * 2048 + k * 1024); } while (0)
; #define PG8_LDB(dst, b, h) do { _Pragma("unroll") for (int n = 0; n < 2; ++n) _Pragma("unroll") for (int k = 0; k < 2; ++k) dst[n][k] = *(const PG8_LAS bf16x8*)(lds + PG8_SB(b, h) + boff + n * 2048 + k * 1024); } while (0)
; #define PG8_MMA(ai, bj, At, Bt) do { __builtin_amdgcn_s_setprio(1); _Pragma("unroll") for (int m = 0; m < 4; ++m) _Pragma("unroll") for (int n = 0; n < 2; ++n) _Pragma("unroll") for (int k = 0; k < 2; ++k) \
;         acc[ai][bj][m][n] = __builtin_amdgcn_mfma_f32_16x16x32_bf16(Bt[n][k], At[m][k], acc[ai][bj][m][n], 0, 0, 0); __builtin_amdgcn_s_setprio(0); } while (0)
; #define PG8_WAIT_V(n) asm volatile("s_waitcnt vmcnt(" #n ")" ::: "memory")
; #define PG8_WAIT_L(n) asm volatile("s_waitcnt lgkmcnt(" #n ")" ::: "memory")
; #define PG8_BAR __builtin_amdgcn_s_barrier()
; #define PG8_SCHED __builtin_amdgcn_sched_barrier(0)
; template <class Epi, class Sched, bool ALIGN_EPI = false, bool SP2 = false>
; __device__ __forceinline__ void gemm_phase(PG8_LAS unsigned char* lds, const Gemm g, const Sched& S, const Epi& E, const int tid) {
;     ...
;             const char* a1 = cA + (size_t)(t + 1) * kstepA;
;             const char* a2 = last ? nA : cA + (size_t)(t + 2) * kstepA; const char* b2 = last ? nB : cB + (size_t)(t + 2) * kstepB;
;             const char* a3 = a2 + kstepA; const char* b3 = b2 + kstepB;
;             if (last && has_next) S.a_ready(nxt);
;             if constexpr (SP2) {
;             PG8_LDB(B0, 0, 0); PG8_LDB(B1, 0, 1); PG8_SCHED; PG8_LDA(At, 0, 0); PG8_STAGE(PG8_SA(1, 1), a1 + hstepA, voffA);
;             PG8_WAIT_V(8); PG8_WAIT_L(0); PG8_BAR; PG8_MMA(0, 0, At, B0); PG8_MMA(0, 1, At, B1); PG8_BAR; PG8_SCHED;
;             PG8_LDA(At, 0, 1); PG8_STAGE(PG8_SB(0, 0), b2, voffB); PG8_STAGE(PG8_SB(0, 1), b2 + hstepB, voffB); PG8_STAGE(PG8_SA(0, 0), a2, voffA);
;             PG8_WAIT_V(8); PG8_WAIT_L(0); PG8_BAR; PG8_MMA(1, 0, At, B0); PG8_MMA(1, 1, At, B1); PG8_BAR; PG8_SCHED;
.LBB0_986:
	v_add_u32_e32 v142, 0x10000, v181
	v_add_u32_e32 v158, 0x14000, v181
	ds_read_b128 v[130:133], v142
	ds_read_b128 v[134:137], v142 offset:1024
	ds_read_b128 v[138:141], v142 offset:2048
	ds_read_b128 v[142:145], v142 offset:3072
	ds_read_b128 v[146:149], v158
	ds_read_b128 v[150:153], v158 offset:1024
	ds_read_b128 v[154:157], v158 offset:2048
	ds_read_b128 v[158:161], v158 offset:3072
	s_cmp_eq_u32 s83, 28
	s_cselect_b32 s38, s21, s67
	s_cselect_b32 s39, s11, s78
	s_cselect_b32 s34, s27, s58
	s_cselect_b32 s35, s19, s59
	s_add_u32 s30, s38, 0x80
	s_addc_u32 s31, s39, 0
	ds_read_b128 v[162:165], v182
	ds_read_b128 v[166:169], v182 offset:1024
	ds_read_b128 v[170:173], v182 offset:2048
	ds_read_b128 v[184:187], v182 offset:3072
	ds_read_b128 v[188:191], v182 offset:4096
	ds_read_b128 v[192:195], v182 offset:5120
	ds_read_b128 v[196:199], v182 offset:6144
	ds_read_b128 v[200:203], v182 offset:7168
	s_mov_b32 m0, s61
	s_nop 0
	global_load_lds_dwordx4 v0, s[28:29]
	s_nop 0
	s_mov_b32 m0, s65
	s_nop 0
	global_load_lds_dwordx4 v177, s[28:29]
	s_waitcnt vmcnt(8)
	s_waitcnt lgkmcnt(0)
	s_barrier
	s_setprio 1
	v_mfma_f32_16x16x32_bf16 v[126:129], v[130:133], v[162:165], v[126:129]
	v_mfma_f32_16x16x32_bf16 v[122:125], v[138:141], v[162:165], v[122:125]
	v_mfma_f32_16x16x32_bf16 v[110:113], v[130:133], v[170:173], v[110:113]
	v_mfma_f32_16x16x32_bf16 v[106:109], v[138:141], v[170:173], v[106:109]
	v_mfma_f32_16x16x32_bf16 v[94:97], v[130:133], v[188:191], v[94:97]
	v_mfma_f32_16x16x32_bf16 v[90:93], v[138:141], v[188:191], v[90:93]
	v_mfma_f32_16x16x32_bf16 v[78:81], v[130:133], v[196:199], v[78:81]
	v_mfma_f32_16x16x32_bf16 v[74:77], v[138:141], v[196:199], v[74:77]
	v_mfma_f32_16x16x32_bf16 v[126:129], v[134:137], v[166:169], v[126:129]
	v_mfma_f32_16x16x32_bf16 v[122:125], v[142:145], v[166:169], v[122:125]
	v_mfma_f32_16x16x32_bf16 v[110:113], v[134:137], v[184:187], v[110:113]
	v_mfma_f32_16x16x32_bf16 v[106:109], v[142:145], v[184:187], v[106:109]
	v_mfma_f32_16x16x32_bf16 v[94:97], v[134:137], v[192:195], v[94:97]
	v_mfma_f32_16x16x32_bf16 v[90:93], v[142:145], v[192:195], v[90:93]
	v_mfma_f32_16x16x32_bf16 v[78:81], v[134:137], v[200:203], v[78:81]
	v_mfma_f32_16x16x32_bf16 v[74:77], v[142:145], v[200:203], v[74:77]
	v_mfma_f32_16x16x32_bf16 v[118:121], v[146:149], v[162:165], v[118:121]
	v_mfma_f32_16x16x32_bf16 v[114:117], v[154:157], v[162:165], v[114:117]
	v_mfma_f32_16x16x32_bf16 v[102:105], v[146:149], v[170:173], v[102:105]
	v_mfma_f32_16x16x32_bf16 v[98:101], v[154:157], v[170:173], v[98:101]
	v_mfma_f32_16x16x32_bf16 v[86:89], v[146:149], v[188:191], v[86:89]
	v_mfma_f32_16x16x32_bf16 v[82:85], v[154:157], v[188:191], v[82:85]
	v_mfma_f32_16x16x32_bf16 v[70:73], v[146:149], v[196:199], v[70:73]
	v_mfma_f32_16x16x32_bf16 v[66:69], v[154:157], v[196:199], v[66:69]
	v_mfma_f32_16x16x32_bf16 v[118:121], v[150:153], v[166:169], v[118:121]
	v_mfma_f32_16x16x32_bf16 v[114:117], v[158:161], v[166:169], v[114:117]
	v_mfma_f32_16x16x32_bf16 v[102:105], v[150:153], v[184:187], v[102:105]
	v_mfma_f32_16x16x32_bf16 v[98:101], v[158:161], v[184:187], v[98:101]
	v_mfma_f32_16x16x32_bf16 v[86:89], v[150:153], v[192:195], v[86:89]
	v_mfma_f32_16x16x32_bf16 v[82:85], v[158:161], v[192:195], v[82:85]
	v_mfma_f32_16x16x32_bf16 v[70:73], v[150:153], v[200:203], v[70:73]
	v_mfma_f32_16x16x32_bf16 v[66:69], v[158:161], v[200:203], v[66:69]
	s_setprio 0
	s_barrier
	ds_read_b128 v[162:165], v182 offset:16384
	ds_read_b128 v[166:169], v182 offset:17408
	ds_read_b128 v[170:173], v182 offset:18432
	ds_read_b128 v[184:187], v182 offset:19456
	ds_read_b128 v[188:191], v182 offset:20480
	ds_read_b128 v[192:195], v182 offset:21504
	ds_read_b128 v[196:199], v182 offset:22528
	ds_read_b128 v[200:203], v182 offset:23552
	s_mov_b32 m0, s7
	s_nop 0
	global_load_lds_dwordx4 v176, s[34:35]
	s_add_u32 s90, s34, 0x80000
	s_mov_b32 m0, s43
	s_nop 0
	global_load_lds_dwordx4 v178, s[34:35]
	s_addc_u32 s91, s35, 0
	s_mov_b32 m0, s44
	s_nop 0
	global_load_lds_dwordx4 v176, s[90:91]
	s_nop 0
	s_mov_b32 m0, s45
	s_nop 0
	global_load_lds_dwordx4 v178, s[90:91]
	s_nop 0
	s_mov_b32 m0, s10
	s_nop 0
	global_load_lds_dwordx4 v0, s[38:39]
	s_nop 0
	s_mov_b32 m0, s46
	s_nop 0
	global_load_lds_dwordx4 v177, s[38:39]
	s_waitcnt vmcnt(8)
	s_waitcnt lgkmcnt(0)
	s_barrier
	s_setprio 1
	v_mfma_f32_16x16x32_bf16 v[62:65], v[130:133], v[162:165], v[62:65]
	v_mfma_f32_16x16x32_bf16 v[58:61], v[138:141], v[162:165], v[58:61]
	v_mfma_f32_16x16x32_bf16 v[46:49], v[130:133], v[170:173], v[46:49]
	v_mfma_f32_16x16x32_bf16 v[42:45], v[138:141], v[170:173], v[42:45]
	v_mfma_f32_16x16x32_bf16 v[30:33], v[130:133], v[188:191], v[30:33]
	v_mfma_f32_16x16x32_bf16 v[26:29], v[138:141], v[188:191], v[26:29]
	v_mfma_f32_16x16x32_bf16 v[14:17], v[130:133], v[196:199], v[14:17]
	v_mfma_f32_16x16x32_bf16 v[10:13], v[138:141], v[196:199], v[10:13]
	v_mfma_f32_16x16x32_bf16 v[62:65], v[134:137], v[166:169], v[62:65]
	v_mfma_f32_16x16x32_bf16 v[58:61], v[142:145], v[166:169], v[58:61]
	v_mfma_f32_16x16x32_bf16 v[46:49], v[134:137], v[184:187], v[46:49]
	v_mfma_f32_16x16x32_bf16 v[42:45], v[142:145], v[184:187], v[42:45]
	v_mfma_f32_16x16x32_bf16 v[30:33], v[134:137], v[192:195], v[30:33]
	v_mfma_f32_16x16x32_bf16 v[26:29], v[142:145], v[192:195], v[26:29]
	v_mfma_f32_16x16x32_bf16 v[14:17], v[134:137], v[200:203], v[14:17]
	v_mfma_f32_16x16x32_bf16 v[10:13], v[142:145], v[200:203], v[10:13]
	v_mfma_f32_16x16x32_bf16 v[54:57], v[146:149], v[162:165], v[54:57]
	v_mfma_f32_16x16x32_bf16 v[50:53], v[154:157], v[162:165], v[50:53]
	v_mfma_f32_16x16x32_bf16 v[38:41], v[146:149], v[170:173], v[38:41]
	v_mfma_f32_16x16x32_bf16 v[34:37], v[154:157], v[170:173], v[34:37]
	v_mfma_f32_16x16x32_bf16 v[22:25], v[146:149], v[188:191], v[22:25]
	v_mfma_f32_16x16x32_bf16 v[18:21], v[154:157], v[188:191], v[18:21]
	v_mfma_f32_16x16x32_bf16 v[6:9], v[146:149], v[196:199], v[6:9]
	v_mfma_f32_16x16x32_bf16 v[2:5], v[154:157], v[196:199], v[2:5]
	v_mfma_f32_16x16x32_bf16 v[54:57], v[150:153], v[166:169], v[54:57]
	v_mfma_f32_16x16x32_bf16 v[50:53], v[158:161], v[166:169], v[50:53]
	v_mfma_f32_16x16x32_bf16 v[38:41], v[150:153], v[184:187], v[38:41]
	v_mfma_f32_16x16x32_bf16 v[34:37], v[158:161], v[184:187], v[34:37]
	v_mfma_f32_16x16x32_bf16 v[22:25], v[150:153], v[192:195], v[22:25]
	v_mfma_f32_16x16x32_bf16 v[18:21], v[158:161], v[192:195], v[18:21]
	v_mfma_f32_16x16x32_bf16 v[6:9], v[150:153], v[200:203], v[6:9]
	v_mfma_f32_16x16x32_bf16 v[2:5], v[158:161], v[200:203], v[2:5]
	s_setprio 0
	s_barrier
; #define PG8_LDA(dst, b, h) do { _Pragma("unroll") for (int m = 0; m < 4; ++m) _Pragma("unroll") for (int k = 0; k < 2; ++k) dst[m][k] = *(const PG8_LAS bf16x8*)(lds + PG8_SA(b, h) + aoff + m * 2048 + k * 1024); } while (0)
; #define PG8_LDB(dst, b, h) do { _Pragma("unroll") for (int n = 0; n < 2; ++n) _Pragma("unroll") for (int k = 0; k < 2; ++k) dst[n][k] = *(const PG8_LAS bf16x8*)(lds + PG8_SB(b, h) + boff + n * 2048 + k * 1024); } while (0)
; #define PG8_MMA(ai, bj, At, Bt) do { __builtin_amdgcn_s_setprio(1); _Pragma("unroll") for (int m = 0; m < 4; ++m) _Pragma("unroll") for (int n = 0; n < 2; ++n) _Pragma("unroll") for (int k = 0; k < 2; ++k) \
;         acc[ai][bj][m][n] = __builtin_amdgcn_mfma_f32_16x16x32_bf16(Bt[n][k], At[m][k], acc[ai][bj][m][n], 0, 0, 0); __builtin_amdgcn_s_setprio(0); } while (0)
; #define PG8_WAIT_V(n) asm volatile("s_waitcnt vmcnt(" #n ")" ::: "memory")
; #define PG8_WAIT_L(n) asm volatile("s_waitcnt lgkmcnt(" #n ")" ::: "memory")
; #define PG8_BAR __builtin_amdgcn_s_barrier()
; #define PG8_SCHED __builtin_amdgcn_sched_barrier(0)
; template <class Epi, class Sched, bool ALIGN_EPI = false, bool SP2 = false>
; __device__ __forceinline__ void gemm_phase(PG8_LAS unsigned char* lds, const Gemm g, const Sched& S, const Epi& E, const int tid) {
;     ...
;             PG8_LDB(B0, 1, 0); PG8_LDB(B1, 1, 1); PG8_SCHED; PG8_LDA(At, 1, 0); PG8_STAGE(PG8_SA(0, 1), a2 + hstepA, voffA);
;             PG8_WAIT_V(8); PG8_WAIT_L(0); PG8_BAR; PG8_MMA(0, 0, At, B0); PG8_MMA(0, 1, At, B1); PG8_BAR; PG8_SCHED;
;             PG8_LDA(At, 1, 1); PG8_STAGE(PG8_SB(1, 0), b3, voffB); PG8_STAGE(PG8_SB(1, 1), b3 + hstepB, voffB); PG8_STAGE(PG8_SA(1, 0), a3, voffA);
;             PG8_WAIT_V(8); PG8_WAIT_L(0); PG8_BAR; PG8_MMA(1, 0, At, B0); PG8_MMA(1, 1, At, B1); PG8_BAR; PG8_SCHED;
	v_add_u32_e32 v142, 0x18000, v181
	v_add_u32_e32 v158, 0x1c000, v181
	ds_read_b128 v[130:133], v142
	ds_read_b128 v[134:137], v142 offset:1024
	ds_read_b128 v[138:141], v142 offset:2048
	ds_read_b128 v[142:145], v142 offset:3072
	ds_read_b128 v[146:149], v158
	ds_read_b128 v[150:153], v158 offset:1024
	ds_read_b128 v[154:157], v158 offset:2048
	ds_read_b128 v[158:161], v158 offset:3072
	ds_read_b128 v[162:165], v182 offset:32768
	ds_read_b128 v[166:169], v182 offset:33792
	ds_read_b128 v[170:173], v182 offset:34816
	ds_read_b128 v[184:187], v182 offset:35840
	ds_read_b128 v[188:191], v182 offset:36864
	ds_read_b128 v[192:195], v182 offset:37888
	ds_read_b128 v[196:199], v182 offset:38912
	ds_read_b128 v[200:203], v182 offset:39936
	s_add_u32 s38, s38, 0x80000
	s_addc_u32 s39, s39, 0
	s_mov_b32 m0, s47
	s_nop 0
	global_load_lds_dwordx4 v0, s[38:39]
	s_nop 0
	s_mov_b32 m0, s48
	s_nop 0
	global_load_lds_dwordx4 v177, s[38:39]
	s_waitcnt vmcnt(8)
	s_waitcnt lgkmcnt(0)
	s_barrier
	s_setprio 1
	v_mfma_f32_16x16x32_bf16 v[126:129], v[130:133], v[162:165], v[126:129]
	v_mfma_f32_16x16x32_bf16 v[122:125], v[138:141], v[162:165], v[122:125]
	v_mfma_f32_16x16x32_bf16 v[110:113], v[130:133], v[170:173], v[110:113]
	v_mfma_f32_16x16x32_bf16 v[106:109], v[138:141], v[170:173], v[106:109]
	v_mfma_f32_16x16x32_bf16 v[94:97], v[130:133], v[188:191], v[94:97]
	v_mfma_f32_16x16x32_bf16 v[90:93], v[138:141], v[188:191], v[90:93]
	v_mfma_f32_16x16x32_bf16 v[78:81], v[130:133], v[196:199], v[78:81]
	v_mfma_f32_16x16x32_bf16 v[74:77], v[138:141], v[196:199], v[74:77]
	v_mfma_f32_16x16x32_bf16 v[126:129], v[134:137], v[166:169], v[126:129]
	v_mfma_f32_16x16x32_bf16 v[122:125], v[142:145], v[166:169], v[122:125]
	v_mfma_f32_16x16x32_bf16 v[110:113], v[134:137], v[184:187], v[110:113]
	v_mfma_f32_16x16x32_bf16 v[106:109], v[142:145], v[184:187], v[106:109]
	v_mfma_f32_16x16x32_bf16 v[94:97], v[134:137], v[192:195], v[94:97]
	v_mfma_f32_16x16x32_bf16 v[90:93], v[142:145], v[192:195], v[90:93]
	v_mfma_f32_16x16x32_bf16 v[78:81], v[134:137], v[200:203], v[78:81]
	v_mfma_f32_16x16x32_bf16 v[74:77], v[142:145], v[200:203], v[74:77]
	v_mfma_f32_16x16x32_bf16 v[118:121], v[146:149], v[162:165], v[118:121]
	v_mfma_f32_16x16x32_bf16 v[114:117], v[154:157], v[162:165], v[114:117]
	v_mfma_f32_16x16x32_bf16 v[102:105], v[146:149], v[170:173], v[102:105]
	v_mfma_f32_16x16x32_bf16 v[98:101], v[154:157], v[170:173], v[98:101]
	v_mfma_f32_16x16x32_bf16 v[86:89], v[146:149], v[188:191], v[86:89]
	v_mfma_f32_16x16x32_bf16 v[82:85], v[154:157], v[188:191], v[82:85]
	v_mfma_f32_16x16x32_bf16 v[70:73], v[146:149], v[196:199], v[70:73]
	v_mfma_f32_16x16x32_bf16 v[66:69], v[154:157], v[196:199], v[66:69]
	v_mfma_f32_16x16x32_bf16 v[118:121], v[150:153], v[166:169], v[118:121]
	v_mfma_f32_16x16x32_bf16 v[114:117], v[158:161], v[166:169], v[114:117]
	v_mfma_f32_16x16x32_bf16 v[102:105], v[150:153], v[184:187], v[102:105]
	v_mfma_f32_16x16x32_bf16 v[98:101], v[158:161], v[184:187], v[98:101]
	v_mfma_f32_16x16x32_bf16 v[86:89], v[150:153], v[192:195], v[86:89]
	v_mfma_f32_16x16x32_bf16 v[82:85], v[158:161], v[192:195], v[82:85]
	v_mfma_f32_16x16x32_bf16 v[70:73], v[150:153], v[200:203], v[70:73]
	v_mfma_f32_16x16x32_bf16 v[66:69], v[158:161], v[200:203], v[66:69]
	s_setprio 0
	s_barrier
	ds_read_b128 v[162:165], v182 offset:49152
	ds_read_b128 v[166:169], v182 offset:50176
	ds_read_b128 v[170:173], v182 offset:51200
	ds_read_b128 v[184:187], v182 offset:52224
	ds_read_b128 v[188:191], v182 offset:53248
	ds_read_b128 v[192:195], v182 offset:54272
	ds_read_b128 v[196:199], v182 offset:55296
	ds_read_b128 v[200:203], v182 offset:56320
	s_add_u32 s38, s34, 0x80
	s_addc_u32 s39, s35, 0
	s_mov_b32 m0, s50
	s_nop 0
	global_load_lds_dwordx4 v176, s[38:39]
	s_add_u32 s34, s34, 0x80080
	s_mov_b32 m0, s51
	s_nop 0
	global_load_lds_dwordx4 v178, s[38:39]
	s_addc_u32 s35, s35, 0
	s_mov_b32 m0, s56
	s_nop 0
	global_load_lds_dwordx4 v176, s[34:35]
	s_nop 0
	s_mov_b32 m0, s57
	s_nop 0
	global_load_lds_dwordx4 v178, s[34:35]
	s_mov_b32 m0, s54
	s_nop 0
	global_load_lds_dwordx4 v0, s[30:31]
	s_nop 0
	s_mov_b32 m0, s55
	s_nop 0
	global_load_lds_dwordx4 v177, s[30:31]
	s_waitcnt vmcnt(8)
	s_waitcnt lgkmcnt(0)
	s_barrier
	s_setprio 1
	v_mfma_f32_16x16x32_bf16 v[62:65], v[130:133], v[162:165], v[62:65]
	v_mfma_f32_16x16x32_bf16 v[58:61], v[138:141], v[162:165], v[58:61]
	v_mfma_f32_16x16x32_bf16 v[46:49], v[130:133], v[170:173], v[46:49]
	v_mfma_f32_16x16x32_bf16 v[42:45], v[138:141], v[170:173], v[42:45]
	v_mfma_f32_16x16x32_bf16 v[30:33], v[130:133], v[188:191], v[30:33]
	v_mfma_f32_16x16x32_bf16 v[26:29], v[138:141], v[188:191], v[26:29]
	v_mfma_f32_16x16x32_bf16 v[14:17], v[130:133], v[196:199], v[14:17]
	v_mfma_f32_16x16x32_bf16 v[10:13], v[138:141], v[196:199], v[10:13]
	v_mfma_f32_16x16x32_bf16 v[62:65], v[134:137], v[166:169], v[62:65]
	v_mfma_f32_16x16x32_bf16 v[58:61], v[142:145], v[166:169], v[58:61]
	v_mfma_f32_16x16x32_bf16 v[46:49], v[134:137], v[184:187], v[46:49]
	v_mfma_f32_16x16x32_bf16 v[42:45], v[142:145], v[184:187], v[42:45]
	v_mfma_f32_16x16x32_bf16 v[30:33], v[134:137], v[192:195], v[30:33]
	v_mfma_f32_16x16x32_bf16 v[26:29], v[142:145], v[192:195], v[26:29]
	v_mfma_f32_16x16x32_bf16 v[14:17], v[134:137], v[200:203], v[14:17]
	v_mfma_f32_16x16x32_bf16 v[10:13], v[142:145], v[200:203], v[10:13]
	v_mfma_f32_16x16x32_bf16 v[54:57], v[146:149], v[162:165], v[54:57]
	v_mfma_f32_16x16x32_bf16 v[50:53], v[154:157], v[162:165], v[50:53]
	v_mfma_f32_16x16x32_bf16 v[38:41], v[146:149], v[170:173], v[38:41]
	v_mfma_f32_16x16x32_bf16 v[34:37], v[154:157], v[170:173], v[34:37]
	v_mfma_f32_16x16x32_bf16 v[22:25], v[146:149], v[188:191], v[22:25]
	v_mfma_f32_16x16x32_bf16 v[18:21], v[154:157], v[188:191], v[18:21]
	v_mfma_f32_16x16x32_bf16 v[6:9], v[146:149], v[196:199], v[6:9]
	v_mfma_f32_16x16x32_bf16 v[2:5], v[154:157], v[196:199], v[2:5]
	v_mfma_f32_16x16x32_bf16 v[54:57], v[150:153], v[166:169], v[54:57]
	v_mfma_f32_16x16x32_bf16 v[50:53], v[158:161], v[166:169], v[50:53]
	v_mfma_f32_16x16x32_bf16 v[38:41], v[150:153], v[184:187], v[38:41]
	v_mfma_f32_16x16x32_bf16 v[34:37], v[158:161], v[184:187], v[34:37]
	v_mfma_f32_16x16x32_bf16 v[22:25], v[150:153], v[192:195], v[22:25]
	v_mfma_f32_16x16x32_bf16 v[18:21], v[158:161], v[192:195], v[18:21]
	v_mfma_f32_16x16x32_bf16 v[6:9], v[150:153], v[200:203], v[6:9]
	v_mfma_f32_16x16x32_bf16 v[2:5], v[158:161], v[200:203], v[2:5]
	s_setprio 0
	s_barrier
	s_add_i32 s83, s83, 2
	s_add_u32 s58, s58, 0x100
	s_addc_u32 s59, s59, 0
	s_add_u32 s67, s67, 0x100
	s_addc_u32 s78, s78, 0
	s_add_u32 s28, s28, 0x100
	s_addc_u32 s29, s29, 0
	s_cmp_gt_u32 s83, 29
	s_cbranch_scc0 .LBB0_986
	s_and_b64 vcc, exec, s[16:17]
	s_cbranch_vccz .LBB0_989
	s_barrier

; #define PG8_LDA(dst, b, h) do { _Pragma("unroll") for (int m = 0; m < 4; ++m) _Pragma("unroll") for (int k = 0; k < 2; ++k) dst[m][k] = *(const PG8_LAS bf16x8*)(lds + PG8_SA(b, h) + aoff + m * 2048 + k * 1024); } while (0)
; #define PG8_LDB(dst, b, h) do { _Pragma("unroll") for (int n = 0; n < 2; ++n) _Pragma("unroll") for (int k = 0; k < 2; ++k) dst[n][k] = *(const PG8_LAS bf16x8*)(lds + PG8_SB(b, h) + boff + n * 2048 + k * 1024); } while (0)
; #define PG8_MMA(ai, bj, At, Bt) do { __builtin_amdgcn_s_setprio(1); _Pragma("unroll") for (int m = 0; m < 4; ++m) _Pragma("unroll") for (int n = 0; n < 2; ++n) _Pragma("unroll") for (int k = 0; k < 2; ++k) \
;         acc[ai][bj][m][n] = __builtin_amdgcn_mfma_f32_16x16x32_bf16(Bt[n][k], At[m][k], acc[ai][bj][m][n], 0, 0, 0); __builtin_amdgcn_s_setprio(0); } while (0)
; #define PG8_WAIT_V(n) asm volatile("s_waitcnt vmcnt(" #n ")" ::: "memory")
; #define PG8_WAIT_L(n) asm volatile("s_waitcnt lgkmcnt(" #n ")" ::: "memory")
; #define PG8_BAR __builtin_amdgcn_s_barrier()
; #define PG8_SCHED __builtin_amdgcn_sched_barrier(0)
; template <class Epi, class Sched, bool ALIGN_EPI = false, bool SP2 = false>
; __device__ __forceinline__ void gemm_phase(PG8_LAS unsigned char* lds, const Gemm g, const Sched& S, const Epi& E, const int tid) {
;     ...
;             const char* a1 = cA + (size_t)(t + 1) * kstepA;
;             const char* a2 = last ? nA : cA + (size_t)(t + 2) * kstepA; const char* b2 = last ? nB : cB + (size_t)(t + 2) * kstepB;
;             const char* a3 = a2 + kstepA; const char* b3 = b2 + kstepB;
;             if (last && has_next) S.a_ready(nxt);
;             if constexpr (SP2) {
;             PG8_LDB(B0, 0, 0); PG8_LDB(B1, 0, 1); PG8_SCHED; PG8_LDA(At, 0, 0); PG8_STAGE(PG8_SA(1, 1), a1 + hstepA, voffA);
;             PG8_WAIT_V(8); PG8_WAIT_L(0); PG8_BAR; PG8_MMA(0, 0, At, B0); PG8_MMA(0, 1, At, B1); PG8_BAR; PG8_SCHED;
;             PG8_LDA(At, 0, 1); PG8_STAGE(PG8_SB(0, 0), b2, voffB); PG8_STAGE(PG8_SB(0, 1), b2 + hstepB, voffB); PG8_STAGE(PG8_SA(0, 0), a2, voffA);
;             PG8_WAIT_V(8); PG8_WAIT_L(0); PG8_BAR; PG8_MMA(1, 0, At, B0); PG8_MMA(1, 1, At, B1); PG8_BAR; PG8_SCHED;
.LBB0_1070:
	s_or_b64 exec, exec, s[34:35]
	v_add_u32_e32 v145, 0x10000, v154
	ds_read_b128 v[156:159], v145
	ds_read_b128 v[160:163], v145 offset:1024
	ds_read_b128 v[164:167], v145 offset:2048
	ds_read_b128 v[168:171], v145 offset:3072
	v_add_u32_e32 v145, 0x14000, v154
	s_add_u32 s34, s26, 0x100
	ds_read_b128 v[172:175], v145
	ds_read_b128 v[176:179], v145 offset:1024
	ds_read_b128 v[180:183], v145 offset:2048
	ds_read_b128 v[184:187], v145 offset:3072
	s_addc_u32 s35, s27, 0
	s_and_b64 s[30:31], s[30:31], exec
	s_cselect_b32 s42, s91, s34
	s_cselect_b32 s43, s19, s35
	s_cselect_b32 s31, s17, s67
	s_cselect_b32 s30, s95, s59
	s_add_u32 s38, s42, 0x80
	s_addc_u32 s39, s43, 0
	s_add_u32 s40, s30, 0x80
	s_addc_u32 s41, s31, 0
	ds_read_b128 v[188:191], v155
	ds_read_b128 v[192:195], v155 offset:1024
	ds_read_b128 v[196:199], v155 offset:2048
	ds_read_b128 v[200:203], v155 offset:3072
	ds_read_b128 v[204:207], v155 offset:4096
	ds_read_b128 v[208:211], v155 offset:5120
	ds_read_b128 v[212:215], v155 offset:6144
	ds_read_b128 v[216:219], v155 offset:7168
	s_add_u32 s26, s26, 0x80080
	s_addc_u32 s27, s27, 0
	s_mov_b32 m0, s69
	s_nop 0
	global_load_lds_dwordx4 v149, s[26:27]
	s_nop 0
	s_mov_b32 m0, s58
	s_nop 0
	global_load_lds_dwordx4 v151, s[26:27]
	s_waitcnt vmcnt(8)
	s_waitcnt lgkmcnt(0)
	s_barrier
	s_setprio 1
	v_mfma_f32_16x16x32_bf16 v[126:129], v[156:159], v[188:191], v[126:129]
	v_mfma_f32_16x16x32_bf16 v[122:125], v[164:167], v[188:191], v[122:125]
	v_mfma_f32_16x16x32_bf16 v[110:113], v[156:159], v[196:199], v[110:113]
	v_mfma_f32_16x16x32_bf16 v[106:109], v[164:167], v[196:199], v[106:109]
	v_mfma_f32_16x16x32_bf16 v[94:97], v[156:159], v[204:207], v[94:97]
	v_mfma_f32_16x16x32_bf16 v[90:93], v[164:167], v[204:207], v[90:93]
	v_mfma_f32_16x16x32_bf16 v[78:81], v[156:159], v[212:215], v[78:81]
	v_mfma_f32_16x16x32_bf16 v[74:77], v[164:167], v[212:215], v[74:77]
	v_mfma_f32_16x16x32_bf16 v[126:129], v[160:163], v[192:195], v[126:129]
	v_mfma_f32_16x16x32_bf16 v[122:125], v[168:171], v[192:195], v[122:125]
	v_mfma_f32_16x16x32_bf16 v[110:113], v[160:163], v[200:203], v[110:113]
	v_mfma_f32_16x16x32_bf16 v[106:109], v[168:171], v[200:203], v[106:109]
	v_mfma_f32_16x16x32_bf16 v[94:97], v[160:163], v[208:211], v[94:97]
	v_mfma_f32_16x16x32_bf16 v[90:93], v[168:171], v[208:211], v[90:93]
	v_mfma_f32_16x16x32_bf16 v[78:81], v[160:163], v[216:219], v[78:81]
	v_mfma_f32_16x16x32_bf16 v[74:77], v[168:171], v[216:219], v[74:77]
	v_mfma_f32_16x16x32_bf16 v[118:121], v[172:175], v[188:191], v[118:121]
	v_mfma_f32_16x16x32_bf16 v[114:117], v[180:183], v[188:191], v[114:117]
	v_mfma_f32_16x16x32_bf16 v[102:105], v[172:175], v[196:199], v[102:105]
	v_mfma_f32_16x16x32_bf16 v[98:101], v[180:183], v[196:199], v[98:101]
	v_mfma_f32_16x16x32_bf16 v[86:89], v[172:175], v[204:207], v[86:89]
	v_mfma_f32_16x16x32_bf16 v[82:85], v[180:183], v[204:207], v[82:85]
	v_mfma_f32_16x16x32_bf16 v[70:73], v[172:175], v[212:215], v[70:73]
	v_mfma_f32_16x16x32_bf16 v[66:69], v[180:183], v[212:215], v[66:69]
	v_mfma_f32_16x16x32_bf16 v[118:121], v[176:179], v[192:195], v[118:121]
	v_mfma_f32_16x16x32_bf16 v[114:117], v[184:187], v[192:195], v[114:117]
	v_mfma_f32_16x16x32_bf16 v[102:105], v[176:179], v[200:203], v[102:105]
	v_mfma_f32_16x16x32_bf16 v[98:101], v[184:187], v[200:203], v[98:101]
	v_mfma_f32_16x16x32_bf16 v[86:89], v[176:179], v[208:211], v[86:89]
	v_mfma_f32_16x16x32_bf16 v[82:85], v[184:187], v[208:211], v[82:85]
	v_mfma_f32_16x16x32_bf16 v[70:73], v[176:179], v[216:219], v[70:73]
	v_mfma_f32_16x16x32_bf16 v[66:69], v[184:187], v[216:219], v[66:69]
	s_setprio 0
	s_barrier
	ds_read_b128 v[188:191], v155 offset:16384
	ds_read_b128 v[192:195], v155 offset:17408
	ds_read_b128 v[196:199], v155 offset:18432
	ds_read_b128 v[200:203], v155 offset:19456
	ds_read_b128 v[204:207], v155 offset:20480
	ds_read_b128 v[208:211], v155 offset:21504
	ds_read_b128 v[212:215], v155 offset:22528
	ds_read_b128 v[216:219], v155 offset:23552
	s_mov_b32 m0, s15
	s_nop 0
	global_load_lds_dwordx4 v150, s[30:31]
	s_nop 0
	s_mov_b32 m0, s25
	s_nop 0
	global_load_lds_dwordx4 v152, s[30:31]
	s_add_u32 s26, s30, 0x80000
	s_addc_u32 s27, s31, 0
	s_mov_b32 m0, s48
	s_nop 0
	global_load_lds_dwordx4 v150, s[26:27]
	s_nop 0
	s_mov_b32 m0, s49
	s_nop 0
	global_load_lds_dwordx4 v152, s[26:27]
	s_mov_b32 m0, s10
	s_nop 0
	global_load_lds_dwordx4 v149, s[42:43]
	s_nop 0
	s_mov_b32 m0, s50
	s_nop 0
	global_load_lds_dwordx4 v151, s[42:43]
	s_waitcnt vmcnt(8)
	s_waitcnt lgkmcnt(0)
	s_barrier
	s_setprio 1
	v_mfma_f32_16x16x32_bf16 v[62:65], v[156:159], v[188:191], v[62:65]
	v_mfma_f32_16x16x32_bf16 v[58:61], v[164:167], v[188:191], v[58:61]
	v_mfma_f32_16x16x32_bf16 v[46:49], v[156:159], v[196:199], v[46:49]
	v_mfma_f32_16x16x32_bf16 v[42:45], v[164:167], v[196:199], v[42:45]
	v_mfma_f32_16x16x32_bf16 v[30:33], v[156:159], v[204:207], v[30:33]
	v_mfma_f32_16x16x32_bf16 v[26:29], v[164:167], v[204:207], v[26:29]
	v_mfma_f32_16x16x32_bf16 v[14:17], v[156:159], v[212:215], v[14:17]
	v_mfma_f32_16x16x32_bf16 v[10:13], v[164:167], v[212:215], v[10:13]
	v_mfma_f32_16x16x32_bf16 v[62:65], v[160:163], v[192:195], v[62:65]
	v_mfma_f32_16x16x32_bf16 v[58:61], v[168:171], v[192:195], v[58:61]
	v_mfma_f32_16x16x32_bf16 v[46:49], v[160:163], v[200:203], v[46:49]
	v_mfma_f32_16x16x32_bf16 v[42:45], v[168:171], v[200:203], v[42:45]
	v_mfma_f32_16x16x32_bf16 v[30:33], v[160:163], v[208:211], v[30:33]
	v_mfma_f32_16x16x32_bf16 v[26:29], v[168:171], v[208:211], v[26:29]
	v_mfma_f32_16x16x32_bf16 v[14:17], v[160:163], v[216:219], v[14:17]
	v_mfma_f32_16x16x32_bf16 v[10:13], v[168:171], v[216:219], v[10:13]
	v_mfma_f32_16x16x32_bf16 v[54:57], v[172:175], v[188:191], v[54:57]
	v_mfma_f32_16x16x32_bf16 v[50:53], v[180:183], v[188:191], v[50:53]
	v_mfma_f32_16x16x32_bf16 v[38:41], v[172:175], v[196:199], v[38:41]
	v_mfma_f32_16x16x32_bf16 v[34:37], v[180:183], v[196:199], v[34:37]
	v_mfma_f32_16x16x32_bf16 v[22:25], v[172:175], v[204:207], v[22:25]
	v_mfma_f32_16x16x32_bf16 v[18:21], v[180:183], v[204:207], v[18:21]
	v_mfma_f32_16x16x32_bf16 v[6:9], v[172:175], v[212:215], v[6:9]
	v_mfma_f32_16x16x32_bf16 v[2:5], v[180:183], v[212:215], v[2:5]
	v_mfma_f32_16x16x32_bf16 v[54:57], v[176:179], v[192:195], v[54:57]
	v_mfma_f32_16x16x32_bf16 v[50:53], v[184:187], v[192:195], v[50:53]
	v_mfma_f32_16x16x32_bf16 v[38:41], v[176:179], v[200:203], v[38:41]
	v_mfma_f32_16x16x32_bf16 v[34:37], v[184:187], v[200:203], v[34:37]
	v_mfma_f32_16x16x32_bf16 v[22:25], v[176:179], v[208:211], v[22:25]
	v_mfma_f32_16x16x32_bf16 v[18:21], v[184:187], v[208:211], v[18:21]
	v_mfma_f32_16x16x32_bf16 v[6:9], v[176:179], v[216:219], v[6:9]
	v_mfma_f32_16x16x32_bf16 v[2:5], v[184:187], v[216:219], v[2:5]
	s_setprio 0
	s_barrier
; #define PG8_LDA(dst, b, h) do { _Pragma("unroll") for (int m = 0; m < 4; ++m) _Pragma("unroll") for (int k = 0; k < 2; ++k) dst[m][k] = *(const PG8_LAS bf16x8*)(lds + PG8_SA(b, h) + aoff + m * 2048 + k * 1024); } while (0)
; #define PG8_LDB(dst, b, h) do { _Pragma("unroll") for (int n = 0; n < 2; ++n) _Pragma("unroll") for (int k = 0; k < 2; ++k) dst[n][k] = *(const PG8_LAS bf16x8*)(lds + PG8_SB(b, h) + boff + n * 2048 + k * 1024); } while (0)
; #define PG8_MMA(ai, bj, At, Bt) do { __builtin_amdgcn_s_setprio(1); _Pragma("unroll") for (int m = 0; m < 4; ++m) _Pragma("unroll") for (int n = 0; n < 2; ++n) _Pragma("unroll") for (int k = 0; k < 2; ++k) \
;         acc[ai][bj][m][n] = __builtin_amdgcn_mfma_f32_16x16x32_bf16(Bt[n][k], At[m][k], acc[ai][bj][m][n], 0, 0, 0); __builtin_amdgcn_s_setprio(0); } while (0)
; #define PG8_WAIT_V(n) asm volatile("s_waitcnt vmcnt(" #n ")" ::: "memory")
; #define PG8_WAIT_L(n) asm volatile("s_waitcnt lgkmcnt(" #n ")" ::: "memory")
; #define PG8_BAR __builtin_amdgcn_s_barrier()
; #define PG8_SCHED __builtin_amdgcn_sched_barrier(0)
; template <class Epi, class Sched, bool ALIGN_EPI = false, bool SP2 = false>
; __device__ __forceinline__ void gemm_phase(PG8_LAS unsigned char* lds, const Gemm g, const Sched& S, const Epi& E, const int tid) {
;     ...
;             PG8_LDB(B0, 1, 0); PG8_LDB(B1, 1, 1); PG8_SCHED; PG8_LDA(At, 1, 0); PG8_STAGE(PG8_SA(0, 1), a2 + hstepA, voffA);
;             PG8_WAIT_V(8); PG8_WAIT_L(0); PG8_BAR; PG8_MMA(0, 0, At, B0); PG8_MMA(0, 1, At, B1); PG8_BAR; PG8_SCHED;
;             PG8_LDA(At, 1, 1); PG8_STAGE(PG8_SB(1, 0), b3, voffB); PG8_STAGE(PG8_SB(1, 1), b3 + hstepB, voffB); PG8_STAGE(PG8_SA(1, 0), a3, voffA);
;             PG8_WAIT_V(8); PG8_WAIT_L(0); PG8_BAR; PG8_MMA(1, 0, At, B0); PG8_MMA(1, 1, At, B1); PG8_BAR; PG8_SCHED;
	v_add_u32_e32 v145, 0x18000, v154
	ds_read_b128 v[156:159], v145
	ds_read_b128 v[160:163], v145 offset:1024
	ds_read_b128 v[164:167], v145 offset:2048
	ds_read_b128 v[168:171], v145 offset:3072
	v_add_u32_e32 v145, 0x1c000, v154
	ds_read_b128 v[172:175], v145
	ds_read_b128 v[176:179], v145 offset:1024
	ds_read_b128 v[180:183], v145 offset:2048
	ds_read_b128 v[184:187], v145 offset:3072
	ds_read_b128 v[188:191], v155 offset:32768
	ds_read_b128 v[192:195], v155 offset:33792
	ds_read_b128 v[196:199], v155 offset:34816
	ds_read_b128 v[200:203], v155 offset:35840
	ds_read_b128 v[204:207], v155 offset:36864
	ds_read_b128 v[208:211], v155 offset:37888
	ds_read_b128 v[212:215], v155 offset:38912
	ds_read_b128 v[216:219], v155 offset:39936
	s_add_u32 s26, s42, 0x80000
	s_addc_u32 s27, s43, 0
	s_mov_b32 m0, s51
	s_nop 0
	global_load_lds_dwordx4 v149, s[26:27]
	s_nop 0
	s_mov_b32 m0, s54
	s_nop 0
	global_load_lds_dwordx4 v151, s[26:27]
	s_waitcnt vmcnt(8)
	s_waitcnt lgkmcnt(0)
	s_barrier
	s_setprio 1
	v_mfma_f32_16x16x32_bf16 v[126:129], v[156:159], v[188:191], v[126:129]
	v_mfma_f32_16x16x32_bf16 v[122:125], v[164:167], v[188:191], v[122:125]
	v_mfma_f32_16x16x32_bf16 v[110:113], v[156:159], v[196:199], v[110:113]
	v_mfma_f32_16x16x32_bf16 v[106:109], v[164:167], v[196:199], v[106:109]
	v_mfma_f32_16x16x32_bf16 v[94:97], v[156:159], v[204:207], v[94:97]
	v_mfma_f32_16x16x32_bf16 v[90:93], v[164:167], v[204:207], v[90:93]
	v_mfma_f32_16x16x32_bf16 v[78:81], v[156:159], v[212:215], v[78:81]
	v_mfma_f32_16x16x32_bf16 v[74:77], v[164:167], v[212:215], v[74:77]
	v_mfma_f32_16x16x32_bf16 v[126:129], v[160:163], v[192:195], v[126:129]
	v_mfma_f32_16x16x32_bf16 v[122:125], v[168:171], v[192:195], v[122:125]
	v_mfma_f32_16x16x32_bf16 v[110:113], v[160:163], v[200:203], v[110:113]
	v_mfma_f32_16x16x32_bf16 v[106:109], v[168:171], v[200:203], v[106:109]
	v_mfma_f32_16x16x32_bf16 v[94:97], v[160:163], v[208:211], v[94:97]
	v_mfma_f32_16x16x32_bf16 v[90:93], v[168:171], v[208:211], v[90:93]
	v_mfma_f32_16x16x32_bf16 v[78:81], v[160:163], v[216:219], v[78:81]
	v_mfma_f32_16x16x32_bf16 v[74:77], v[168:171], v[216:219], v[74:77]
	v_mfma_f32_16x16x32_bf16 v[118:121], v[172:175], v[188:191], v[118:121]
	v_mfma_f32_16x16x32_bf16 v[114:117], v[180:183], v[188:191], v[114:117]
	v_mfma_f32_16x16x32_bf16 v[102:105], v[172:175], v[196:199], v[102:105]
	v_mfma_f32_16x16x32_bf16 v[98:101], v[180:183], v[196:199], v[98:101]
	v_mfma_f32_16x16x32_bf16 v[86:89], v[172:175], v[204:207], v[86:89]
	v_mfma_f32_16x16x32_bf16 v[82:85], v[180:183], v[204:207], v[82:85]
	v_mfma_f32_16x16x32_bf16 v[70:73], v[172:175], v[212:215], v[70:73]
	v_mfma_f32_16x16x32_bf16 v[66:69], v[180:183], v[212:215], v[66:69]
	v_mfma_f32_16x16x32_bf16 v[118:121], v[176:179], v[192:195], v[118:121]
	v_mfma_f32_16x16x32_bf16 v[114:117], v[184:187], v[192:195], v[114:117]
	v_mfma_f32_16x16x32_bf16 v[102:105], v[176:179], v[200:203], v[102:105]
	v_mfma_f32_16x16x32_bf16 v[98:101], v[184:187], v[200:203], v[98:101]
	v_mfma_f32_16x16x32_bf16 v[86:89], v[176:179], v[208:211], v[86:89]
	v_mfma_f32_16x16x32_bf16 v[82:85], v[184:187], v[208:211], v[82:85]
	v_mfma_f32_16x16x32_bf16 v[70:73], v[176:179], v[216:219], v[70:73]
	v_mfma_f32_16x16x32_bf16 v[66:69], v[184:187], v[216:219], v[66:69]
	s_setprio 0
	s_barrier
	ds_read_b128 v[188:191], v155 offset:49152
	ds_read_b128 v[192:195], v155 offset:50176
	ds_read_b128 v[196:199], v155 offset:51200
	ds_read_b128 v[200:203], v155 offset:52224
	ds_read_b128 v[204:207], v155 offset:53248
	ds_read_b128 v[208:211], v155 offset:54272
	ds_read_b128 v[212:215], v155 offset:55296
	ds_read_b128 v[216:219], v155 offset:56320
	s_mov_b32 m0, s55
	s_nop 0
	global_load_lds_dwordx4 v150, s[40:41]
	s_nop 0
	s_mov_b32 m0, s56
	s_nop 0
	global_load_lds_dwordx4 v152, s[40:41]
	s_add_u32 s26, s30, 0x80080
	s_addc_u32 s27, s31, 0
	s_mov_b32 m0, s64
	s_nop 0
	global_load_lds_dwordx4 v150, s[26:27]
	s_nop 0
	s_mov_b32 m0, s65
	s_nop 0
	global_load_lds_dwordx4 v152, s[26:27]
	s_mov_b32 m0, s57
	s_nop 0
	global_load_lds_dwordx4 v149, s[38:39]
	s_nop 0
	s_mov_b32 m0, s61
	s_nop 0
	global_load_lds_dwordx4 v151, s[38:39]
	s_waitcnt vmcnt(8)
	s_waitcnt lgkmcnt(0)
	s_barrier
	s_setprio 1
	v_mfma_f32_16x16x32_bf16 v[62:65], v[156:159], v[188:191], v[62:65]
	v_mfma_f32_16x16x32_bf16 v[58:61], v[164:167], v[188:191], v[58:61]
	v_mfma_f32_16x16x32_bf16 v[46:49], v[156:159], v[196:199], v[46:49]
	v_mfma_f32_16x16x32_bf16 v[42:45], v[164:167], v[196:199], v[42:45]
	v_mfma_f32_16x16x32_bf16 v[30:33], v[156:159], v[204:207], v[30:33]
	v_mfma_f32_16x16x32_bf16 v[26:29], v[164:167], v[204:207], v[26:29]
	v_mfma_f32_16x16x32_bf16 v[14:17], v[156:159], v[212:215], v[14:17]
	v_mfma_f32_16x16x32_bf16 v[10:13], v[164:167], v[212:215], v[10:13]
	v_mfma_f32_16x16x32_bf16 v[62:65], v[160:163], v[192:195], v[62:65]
	v_mfma_f32_16x16x32_bf16 v[58:61], v[168:171], v[192:195], v[58:61]
	v_mfma_f32_16x16x32_bf16 v[46:49], v[160:163], v[200:203], v[46:49]
	v_mfma_f32_16x16x32_bf16 v[42:45], v[168:171], v[200:203], v[42:45]
	v_mfma_f32_16x16x32_bf16 v[30:33], v[160:163], v[208:211], v[30:33]
	v_mfma_f32_16x16x32_bf16 v[26:29], v[168:171], v[208:211], v[26:29]
	v_mfma_f32_16x16x32_bf16 v[14:17], v[160:163], v[216:219], v[14:17]
	v_mfma_f32_16x16x32_bf16 v[10:13], v[168:171], v[216:219], v[10:13]
	v_mfma_f32_16x16x32_bf16 v[54:57], v[172:175], v[188:191], v[54:57]
	v_mfma_f32_16x16x32_bf16 v[50:53], v[180:183], v[188:191], v[50:53]
	v_mfma_f32_16x16x32_bf16 v[38:41], v[172:175], v[196:199], v[38:41]
	v_mfma_f32_16x16x32_bf16 v[34:37], v[180:183], v[196:199], v[34:37]
	v_mfma_f32_16x16x32_bf16 v[22:25], v[172:175], v[204:207], v[22:25]
	v_mfma_f32_16x16x32_bf16 v[18:21], v[180:183], v[204:207], v[18:21]
	v_mfma_f32_16x16x32_bf16 v[6:9], v[172:175], v[212:215], v[6:9]
	v_mfma_f32_16x16x32_bf16 v[2:5], v[180:183], v[212:215], v[2:5]
	v_mfma_f32_16x16x32_bf16 v[54:57], v[176:179], v[192:195], v[54:57]
	v_mfma_f32_16x16x32_bf16 v[50:53], v[184:187], v[192:195], v[50:53]
	v_mfma_f32_16x16x32_bf16 v[38:41], v[176:179], v[200:203], v[38:41]
	v_mfma_f32_16x16x32_bf16 v[34:37], v[184:187], v[200:203], v[34:37]
	v_mfma_f32_16x16x32_bf16 v[22:25], v[176:179], v[208:211], v[22:25]
	v_mfma_f32_16x16x32_bf16 v[18:21], v[184:187], v[208:211], v[18:21]
	v_mfma_f32_16x16x32_bf16 v[6:9], v[176:179], v[216:219], v[6:9]
	v_mfma_f32_16x16x32_bf16 v[2:5], v[184:187], v[216:219], v[2:5]
	s_setprio 0
	s_barrier
	s_add_i32 s11, s11, 2
	s_add_u32 s59, s59, 0x100
	s_addc_u32 s67, s67, 0
	s_cmp_gt_u32 s11, 29
	s_mov_b64 s[26:27], s[34:35]
	s_cbranch_scc1 .LBB0_1073

; #define PG8_LDA(dst, b, h) do { _Pragma("unroll") for (int m = 0; m < 4; ++m) _Pragma("unroll") for (int k = 0; k < 2; ++k) dst[m][k] = *(const PG8_LAS bf16x8*)(lds + PG8_SA(b, h) + aoff + m * 2048 + k * 1024); } while (0)
; #define PG8_LDB(dst, b, h) do { _Pragma("unroll") for (int n = 0; n < 2; ++n) _Pragma("unroll") for (int k = 0; k < 2; ++k) dst[n][k] = *(const PG8_LAS bf16x8*)(lds + PG8_SB(b, h) + boff + n * 2048 + k * 1024); } while (0)
; #define PG8_MMA(ai, bj, At, Bt) do { __builtin_amdgcn_s_setprio(1); _Pragma("unroll") for (int m = 0; m < 4; ++m) _Pragma("unroll") for (int n = 0; n < 2; ++n) _Pragma("unroll") for (int k = 0; k < 2; ++k) \
;         acc[ai][bj][m][n] = __builtin_amdgcn_mfma_f32_16x16x32_bf16(Bt[n][k], At[m][k], acc[ai][bj][m][n], 0, 0, 0); __builtin_amdgcn_s_setprio(0); } while (0)
; #define PG8_WAIT_V(n) asm volatile("s_waitcnt vmcnt(" #n ")" ::: "memory")
; #define PG8_WAIT_L(n) asm volatile("s_waitcnt lgkmcnt(" #n ")" ::: "memory")
; #define PG8_BAR __builtin_amdgcn_s_barrier()
; #define PG8_SCHED __builtin_amdgcn_sched_barrier(0)
; template <class Epi, class Sched, bool ALIGN_EPI = false, bool SP2 = false>
; __device__ __forceinline__ void gemm_phase(PG8_LAS unsigned char* lds, const Gemm g, const Sched& S, const Epi& E, const int tid) {
;     ...
;             const char* a1 = cA + (size_t)(t + 1) * kstepA;
;             const char* a2 = last ? nA : cA + (size_t)(t + 2) * kstepA; const char* b2 = last ? nB : cB + (size_t)(t + 2) * kstepB;
;             const char* a3 = a2 + kstepA; const char* b3 = b2 + kstepB;
;             if (last && has_next) S.a_ready(nxt);
;             if constexpr (SP2) {
;             PG8_LDB(B0, 0, 0); PG8_LDB(B1, 0, 1); PG8_SCHED; PG8_LDA(At, 0, 0); PG8_STAGE(PG8_SA(1, 1), a1 + hstepA, voffA);
;             PG8_WAIT_V(8); PG8_WAIT_L(0); PG8_BAR; PG8_MMA(0, 0, At, B0); PG8_MMA(0, 1, At, B1); PG8_BAR; PG8_SCHED;
;             PG8_LDA(At, 0, 1); PG8_STAGE(PG8_SB(0, 0), b2, voffB); PG8_STAGE(PG8_SB(0, 1), b2 + hstepB, voffB); PG8_STAGE(PG8_SA(0, 0), a2, voffA);
;             PG8_WAIT_V(8); PG8_WAIT_L(0); PG8_BAR; PG8_MMA(1, 0, At, B0); PG8_MMA(1, 1, At, B1); PG8_BAR; PG8_SCHED;
.LBB0_1151:
	v_add_u32_e32 v142, 0x10000, v185
	v_add_u32_e32 v158, 0x14000, v185
	ds_read_b128 v[122:125], v142
	ds_read_b128 v[130:133], v142 offset:1024
	ds_read_b128 v[138:141], v142 offset:2048
	ds_read_b128 v[142:145], v142 offset:3072
	ds_read_b128 v[146:149], v158
	ds_read_b128 v[150:153], v158 offset:1024
	ds_read_b128 v[154:157], v158 offset:2048
	ds_read_b128 v[158:161], v158 offset:3072
	s_cmpk_eq_i32 s89, 0x54
	s_cselect_b32 s34, s26, s83
	s_cselect_b32 s35, s27, s87
	s_cselect_b32 s30, s28, s59
	s_cselect_b32 s31, s29, s67
	s_add_u32 s8, s34, 0x8000
	s_addc_u32 s9, s35, 0
	ds_read_b128 v[162:165], v186
	ds_read_b128 v[166:169], v186 offset:1024
	ds_read_b128 v[170:173], v186 offset:2048
	ds_read_b128 v[174:177], v186 offset:3072
	ds_read_b128 v[188:191], v186 offset:4096
	ds_read_b128 v[192:195], v186 offset:5120
	ds_read_b128 v[196:199], v186 offset:6144
	ds_read_b128 v[200:203], v186 offset:7168
	s_mov_b32 m0, s61
	s_nop 0
	global_load_lds_dwordx4 v0, s[6:7]
	s_nop 0
	s_mov_b32 m0, s64
	s_nop 0
	global_load_lds_dwordx4 v181, s[6:7]
	s_waitcnt vmcnt(8)
	s_waitcnt lgkmcnt(0)
	s_barrier
	s_setprio 1
	v_mfma_f32_16x16x32_bf16 v[134:137], v[122:125], v[162:165], v[134:137]
	v_mfma_f32_16x16x32_bf16 v[126:129], v[138:141], v[162:165], v[126:129]
	v_mfma_f32_16x16x32_bf16 v[110:113], v[122:125], v[170:173], v[110:113]
	v_mfma_f32_16x16x32_bf16 v[106:109], v[138:141], v[170:173], v[106:109]
	v_mfma_f32_16x16x32_bf16 v[94:97], v[122:125], v[188:191], v[94:97]
	v_mfma_f32_16x16x32_bf16 v[90:93], v[138:141], v[188:191], v[90:93]
	v_mfma_f32_16x16x32_bf16 v[78:81], v[122:125], v[196:199], v[78:81]
	v_mfma_f32_16x16x32_bf16 v[74:77], v[138:141], v[196:199], v[74:77]
	v_mfma_f32_16x16x32_bf16 v[134:137], v[130:133], v[166:169], v[134:137]
	v_mfma_f32_16x16x32_bf16 v[126:129], v[142:145], v[166:169], v[126:129]
	v_mfma_f32_16x16x32_bf16 v[110:113], v[130:133], v[174:177], v[110:113]
	v_mfma_f32_16x16x32_bf16 v[106:109], v[142:145], v[174:177], v[106:109]
	v_mfma_f32_16x16x32_bf16 v[94:97], v[130:133], v[192:195], v[94:97]
	v_mfma_f32_16x16x32_bf16 v[90:93], v[142:145], v[192:195], v[90:93]
	v_mfma_f32_16x16x32_bf16 v[78:81], v[130:133], v[200:203], v[78:81]
	v_mfma_f32_16x16x32_bf16 v[74:77], v[142:145], v[200:203], v[74:77]
	v_mfma_f32_16x16x32_bf16 v[118:121], v[146:149], v[162:165], v[118:121]
	v_mfma_f32_16x16x32_bf16 v[114:117], v[154:157], v[162:165], v[114:117]
	v_mfma_f32_16x16x32_bf16 v[102:105], v[146:149], v[170:173], v[102:105]
	v_mfma_f32_16x16x32_bf16 v[98:101], v[154:157], v[170:173], v[98:101]
	v_mfma_f32_16x16x32_bf16 v[86:89], v[146:149], v[188:191], v[86:89]
	v_mfma_f32_16x16x32_bf16 v[82:85], v[154:157], v[188:191], v[82:85]
	v_mfma_f32_16x16x32_bf16 v[70:73], v[146:149], v[196:199], v[70:73]
	v_mfma_f32_16x16x32_bf16 v[66:69], v[154:157], v[196:199], v[66:69]
	v_mfma_f32_16x16x32_bf16 v[118:121], v[150:153], v[166:169], v[118:121]
	v_mfma_f32_16x16x32_bf16 v[114:117], v[158:161], v[166:169], v[114:117]
	v_mfma_f32_16x16x32_bf16 v[102:105], v[150:153], v[174:177], v[102:105]
	v_mfma_f32_16x16x32_bf16 v[98:101], v[158:161], v[174:177], v[98:101]
	v_mfma_f32_16x16x32_bf16 v[86:89], v[150:153], v[192:195], v[86:89]
	v_mfma_f32_16x16x32_bf16 v[82:85], v[158:161], v[192:195], v[82:85]
	v_mfma_f32_16x16x32_bf16 v[70:73], v[150:153], v[200:203], v[70:73]
	v_mfma_f32_16x16x32_bf16 v[66:69], v[158:161], v[200:203], v[66:69]
	s_setprio 0
	s_barrier
	ds_read_b128 v[162:165], v186 offset:16384
	ds_read_b128 v[166:169], v186 offset:17408
	ds_read_b128 v[170:173], v186 offset:18432
	ds_read_b128 v[174:177], v186 offset:19456
	ds_read_b128 v[188:191], v186 offset:20480
	ds_read_b128 v[192:195], v186 offset:21504
	ds_read_b128 v[196:199], v186 offset:22528
	ds_read_b128 v[200:203], v186 offset:23552
	s_mov_b32 m0, s41
	s_nop 0
	global_load_lds_dwordx4 v180, s[30:31]
	s_add_u32 s90, s30, 0x4000
	s_mov_b32 m0, s42
	s_nop 0
	global_load_lds_dwordx4 v182, s[30:31]
	s_addc_u32 s91, s31, 0
	s_mov_b32 m0, s43
	s_nop 0
	global_load_lds_dwordx4 v180, s[90:91]
	s_nop 0
	s_mov_b32 m0, s44
	s_nop 0
	global_load_lds_dwordx4 v182, s[90:91]
	s_nop 0
	s_mov_b32 m0, s10
	s_nop 0
	global_load_lds_dwordx4 v0, s[34:35]
	s_nop 0
	s_mov_b32 m0, s45
	s_nop 0
	global_load_lds_dwordx4 v181, s[34:35]
	s_waitcnt vmcnt(8)
	s_waitcnt lgkmcnt(0)
	s_barrier
	s_setprio 1
	v_mfma_f32_16x16x32_bf16 v[62:65], v[122:125], v[162:165], v[62:65]
	v_mfma_f32_16x16x32_bf16 v[58:61], v[138:141], v[162:165], v[58:61]
	v_mfma_f32_16x16x32_bf16 v[46:49], v[122:125], v[170:173], v[46:49]
	v_mfma_f32_16x16x32_bf16 v[42:45], v[138:141], v[170:173], v[42:45]
	v_mfma_f32_16x16x32_bf16 v[30:33], v[122:125], v[188:191], v[30:33]
	v_mfma_f32_16x16x32_bf16 v[26:29], v[138:141], v[188:191], v[26:29]
	v_mfma_f32_16x16x32_bf16 v[14:17], v[122:125], v[196:199], v[14:17]
	v_mfma_f32_16x16x32_bf16 v[10:13], v[138:141], v[196:199], v[10:13]
	v_mfma_f32_16x16x32_bf16 v[62:65], v[130:133], v[166:169], v[62:65]
	v_mfma_f32_16x16x32_bf16 v[58:61], v[142:145], v[166:169], v[58:61]
	v_mfma_f32_16x16x32_bf16 v[46:49], v[130:133], v[174:177], v[46:49]
	v_mfma_f32_16x16x32_bf16 v[42:45], v[142:145], v[174:177], v[42:45]
	v_mfma_f32_16x16x32_bf16 v[30:33], v[130:133], v[192:195], v[30:33]
	v_mfma_f32_16x16x32_bf16 v[26:29], v[142:145], v[192:195], v[26:29]
	v_mfma_f32_16x16x32_bf16 v[14:17], v[130:133], v[200:203], v[14:17]
	v_mfma_f32_16x16x32_bf16 v[10:13], v[142:145], v[200:203], v[10:13]
	v_mfma_f32_16x16x32_bf16 v[54:57], v[146:149], v[162:165], v[54:57]
	v_mfma_f32_16x16x32_bf16 v[50:53], v[154:157], v[162:165], v[50:53]
	v_mfma_f32_16x16x32_bf16 v[38:41], v[146:149], v[170:173], v[38:41]
	v_mfma_f32_16x16x32_bf16 v[34:37], v[154:157], v[170:173], v[34:37]
	v_mfma_f32_16x16x32_bf16 v[22:25], v[146:149], v[188:191], v[22:25]
	v_mfma_f32_16x16x32_bf16 v[18:21], v[154:157], v[188:191], v[18:21]
	v_mfma_f32_16x16x32_bf16 v[6:9], v[146:149], v[196:199], v[6:9]
	v_mfma_f32_16x16x32_bf16 v[2:5], v[154:157], v[196:199], v[2:5]
	v_mfma_f32_16x16x32_bf16 v[54:57], v[150:153], v[166:169], v[54:57]
	v_mfma_f32_16x16x32_bf16 v[50:53], v[158:161], v[166:169], v[50:53]
	v_mfma_f32_16x16x32_bf16 v[38:41], v[150:153], v[174:177], v[38:41]
	v_mfma_f32_16x16x32_bf16 v[34:37], v[158:161], v[174:177], v[34:37]
	v_mfma_f32_16x16x32_bf16 v[22:25], v[150:153], v[192:195], v[22:25]
	v_mfma_f32_16x16x32_bf16 v[18:21], v[158:161], v[192:195], v[18:21]
	v_mfma_f32_16x16x32_bf16 v[6:9], v[150:153], v[200:203], v[6:9]
	v_mfma_f32_16x16x32_bf16 v[2:5], v[158:161], v[200:203], v[2:5]
	s_setprio 0
	s_barrier
; #define PG8_LDA(dst, b, h) do { _Pragma("unroll") for (int m = 0; m < 4; ++m) _Pragma("unroll") for (int k = 0; k < 2; ++k) dst[m][k] = *(const PG8_LAS bf16x8*)(lds + PG8_SA(b, h) + aoff + m * 2048 + k * 1024); } while (0)
; #define PG8_LDB(dst, b, h) do { _Pragma("unroll") for (int n = 0; n < 2; ++n) _Pragma("unroll") for (int k = 0; k < 2; ++k) dst[n][k] = *(const PG8_LAS bf16x8*)(lds + PG8_SB(b, h) + boff + n * 2048 + k * 1024); } while (0)
; #define PG8_MMA(ai, bj, At, Bt) do { __builtin_amdgcn_s_setprio(1); _Pragma("unroll") for (int m = 0; m < 4; ++m) _Pragma("unroll") for (int n = 0; n < 2; ++n) _Pragma("unroll") for (int k = 0; k < 2; ++k) \
;         acc[ai][bj][m][n] = __builtin_amdgcn_mfma_f32_16x16x32_bf16(Bt[n][k], At[m][k], acc[ai][bj][m][n], 0, 0, 0); __builtin_amdgcn_s_setprio(0); } while (0)
; #define PG8_WAIT_V(n) asm volatile("s_waitcnt vmcnt(" #n ")" ::: "memory")
; #define PG8_WAIT_L(n) asm volatile("s_waitcnt lgkmcnt(" #n ")" ::: "memory")
; #define PG8_BAR __builtin_amdgcn_s_barrier()
; #define PG8_SCHED __builtin_amdgcn_sched_barrier(0)
; template <class Epi, class Sched, bool ALIGN_EPI = false, bool SP2 = false>
; __device__ __forceinline__ void gemm_phase(PG8_LAS unsigned char* lds, const Gemm g, const Sched& S, const Epi& E, const int tid) {
;     ...
;             PG8_LDB(B0, 1, 0); PG8_LDB(B1, 1, 1); PG8_SCHED; PG8_LDA(At, 1, 0); PG8_STAGE(PG8_SA(0, 1), a2 + hstepA, voffA);
;             PG8_WAIT_V(8); PG8_WAIT_L(0); PG8_BAR; PG8_MMA(0, 0, At, B0); PG8_MMA(0, 1, At, B1); PG8_BAR; PG8_SCHED;
;             PG8_LDA(At, 1, 1); PG8_STAGE(PG8_SB(1, 0), b3, voffB); PG8_STAGE(PG8_SB(1, 1), b3 + hstepB, voffB); PG8_STAGE(PG8_SA(1, 0), a3, voffA);
;             PG8_WAIT_V(8); PG8_WAIT_L(0); PG8_BAR; PG8_MMA(1, 0, At, B0); PG8_MMA(1, 1, At, B1); PG8_BAR; PG8_SCHED;
	v_add_u32_e32 v142, 0x18000, v185
	v_add_u32_e32 v158, 0x1c000, v185
	ds_read_b128 v[122:125], v142
	ds_read_b128 v[130:133], v142 offset:1024
	ds_read_b128 v[138:141], v142 offset:2048
	ds_read_b128 v[142:145], v142 offset:3072
	ds_read_b128 v[146:149], v158
	ds_read_b128 v[150:153], v158 offset:1024
	ds_read_b128 v[154:157], v158 offset:2048
	ds_read_b128 v[158:161], v158 offset:3072
	ds_read_b128 v[162:165], v186 offset:32768
	ds_read_b128 v[166:169], v186 offset:33792
	ds_read_b128 v[170:173], v186 offset:34816
	ds_read_b128 v[174:177], v186 offset:35840
	ds_read_b128 v[188:191], v186 offset:36864
	ds_read_b128 v[192:195], v186 offset:37888
	ds_read_b128 v[196:199], v186 offset:38912
	ds_read_b128 v[200:203], v186 offset:39936
	s_add_u32 s34, s34, 0x4000
	s_addc_u32 s35, s35, 0
	s_mov_b32 m0, s46
	s_nop 0
	global_load_lds_dwordx4 v0, s[34:35]
	s_nop 0
	s_mov_b32 m0, s47
	s_nop 0
	global_load_lds_dwordx4 v181, s[34:35]
	s_waitcnt vmcnt(8)
	s_waitcnt lgkmcnt(0)
	s_barrier
	s_setprio 1
	v_mfma_f32_16x16x32_bf16 v[134:137], v[122:125], v[162:165], v[134:137]
	v_mfma_f32_16x16x32_bf16 v[126:129], v[138:141], v[162:165], v[126:129]
	v_mfma_f32_16x16x32_bf16 v[110:113], v[122:125], v[170:173], v[110:113]
	v_mfma_f32_16x16x32_bf16 v[106:109], v[138:141], v[170:173], v[106:109]
	v_mfma_f32_16x16x32_bf16 v[94:97], v[122:125], v[188:191], v[94:97]
	v_mfma_f32_16x16x32_bf16 v[90:93], v[138:141], v[188:191], v[90:93]
	v_mfma_f32_16x16x32_bf16 v[78:81], v[122:125], v[196:199], v[78:81]
	v_mfma_f32_16x16x32_bf16 v[74:77], v[138:141], v[196:199], v[74:77]
	v_mfma_f32_16x16x32_bf16 v[134:137], v[130:133], v[166:169], v[134:137]
	v_mfma_f32_16x16x32_bf16 v[126:129], v[142:145], v[166:169], v[126:129]
	v_mfma_f32_16x16x32_bf16 v[110:113], v[130:133], v[174:177], v[110:113]
	v_mfma_f32_16x16x32_bf16 v[106:109], v[142:145], v[174:177], v[106:109]
	v_mfma_f32_16x16x32_bf16 v[94:97], v[130:133], v[192:195], v[94:97]
	v_mfma_f32_16x16x32_bf16 v[90:93], v[142:145], v[192:195], v[90:93]
	v_mfma_f32_16x16x32_bf16 v[78:81], v[130:133], v[200:203], v[78:81]
	v_mfma_f32_16x16x32_bf16 v[74:77], v[142:145], v[200:203], v[74:77]
	v_mfma_f32_16x16x32_bf16 v[118:121], v[146:149], v[162:165], v[118:121]
	v_mfma_f32_16x16x32_bf16 v[114:117], v[154:157], v[162:165], v[114:117]
	v_mfma_f32_16x16x32_bf16 v[102:105], v[146:149], v[170:173], v[102:105]
	v_mfma_f32_16x16x32_bf16 v[98:101], v[154:157], v[170:173], v[98:101]
	v_mfma_f32_16x16x32_bf16 v[86:89], v[146:149], v[188:191], v[86:89]
	v_mfma_f32_16x16x32_bf16 v[82:85], v[154:157], v[188:191], v[82:85]
	v_mfma_f32_16x16x32_bf16 v[70:73], v[146:149], v[196:199], v[70:73]
	v_mfma_f32_16x16x32_bf16 v[66:69], v[154:157], v[196:199], v[66:69]
	v_mfma_f32_16x16x32_bf16 v[118:121], v[150:153], v[166:169], v[118:121]
	v_mfma_f32_16x16x32_bf16 v[114:117], v[158:161], v[166:169], v[114:117]
	v_mfma_f32_16x16x32_bf16 v[102:105], v[150:153], v[174:177], v[102:105]
	v_mfma_f32_16x16x32_bf16 v[98:101], v[158:161], v[174:177], v[98:101]
	v_mfma_f32_16x16x32_bf16 v[86:89], v[150:153], v[192:195], v[86:89]
	v_mfma_f32_16x16x32_bf16 v[82:85], v[158:161], v[192:195], v[82:85]
	v_mfma_f32_16x16x32_bf16 v[70:73], v[150:153], v[200:203], v[70:73]
	v_mfma_f32_16x16x32_bf16 v[66:69], v[158:161], v[200:203], v[66:69]
	s_setprio 0
	s_barrier
	ds_read_b128 v[162:165], v186 offset:49152
	ds_read_b128 v[166:169], v186 offset:50176
	ds_read_b128 v[170:173], v186 offset:51200
	ds_read_b128 v[174:177], v186 offset:52224
	ds_read_b128 v[188:191], v186 offset:53248
	ds_read_b128 v[192:195], v186 offset:54272
	ds_read_b128 v[196:199], v186 offset:55296
	ds_read_b128 v[200:203], v186 offset:56320
	s_add_u32 s34, s30, 0x8000
	s_addc_u32 s35, s31, 0
	s_mov_b32 m0, s50
	s_nop 0
	global_load_lds_dwordx4 v180, s[34:35]
	s_add_u32 s30, s30, 0xc000
	s_mov_b32 m0, s51
	s_nop 0
	global_load_lds_dwordx4 v182, s[34:35]
	s_addc_u32 s31, s31, 0
	s_mov_b32 m0, s56
	s_nop 0
	global_load_lds_dwordx4 v180, s[30:31]
	s_nop 0
	s_mov_b32 m0, s57
	s_nop 0
	global_load_lds_dwordx4 v182, s[30:31]
	s_mov_b32 m0, s54
	s_nop 0
	global_load_lds_dwordx4 v0, s[8:9]
	s_nop 0
	s_mov_b32 m0, s55
	s_nop 0
	global_load_lds_dwordx4 v181, s[8:9]
	s_waitcnt vmcnt(8)
	s_waitcnt lgkmcnt(0)
	s_barrier
	s_setprio 1
	v_mfma_f32_16x16x32_bf16 v[62:65], v[122:125], v[162:165], v[62:65]
	v_mfma_f32_16x16x32_bf16 v[58:61], v[138:141], v[162:165], v[58:61]
	v_mfma_f32_16x16x32_bf16 v[46:49], v[122:125], v[170:173], v[46:49]
	v_mfma_f32_16x16x32_bf16 v[42:45], v[138:141], v[170:173], v[42:45]
	v_mfma_f32_16x16x32_bf16 v[30:33], v[122:125], v[188:191], v[30:33]
	v_mfma_f32_16x16x32_bf16 v[26:29], v[138:141], v[188:191], v[26:29]
	v_mfma_f32_16x16x32_bf16 v[14:17], v[122:125], v[196:199], v[14:17]
	v_mfma_f32_16x16x32_bf16 v[10:13], v[138:141], v[196:199], v[10:13]
	v_mfma_f32_16x16x32_bf16 v[62:65], v[130:133], v[166:169], v[62:65]
	v_mfma_f32_16x16x32_bf16 v[58:61], v[142:145], v[166:169], v[58:61]
	v_mfma_f32_16x16x32_bf16 v[46:49], v[130:133], v[174:177], v[46:49]
	v_mfma_f32_16x16x32_bf16 v[42:45], v[142:145], v[174:177], v[42:45]
	v_mfma_f32_16x16x32_bf16 v[30:33], v[130:133], v[192:195], v[30:33]
	v_mfma_f32_16x16x32_bf16 v[26:29], v[142:145], v[192:195], v[26:29]
	v_mfma_f32_16x16x32_bf16 v[14:17], v[130:133], v[200:203], v[14:17]
	v_mfma_f32_16x16x32_bf16 v[10:13], v[142:145], v[200:203], v[10:13]
	v_mfma_f32_16x16x32_bf16 v[54:57], v[146:149], v[162:165], v[54:57]
	v_mfma_f32_16x16x32_bf16 v[50:53], v[154:157], v[162:165], v[50:53]
	v_mfma_f32_16x16x32_bf16 v[38:41], v[146:149], v[170:173], v[38:41]
	v_mfma_f32_16x16x32_bf16 v[34:37], v[154:157], v[170:173], v[34:37]
	v_mfma_f32_16x16x32_bf16 v[22:25], v[146:149], v[188:191], v[22:25]
	v_mfma_f32_16x16x32_bf16 v[18:21], v[154:157], v[188:191], v[18:21]
	v_mfma_f32_16x16x32_bf16 v[6:9], v[146:149], v[196:199], v[6:9]
	v_mfma_f32_16x16x32_bf16 v[2:5], v[154:157], v[196:199], v[2:5]
	v_mfma_f32_16x16x32_bf16 v[54:57], v[150:153], v[166:169], v[54:57]
	v_mfma_f32_16x16x32_bf16 v[50:53], v[158:161], v[166:169], v[50:53]
	v_mfma_f32_16x16x32_bf16 v[38:41], v[150:153], v[174:177], v[38:41]
	v_mfma_f32_16x16x32_bf16 v[34:37], v[158:161], v[174:177], v[34:37]
	v_mfma_f32_16x16x32_bf16 v[22:25], v[150:153], v[192:195], v[22:25]
	v_mfma_f32_16x16x32_bf16 v[18:21], v[158:161], v[192:195], v[18:21]
	v_mfma_f32_16x16x32_bf16 v[6:9], v[150:153], v[200:203], v[6:9]
	v_mfma_f32_16x16x32_bf16 v[2:5], v[158:161], v[200:203], v[2:5]
	s_setprio 0
	s_barrier
	s_add_i32 s89, s89, 2
	s_add_u32 s59, s59, 0x10000
	s_addc_u32 s67, s67, 0
	s_add_u32 s83, s83, 0x10000
	s_addc_u32 s87, s87, 0
	s_add_u32 s6, s6, 0x10000
	s_addc_u32 s7, s7, 0
	s_cmpk_gt_u32 s89, 0x55
	s_cbranch_scc0 .LBB0_1151
	s_and_b64 vcc, exec, s[20:21]
	s_cbranch_vccz .LBB0_1154
	s_barrier
